# dense attention loop on v_mfma_f32_16x16x32_bf16 (same bf16 operands, f32 accumulate) with static priority for waves 4-7, plus banded counted waits and v_rsq rstd
# speedup vs baseline: 1.0006x; 1.0006x over previous
; #define SBAR() __builtin_amdgcn_sched_barrier(0)
; __device__ __forceinline__ int v_st(int k, int c) { const int kk = (k & ~0xC) | ((k & 4) << 1) | ((k & 8) >> 1); return ((kk >> 3) * 4 + (c >> 5)) * 512 + ((kk & 7) * 32 + (c & 31)) * 2; }
; __device__ __forceinline__ int v_rd_base(int lane) { return ((lane & 3) << 3) | (((lane >> 2) & 3) << 6) | (((lane >> 4) & 1) << 5) | (((lane >> 5) & 1) << 8); }
;     ...
;   const int sr = tid >> 4, sc = (tid & 15) * 8, vst0 = v_st(sr, sc), vst1 = vst0 + 8192;
;   const int vb0 = (int)(uintptr_t)V_lds + v_rd_base(lane);
;   const int qrel = wid * QBLK + r32;
;   constexpr int SD = (MODE == 0) ? ATT_SD0 : 2;
;   struct { bf16x8 vs0, vs1, ks0, ks1; } sr_[SD];
;   const unsigned soff0 = (unsigned)(sr * (int)ldk + sc) * 2u, soff1 = soff0 + (unsigned)(32 * (int)ldk) * 2u;
;     ...
;   if constexpr (MODE == 1) {
;     f32x16 pA0, pA1; float mnA, alA; bf16x8 pa0, pa1, pa2, pa3;
;     const int jlo = wid >> 1;
;     SLOAD(0, 0); SLOAD(1, 1);
;     for (int j = 0; j < NT; j += 2) {
;       SWRITE(0, 0); __syncthreads();
;       if (j + 2 < NT) SLOAD(0, j + 2);
;       if (j >= jlo && j <= jlo + 2) {
;         qkt(pA0, pA1, K_lds, qr, r32, hi); BIASM(pA0, pA1, j); partialSM(pA0, pA1, m_reg, mnA, alA);
;         RESC(alA);
;         finishSM(pA0, pA1, alA, l_reg, pa0, pa1, pa2, pa3); SBAR();
;         pv_d0(o, vb0, pa0, pa1, pa2, pa3);
;       }
;       SWRITE(1, 1); __syncthreads();
;       if (j + 3 < NT) SLOAD(1, j + 3);
;       if (j + 1 >= jlo && j + 1 <= jlo + 2) {
;         qkt(pA0, pA1, (bf16*)((char*)K_lds + SHM_K), qr, r32, hi); BIASM(pA0, pA1, j + 1); partialSM(pA0, pA1, m_reg, mnA, alA);
;         RESC(alA);
;         finishSM(pA0, pA1, alA, l_reg, pa0, pa1, pa2, pa3); SBAR();
;         pv_d0(o, vb0 + (int)SHM_V, pa0, pa1, pa2, pa3);
;       }
;     }
;   } else {
;   f32x16 pA0, pA1, pB0, pB1; float mnA, mnB, alA, alB; bf16x8 pa0, pa1, pa2, pa3;
;   bf16x8 pv0_, pv1_, pv2_, pv3_, pk0_, pk1_, pk2_, pk3_;
;   const int NP = NT >> 1;
;   const unsigned rstep = (unsigned)(32 * (int)ldk) * 2u;
;     ...
;   PLOAD(0); asm volatile("s_waitcnt vmcnt(0)" ::: "memory"); PWRITE(0); __syncthreads();
;   qkt(pA0, pA1, KSUB(0, 0), qr, r32, hi); partialSM(pA0, pA1, m_reg, mnA, alA);
.LBB0_486:
	v_and_b32_e32 v64, 63, v218
	v_and_b32_e32 v65, 15, v64
	v_lshrrev_b32_e32 v66, 4, v64
	v_add_u32_e32 v67, 0, v66
	v_xor_b32_e32 v67, v67, v65
	v_lshlrev_b32_e32 v67, 4, v67
	v_lshl_or_b32 v172, v65, 8, v67
	v_add_u32_e32 v67, 4, v66
	v_xor_b32_e32 v67, v67, v65
	v_lshlrev_b32_e32 v67, 4, v67
	v_lshl_or_b32 v173, v65, 8, v67
	v_add_u32_e32 v67, 8, v66
	v_xor_b32_e32 v67, v67, v65
	v_lshlrev_b32_e32 v67, 4, v67
	v_lshl_or_b32 v174, v65, 8, v67
	v_add_u32_e32 v67, 12, v66
	v_xor_b32_e32 v67, v67, v65
	v_lshlrev_b32_e32 v67, 4, v67
	v_lshl_or_b32 v175, v65, 8, v67
	v_bfe_u32 v68, v64, 2, 2
	v_and_b32_e32 v69, 3, v64
	v_lshl_add_u32 v70, v66, 2, v68
	v_and_b32_e32 v71, 7, v70
	v_lshlrev_b32_e32 v70, 8, v70
	v_lshl_add_u32 v70, v69, 3, v70
	v_add_u32_e32 v70, 0x10000, v70
	v_xor_b32_e32 v72, 0, v71
	v_lshl_add_u32 v176, v72, 5, v70
	v_xor_b32_e32 v72, 1, v71
	v_lshl_add_u32 v177, v72, 5, v70
	v_xor_b32_e32 v72, 2, v71
	v_lshl_add_u32 v178, v72, 5, v70
	v_xor_b32_e32 v72, 3, v71
	v_lshl_add_u32 v179, v72, 5, v70
	v_xor_b32_e32 v72, 4, v71
	v_lshl_add_u32 v180, v72, 5, v70
	v_xor_b32_e32 v72, 5, v71
	v_lshl_add_u32 v182, v72, 5, v70
	v_xor_b32_e32 v72, 6, v71
	v_lshl_add_u32 v216, v72, 5, v70
	v_xor_b32_e32 v72, 7, v71
	v_lshl_add_u32 v217, v72, 5, v70
	v_lshrrev_b32_e32 v72, 4, v218
	v_and_b32_e32 v73, 7, v72
	v_lshlrev_b32_e32 v73, 1, v73
	v_and_b32_e32 v74, 15, v218
	v_xor_b32_e32 v73, v73, v74
	v_lshlrev_b32_e32 v73, 4, v73
	v_lshl_or_b32 v219, v72, 8, v73
	v_add_u32_e32 v219, 0x10000, v219
	s_add_u32 s100, s98, 0xa8000
	s_addc_u32 s101, s99, 0
	s_sub_u32 s0, s98, 0x2a0000
	s_subb_u32 s1, s99, 0
	s_add_u32 s4, s0, 0xa8000
	s_addc_u32 s5, s1, 0
	global_load_dwordx4 v[164:167], v183, s[0:1] offset:512
	global_load_dwordx4 v[160:163], v183, s[4:5] offset:512
	s_add_u32 s0, s0, 0x150000
	s_addc_u32 s1, s1, 0
	s_add_u32 s4, s4, 0x150000
	s_addc_u32 s5, s5, 0
	global_load_dwordx4 v[184:187], v183, s[0:1] offset:512
	global_load_dwordx4 v[188:191], v183, s[4:5] offset:512
	s_add_u32 s0, s0, 0x150000
	s_addc_u32 s1, s1, 0
	s_add_u32 s4, s4, 0x150000
	s_addc_u32 s5, s5, 0
	global_load_dwordx4 v[246:249], v183, s[98:99]
	global_load_dwordx4 v[250:253], v183, s[100:101]
	s_add_u32 s98, s98, 0x150000
	s_addc_u32 s99, s99, 0
	s_add_u32 s100, s100, 0x150000
	s_addc_u32 s101, s101, 0
	v_and_b32_e32 v67, 1, v66
	v_lshl_add_u32 v67, v67, 5, v65
	v_lshlrev_b32_e32 v68, 2, v67
	v_add_u32_e32 v69, 64, v68
	s_mov_b32 vcc_lo, 0
	s_mov_b32 vcc_hi, -1
	ds_bpermute_b32 v200, v68, v124
	ds_bpermute_b32 v201, v68, v120
	ds_bpermute_b32 v202, v68, v125
	ds_bpermute_b32 v203, v68, v121
	ds_bpermute_b32 v204, v68, v126
	ds_bpermute_b32 v205, v68, v122
	ds_bpermute_b32 v206, v68, v127
	ds_bpermute_b32 v207, v68, v123
	ds_bpermute_b32 v208, v68, v116
	ds_bpermute_b32 v209, v68, v112
	ds_bpermute_b32 v210, v68, v117
	ds_bpermute_b32 v211, v68, v113
	ds_bpermute_b32 v212, v68, v118
	ds_bpermute_b32 v213, v68, v114
	s_waitcnt lgkmcnt(0)
	v_cndmask_b32_e64 v128, v200, v201, vcc
	v_cndmask_b32_e64 v129, v202, v203, vcc
	v_cndmask_b32_e64 v130, v204, v205, vcc
	v_cndmask_b32_e64 v131, v206, v207, vcc
	v_cndmask_b32_e64 v132, v208, v209, vcc
	v_cndmask_b32_e64 v133, v210, v211, vcc
	v_cndmask_b32_e64 v134, v212, v213, vcc
	ds_bpermute_b32 v200, v68, v119
	ds_bpermute_b32 v201, v68, v115
	ds_bpermute_b32 v202, v68, v108
	ds_bpermute_b32 v203, v68, v104
	ds_bpermute_b32 v204, v68, v109
	ds_bpermute_b32 v205, v68, v105
	ds_bpermute_b32 v206, v68, v110
	ds_bpermute_b32 v207, v68, v106
	ds_bpermute_b32 v208, v68, v111
	ds_bpermute_b32 v209, v68, v107
	ds_bpermute_b32 v210, v68, v100
	ds_bpermute_b32 v211, v68, v96
	ds_bpermute_b32 v212, v68, v101
	ds_bpermute_b32 v213, v68, v97
	s_waitcnt lgkmcnt(0)
	v_cndmask_b32_e64 v135, v200, v201, vcc
	v_cndmask_b32_e64 v136, v202, v203, vcc
	v_cndmask_b32_e64 v137, v204, v205, vcc
	v_cndmask_b32_e64 v138, v206, v207, vcc
	v_cndmask_b32_e64 v139, v208, v209, vcc
	v_cndmask_b32_e64 v140, v210, v211, vcc
	v_cndmask_b32_e64 v141, v212, v213, vcc
	ds_bpermute_b32 v200, v68, v102
	ds_bpermute_b32 v201, v68, v98
	ds_bpermute_b32 v202, v68, v103
	ds_bpermute_b32 v203, v68, v99
	ds_bpermute_b32 v204, v69, v124
	ds_bpermute_b32 v205, v69, v120
	ds_bpermute_b32 v206, v69, v125
	ds_bpermute_b32 v207, v69, v121
	ds_bpermute_b32 v208, v69, v126
	ds_bpermute_b32 v209, v69, v122
	ds_bpermute_b32 v210, v69, v127
	ds_bpermute_b32 v211, v69, v123
	ds_bpermute_b32 v212, v69, v116
	ds_bpermute_b32 v213, v69, v112
	s_waitcnt lgkmcnt(0)
	v_cndmask_b32_e64 v142, v200, v201, vcc
	v_cndmask_b32_e64 v143, v202, v203, vcc
	v_cndmask_b32_e64 v144, v204, v205, vcc
	v_cndmask_b32_e64 v145, v206, v207, vcc
	v_cndmask_b32_e64 v146, v208, v209, vcc
	v_cndmask_b32_e64 v147, v210, v211, vcc
	v_cndmask_b32_e64 v148, v212, v213, vcc
	ds_bpermute_b32 v200, v69, v117
	ds_bpermute_b32 v201, v69, v113
	ds_bpermute_b32 v202, v69, v118
	ds_bpermute_b32 v203, v69, v114
	ds_bpermute_b32 v204, v69, v119
	ds_bpermute_b32 v205, v69, v115
	ds_bpermute_b32 v206, v69, v108
	ds_bpermute_b32 v207, v69, v104
	ds_bpermute_b32 v208, v69, v109
	ds_bpermute_b32 v209, v69, v105
	ds_bpermute_b32 v210, v69, v110
	ds_bpermute_b32 v211, v69, v106
	ds_bpermute_b32 v212, v69, v111
	ds_bpermute_b32 v213, v69, v107
	s_waitcnt lgkmcnt(0)
	v_cndmask_b32_e64 v149, v200, v201, vcc
	v_cndmask_b32_e64 v150, v202, v203, vcc
	v_cndmask_b32_e64 v151, v204, v205, vcc
	v_cndmask_b32_e64 v152, v206, v207, vcc
	v_cndmask_b32_e64 v153, v208, v209, vcc
	v_cndmask_b32_e64 v154, v210, v211, vcc
	v_cndmask_b32_e64 v155, v212, v213, vcc
	ds_bpermute_b32 v200, v69, v100
	ds_bpermute_b32 v201, v69, v96
	ds_bpermute_b32 v202, v69, v101
	ds_bpermute_b32 v203, v69, v97
	ds_bpermute_b32 v204, v69, v102
	ds_bpermute_b32 v205, v69, v98
	ds_bpermute_b32 v206, v69, v103
	ds_bpermute_b32 v207, v69, v99
	s_waitcnt lgkmcnt(0)
; __device__ __forceinline__ void qkt(f32x16& p0, f32x16& p1, const bf16* Ks, const bf16x8* qr, int r32, int hi) {
;   p0 = f32x16{}; p1 = f32x16{};
; #pragma unroll
;   for (int d0 = 0; d0 < 8; ++d0) { int cb = (d0 * 16 + hi * 8) * 2;
;     bf16x8 b0 = *reinterpret_cast<const bf16x8*>((const char*)Ks + KSWZ(r32, cb));
;     bf16x8 b1 = *reinterpret_cast<const bf16x8*>((const char*)Ks + KSWZ(32 + r32, cb));
;     p0 = __builtin_amdgcn_mfma_f32_32x32x16_bf16(b0, qr[d0], p0, 0, 0, 0);
;     p1 = __builtin_amdgcn_mfma_f32_32x32x16_bf16(b1, qr[d0], p1, 0, 0, 0); }
; }
;     ...
;   PLOAD(0); asm volatile("s_waitcnt vmcnt(0)" ::: "memory"); PWRITE(0); __syncthreads();
;   qkt(pA0, pA1, KSUB(0, 0), qr, r32, hi); partialSM(pA0, pA1, m_reg, mnA, alA);
	v_cndmask_b32_e64 v156, v200, v201, vcc
	v_cndmask_b32_e64 v157, v202, v203, vcc
	v_cndmask_b32_e64 v158, v204, v205, vcc
	v_cndmask_b32_e64 v159, v206, v207, vcc
	v_mov_b32_e32 v96, v128
	v_mov_b32_e32 v97, v129
	v_mov_b32_e32 v98, v130
	v_mov_b32_e32 v99, v131
	v_mov_b32_e32 v100, v132
	v_mov_b32_e32 v101, v133
	v_mov_b32_e32 v102, v134
	v_mov_b32_e32 v103, v135
	v_mov_b32_e32 v104, v136
	v_mov_b32_e32 v105, v137
	v_mov_b32_e32 v106, v138
	v_mov_b32_e32 v107, v139
	v_mov_b32_e32 v108, v140
	v_mov_b32_e32 v109, v141
	v_mov_b32_e32 v110, v142
	v_mov_b32_e32 v111, v143
	v_mov_b32_e32 v112, v144
	v_mov_b32_e32 v113, v145
	v_mov_b32_e32 v114, v146
	v_mov_b32_e32 v115, v147
	v_mov_b32_e32 v116, v148
	v_mov_b32_e32 v117, v149
	v_mov_b32_e32 v118, v150
	v_mov_b32_e32 v119, v151
	v_mov_b32_e32 v120, v152
	v_mov_b32_e32 v121, v153
	v_mov_b32_e32 v122, v154
	v_mov_b32_e32 v123, v155
	v_mov_b32_e32 v124, v156
	v_mov_b32_e32 v125, v157
	v_mov_b32_e32 v126, v158
	v_mov_b32_e32 v127, v159
	v_mov_b32_e32 v169, 0
	v_mov_b32_e32 v222, 0
	s_mov_b32 s44, 0
	ds_read_b128 v[200:203], v172 offset:0
	ds_read_b128 v[204:207], v172 offset:4096
	ds_read_b128 v[208:211], v172 offset:8192
	ds_read_b128 v[212:215], v172 offset:12288
	ds_read_b128 v[230:233], v173 offset:0
	ds_read_b128 v[234:237], v173 offset:4096
	ds_read_b128 v[238:241], v173 offset:8192
	ds_read_b128 v[242:245], v173 offset:12288
	s_waitcnt lgkmcnt(7)
	v_mfma_f32_16x16x32_bf16 v[64:67], v[200:203], v[96:99], 0
	v_mfma_f32_16x16x32_bf16 v[68:71], v[200:203], v[112:115], 0
	ds_read_b128 v[200:203], v174 offset:0
	s_waitcnt lgkmcnt(7)
	v_mfma_f32_16x16x32_bf16 v[72:75], v[204:207], v[96:99], 0
	v_mfma_f32_16x16x32_bf16 v[76:79], v[204:207], v[112:115], 0
	ds_read_b128 v[204:207], v174 offset:4096
	s_waitcnt lgkmcnt(7)
	v_mfma_f32_16x16x32_bf16 v[80:83], v[208:211], v[96:99], 0
	v_mfma_f32_16x16x32_bf16 v[84:87], v[208:211], v[112:115], 0
	ds_read_b128 v[208:211], v174 offset:8192
	s_waitcnt lgkmcnt(7)
	v_mfma_f32_16x16x32_bf16 v[88:91], v[212:215], v[96:99], 0
	v_mfma_f32_16x16x32_bf16 v[92:95], v[212:215], v[112:115], 0
	ds_read_b128 v[212:215], v174 offset:12288
	s_waitcnt lgkmcnt(7)
	v_mfma_f32_16x16x32_bf16 v[64:67], v[230:233], v[100:103], v[64:67]
	v_mfma_f32_16x16x32_bf16 v[68:71], v[230:233], v[116:119], v[68:71]
	ds_read_b128 v[230:233], v175 offset:0
	s_waitcnt lgkmcnt(7)
	v_mfma_f32_16x16x32_bf16 v[72:75], v[234:237], v[100:103], v[72:75]
	v_mfma_f32_16x16x32_bf16 v[76:79], v[234:237], v[116:119], v[76:79]
	ds_read_b128 v[234:237], v175 offset:4096
	s_waitcnt lgkmcnt(7)
	v_mfma_f32_16x16x32_bf16 v[80:83], v[238:241], v[100:103], v[80:83]
	v_mfma_f32_16x16x32_bf16 v[84:87], v[238:241], v[116:119], v[84:87]
	ds_read_b128 v[238:241], v175 offset:8192
	s_waitcnt lgkmcnt(7)
	v_mfma_f32_16x16x32_bf16 v[88:91], v[242:245], v[100:103], v[88:91]
	v_mfma_f32_16x16x32_bf16 v[92:95], v[242:245], v[116:119], v[92:95]
	ds_read_b128 v[242:245], v175 offset:12288
	s_waitcnt lgkmcnt(7)
	v_mfma_f32_16x16x32_bf16 v[64:67], v[200:203], v[104:107], v[64:67]
	v_mfma_f32_16x16x32_bf16 v[68:71], v[200:203], v[120:123], v[68:71]
	s_waitcnt lgkmcnt(6)
	v_mfma_f32_16x16x32_bf16 v[72:75], v[204:207], v[104:107], v[72:75]
	v_mfma_f32_16x16x32_bf16 v[76:79], v[204:207], v[120:123], v[76:79]
	s_waitcnt lgkmcnt(5)
	v_mfma_f32_16x16x32_bf16 v[80:83], v[208:211], v[104:107], v[80:83]
	v_mfma_f32_16x16x32_bf16 v[84:87], v[208:211], v[120:123], v[84:87]
	s_waitcnt lgkmcnt(4)
	v_mfma_f32_16x16x32_bf16 v[88:91], v[212:215], v[104:107], v[88:91]
	v_mfma_f32_16x16x32_bf16 v[92:95], v[212:215], v[120:123], v[92:95]
	s_waitcnt lgkmcnt(3)
	v_mfma_f32_16x16x32_bf16 v[64:67], v[230:233], v[108:111], v[64:67]
	v_mfma_f32_16x16x32_bf16 v[68:71], v[230:233], v[124:127], v[68:71]
	s_waitcnt lgkmcnt(2)
	v_mfma_f32_16x16x32_bf16 v[72:75], v[234:237], v[108:111], v[72:75]
	v_mfma_f32_16x16x32_bf16 v[76:79], v[234:237], v[124:127], v[76:79]
	s_waitcnt lgkmcnt(1)
	v_mfma_f32_16x16x32_bf16 v[80:83], v[238:241], v[108:111], v[80:83]
	v_mfma_f32_16x16x32_bf16 v[84:87], v[238:241], v[124:127], v[84:87]
	s_waitcnt lgkmcnt(0)
	v_mfma_f32_16x16x32_bf16 v[88:91], v[242:245], v[108:111], v[88:91]
	v_mfma_f32_16x16x32_bf16 v[92:95], v[242:245], v[124:127], v[92:95]
	v_exp_f32_e32 v64, v64
	v_exp_f32_e32 v65, v65
	v_exp_f32_e32 v66, v66
	v_exp_f32_e32 v67, v67
	v_exp_f32_e32 v68, v68
	v_exp_f32_e32 v69, v69
	v_exp_f32_e32 v70, v70
	v_exp_f32_e32 v71, v71
	v_exp_f32_e32 v72, v72
	v_exp_f32_e32 v73, v73
	v_exp_f32_e32 v74, v74
	v_exp_f32_e32 v75, v75
	v_exp_f32_e32 v76, v76
	v_exp_f32_e32 v77, v77
	v_exp_f32_e32 v78, v78
	v_exp_f32_e32 v79, v79
	v_exp_f32_e32 v80, v80
	v_exp_f32_e32 v81, v81
	v_exp_f32_e32 v82, v82
	v_exp_f32_e32 v83, v83
	v_exp_f32_e32 v84, v84
	v_exp_f32_e32 v85, v85
	v_exp_f32_e32 v86, v86
	v_exp_f32_e32 v87, v87
	v_exp_f32_e32 v88, v88
	v_exp_f32_e32 v89, v89
	v_exp_f32_e32 v90, v90
	v_exp_f32_e32 v91, v91
	v_exp_f32_e32 v92, v92
	v_exp_f32_e32 v93, v93
	v_exp_f32_e32 v94, v94
	v_exp_f32_e32 v95, v95
	s_waitcnt vmcnt(0)
	ds_write_b128 v219, v[164:167] offset:0
	ds_write_b128 v219, v[160:163] offset:8192
	ds_write_b128 v219, v[184:187] offset:16384
	ds_write_b128 v219, v[188:191] offset:24576
	ds_write_b128 v181, v[246:249] offset:32768
	ds_write_b128 v181, v[250:253] offset:40960
	s_waitcnt lgkmcnt(0)
	ds_read_b128 v[200:203], v172 offset:16384
	ds_read_b128 v[204:207], v172 offset:20480
	ds_read_b128 v[208:211], v172 offset:24576
	ds_read_b128 v[212:215], v172 offset:28672
	ds_read_b128 v[230:233], v173 offset:16384
	ds_read_b128 v[234:237], v173 offset:20480
	ds_read_b128 v[238:241], v173 offset:24576
	ds_read_b128 v[242:245], v173 offset:28672
	s_barrier
	v_readfirstlane_b32 s44, v218
	s_nop 3
	s_cmp_ge_u32 s44, 0x100
	s_mov_b32 s44, 0
	s_cbranch_scc0 .Lprio_done
	s_setprio 1
; __device__ __forceinline__ void qkt(f32x16& p0, f32x16& p1, const bf16* Ks, const bf16x8* qr, int r32, int hi) {
;   p0 = f32x16{}; p1 = f32x16{};
; #pragma unroll
;   for (int d0 = 0; d0 < 8; ++d0) { int cb = (d0 * 16 + hi * 8) * 2;
;     bf16x8 b0 = *reinterpret_cast<const bf16x8*>((const char*)Ks + KSWZ(r32, cb));
;     bf16x8 b1 = *reinterpret_cast<const bf16x8*>((const char*)Ks + KSWZ(32 + r32, cb));
;     p0 = __builtin_amdgcn_mfma_f32_32x32x16_bf16(b0, qr[d0], p0, 0, 0, 0);
;     p1 = __builtin_amdgcn_mfma_f32_32x32x16_bf16(b1, qr[d0], p1, 0, 0, 0); }
; }
; __device__ __forceinline__ int v_st(int k, int c) { const int kk = (k & ~0xC) | ((k & 4) << 1) | ((k & 8) >> 1); return ((kk >> 3) * 4 + (c >> 5)) * 512 + ((kk & 7) * 32 + (c & 31)) * 2; }
; __device__ __forceinline__ int v_rd_base(int lane) { return ((lane & 3) << 3) | (((lane >> 2) & 3) << 6) | (((lane >> 4) & 1) << 5) | (((lane >> 5) & 1) << 8); }
; template <int OFF> __device__ __forceinline__ s16x4 tr_read(int vb) {
;   s16x4 r; asm volatile("ds_read_b64_tr_b16 %0, %1 offset:%2" : "=&v"(r) : "v"(vb), "i"(OFF) : "memory"); return r;
; }
; template <int D0> __device__ __forceinline__ void pv_one(f32x16& od, int vb, bf16x8 pa0, bf16x8 pa1, bf16x8 pa2, bf16x8 pa3) {
;   const s16x4 l0 = tr_read<v_rd_off(D0, 0, 0)>(vb), h0 = tr_read<v_rd_off(D0, 0, 1)>(vb), l1 = tr_read<v_rd_off(D0, 1, 0)>(vb), h1 = tr_read<v_rd_off(D0, 1, 1)>(vb);
;   const s16x4 l2 = tr_read<v_rd_off(D0, 2, 0)>(vb), h2 = tr_read<v_rd_off(D0, 2, 1)>(vb), l3 = tr_read<v_rd_off(D0, 3, 0)>(vb), h3 = tr_read<v_rd_off(D0, 3, 1)>(vb);
;   asm volatile("s_waitcnt lgkmcnt(0)" ::: "memory"); SBAR();
;     ...
;   od = __builtin_amdgcn_mfma_f32_32x32x16_bf16(pa0, PK(l0, h0), od, 0, 0, 0);
;   od = __builtin_amdgcn_mfma_f32_32x32x16_bf16(pa1, PK(l1, h1), od, 0, 0, 0);
;   od = __builtin_amdgcn_mfma_f32_32x32x16_bf16(pa2, PK(l2, h2), od, 0, 0, 0);
;   od = __builtin_amdgcn_mfma_f32_32x32x16_bf16(pa3, PK(l3, h3), od, 0, 0, 0);
;     ...
; }
; __device__ __forceinline__ void pv_d0(f32x16* o, int vb, bf16x8 pa0, bf16x8 pa1, bf16x8 pa2, bf16x8 pa3) {
;   pv_one<0>(o[0], vb, pa0, pa1, pa2, pa3); pv_one<1>(o[1], vb, pa0, pa1, pa2, pa3); pv_one<2>(o[2], vb, pa0, pa1, pa2, pa3); pv_one<3>(o[3], vb, pa0, pa1, pa2, pa3);
;     ...
;   for (int p = 0; p + 2 < NP; p += 2) {
;     PAIR_FULL(0, 1, p + 1);
;     PAIR_FULL(1, 0, p + 2);
.Lprio_done:
.Ldense_loop:
	s_waitcnt lgkmcnt(7)
	v_mfma_f32_16x16x32_bf16 v[128:131], v[200:203], v[96:99], 0
	v_add_f32_e32 v169, v169, v64
	global_load_dwordx4 v[246:249], v183, s[98:99]
	v_mfma_f32_16x16x32_bf16 v[132:135], v[200:203], v[112:115], 0
	ds_read_b128 v[200:203], v174 offset:16384
	v_add_f32_e32 v169, v169, v65
	v_cvt_pk_bf16_f32 v184, v64, v65
	s_waitcnt lgkmcnt(7)
	v_mfma_f32_16x16x32_bf16 v[136:139], v[204:207], v[96:99], 0
	v_add_f32_e32 v169, v169, v66
	v_mfma_f32_16x16x32_bf16 v[140:143], v[204:207], v[112:115], 0
	ds_read_b128 v[204:207], v174 offset:20480
	v_add_f32_e32 v169, v169, v67
	v_cvt_pk_bf16_f32 v185, v66, v67
	s_waitcnt lgkmcnt(7)
	v_mfma_f32_16x16x32_bf16 v[144:147], v[208:211], v[96:99], 0
	v_add_f32_e32 v222, v222, v68
	global_load_dwordx4 v[250:253], v183, s[100:101]
	s_add_u32 s98, s98, 0x150000
	s_addc_u32 s99, s99, 0
	s_add_u32 s100, s100, 0x150000
	s_addc_u32 s101, s101, 0
	v_mfma_f32_16x16x32_bf16 v[148:151], v[208:211], v[112:115], 0
	ds_read_b128 v[208:211], v174 offset:24576
	v_add_f32_e32 v222, v222, v69
	v_cvt_pk_bf16_f32 v186, v72, v73
	s_waitcnt lgkmcnt(7)
	v_mfma_f32_16x16x32_bf16 v[152:155], v[212:215], v[96:99], 0
	v_add_f32_e32 v222, v222, v70
	v_mfma_f32_16x16x32_bf16 v[156:159], v[212:215], v[112:115], 0
	ds_read_b128 v[212:215], v174 offset:28672
	v_add_f32_e32 v222, v222, v71
	v_cvt_pk_bf16_f32 v187, v74, v75
	s_waitcnt lgkmcnt(7)
	v_mfma_f32_16x16x32_bf16 v[128:131], v[230:233], v[100:103], v[128:131]
	v_add_f32_e32 v169, v169, v72
	global_load_dwordx4 v[164:167], v183, s[0:1] offset:512
	v_mfma_f32_16x16x32_bf16 v[132:135], v[230:233], v[116:119], v[132:135]
	ds_read_b128 v[230:233], v175 offset:16384
	v_add_f32_e32 v169, v169, v73
	v_cvt_pk_bf16_f32 v188, v80, v81
	s_waitcnt lgkmcnt(7)
	v_mfma_f32_16x16x32_bf16 v[136:139], v[234:237], v[100:103], v[136:139]
	v_add_f32_e32 v169, v169, v74
	v_mfma_f32_16x16x32_bf16 v[140:143], v[234:237], v[116:119], v[140:143]
	ds_read_b128 v[234:237], v175 offset:20480
	v_add_f32_e32 v169, v169, v75
	v_cvt_pk_bf16_f32 v189, v82, v83
	s_waitcnt lgkmcnt(7)
	v_mfma_f32_16x16x32_bf16 v[144:147], v[238:241], v[100:103], v[144:147]
	v_add_f32_e32 v222, v222, v76
	global_load_dwordx4 v[160:163], v183, s[4:5] offset:512
	s_add_u32 s0, s0, 0x150000
	s_addc_u32 s1, s1, 0
	s_add_u32 s4, s4, 0x150000
	s_addc_u32 s5, s5, 0
	v_mfma_f32_16x16x32_bf16 v[148:151], v[238:241], v[116:119], v[148:151]
	ds_read_b128 v[238:241], v175 offset:24576
	v_add_f32_e32 v222, v222, v77
	v_cvt_pk_bf16_f32 v190, v88, v89
	s_waitcnt lgkmcnt(7)
	v_mfma_f32_16x16x32_bf16 v[152:155], v[242:245], v[100:103], v[152:155]
	v_add_f32_e32 v222, v222, v78
	v_mfma_f32_16x16x32_bf16 v[156:159], v[242:245], v[116:119], v[156:159]
	ds_read_b128 v[242:245], v175 offset:28672
	v_add_f32_e32 v222, v222, v79
	v_cvt_pk_bf16_f32 v191, v90, v91
	s_waitcnt lgkmcnt(7)
	v_mfma_f32_16x16x32_bf16 v[128:131], v[200:203], v[104:107], v[128:131]
	v_add_f32_e32 v169, v169, v80
	v_mfma_f32_16x16x32_bf16 v[132:135], v[200:203], v[120:123], v[132:135]
	v_add_f32_e32 v169, v169, v81
	v_cvt_pk_bf16_f32 v192, v68, v69
	s_waitcnt lgkmcnt(6)
	v_mfma_f32_16x16x32_bf16 v[136:139], v[204:207], v[104:107], v[136:139]
	v_add_f32_e32 v169, v169, v82
	v_mfma_f32_16x16x32_bf16 v[140:143], v[204:207], v[120:123], v[140:143]
	v_add_f32_e32 v169, v169, v83
	v_cvt_pk_bf16_f32 v193, v70, v71
	s_waitcnt lgkmcnt(5)
	v_mfma_f32_16x16x32_bf16 v[144:147], v[208:211], v[104:107], v[144:147]
	v_add_f32_e32 v222, v222, v84
	v_mfma_f32_16x16x32_bf16 v[148:151], v[208:211], v[120:123], v[148:151]
	v_add_f32_e32 v222, v222, v85
	v_cvt_pk_bf16_f32 v194, v76, v77
	s_waitcnt lgkmcnt(4)
	v_mfma_f32_16x16x32_bf16 v[152:155], v[212:215], v[104:107], v[152:155]
	ds_read_b64_tr_b16 v[200:201], v176 offset:0
	ds_read_b64_tr_b16 v[202:203], v176 offset:4096
	v_add_f32_e32 v222, v222, v86
	v_mfma_f32_16x16x32_bf16 v[156:159], v[212:215], v[120:123], v[156:159]
	v_add_f32_e32 v222, v222, v87
	v_cvt_pk_bf16_f32 v195, v78, v79
	s_waitcnt lgkmcnt(5)
	v_mfma_f32_16x16x32_bf16 v[128:131], v[230:233], v[108:111], v[128:131]
	ds_read_b64_tr_b16 v[204:205], v177 offset:0
	ds_read_b64_tr_b16 v[206:207], v177 offset:4096
	v_add_f32_e32 v169, v169, v88
	v_mfma_f32_16x16x32_bf16 v[132:135], v[230:233], v[124:127], v[132:135]
	v_add_f32_e32 v169, v169, v89
	v_cvt_pk_bf16_f32 v196, v84, v85
	s_waitcnt lgkmcnt(6)
	v_mfma_f32_16x16x32_bf16 v[136:139], v[234:237], v[108:111], v[136:139]
	ds_read_b64_tr_b16 v[208:209], v178 offset:0
	ds_read_b64_tr_b16 v[210:211], v178 offset:4096
	v_add_f32_e32 v169, v169, v90
	v_mfma_f32_16x16x32_bf16 v[140:143], v[234:237], v[124:127], v[140:143]
	v_add_f32_e32 v169, v169, v91
	v_cvt_pk_bf16_f32 v197, v86, v87
	s_waitcnt lgkmcnt(7)
	v_mfma_f32_16x16x32_bf16 v[144:147], v[238:241], v[108:111], v[144:147]
	ds_read_b64_tr_b16 v[212:213], v179 offset:0
	ds_read_b64_tr_b16 v[214:215], v179 offset:4096
	v_add_f32_e32 v222, v222, v92
	v_mfma_f32_16x16x32_bf16 v[148:151], v[238:241], v[124:127], v[148:151]
	v_add_f32_e32 v222, v222, v93
	v_cvt_pk_bf16_f32 v198, v92, v93
	s_waitcnt lgkmcnt(8)
	v_mfma_f32_16x16x32_bf16 v[152:155], v[242:245], v[108:111], v[152:155]
	ds_read_b64_tr_b16 v[230:231], v180 offset:0
	ds_read_b64_tr_b16 v[232:233], v180 offset:4096
	v_add_f32_e32 v222, v222, v94
	v_mfma_f32_16x16x32_bf16 v[156:159], v[242:245], v[124:127], v[156:159]
	v_add_f32_e32 v222, v222, v95
	v_cvt_pk_bf16_f32 v199, v94, v95
	s_waitcnt lgkmcnt(8)
	v_mfma_f32_16x16x32_bf16 v[0:3], v[200:203], v[184:187], v[0:3]
	v_exp_f32_e32 v128, v128
	v_mfma_f32_16x16x32_bf16 v[32:35], v[200:203], v[192:195], v[32:35]
	ds_read_b64_tr_b16 v[234:235], v182 offset:0
	ds_read_b64_tr_b16 v[236:237], v182 offset:4096
	v_exp_f32_e32 v129, v129
	s_waitcnt lgkmcnt(8)
; __device__ __forceinline__ void qkt(f32x16& p0, f32x16& p1, const bf16* Ks, const bf16x8* qr, int r32, int hi) {
;   p0 = f32x16{}; p1 = f32x16{};
; #pragma unroll
;   for (int d0 = 0; d0 < 8; ++d0) { int cb = (d0 * 16 + hi * 8) * 2;
;     bf16x8 b0 = *reinterpret_cast<const bf16x8*>((const char*)Ks + KSWZ(r32, cb));
;     bf16x8 b1 = *reinterpret_cast<const bf16x8*>((const char*)Ks + KSWZ(32 + r32, cb));
;     p0 = __builtin_amdgcn_mfma_f32_32x32x16_bf16(b0, qr[d0], p0, 0, 0, 0);
;     p1 = __builtin_amdgcn_mfma_f32_32x32x16_bf16(b1, qr[d0], p1, 0, 0, 0); }
; }
; __device__ __forceinline__ int v_st(int k, int c) { const int kk = (k & ~0xC) | ((k & 4) << 1) | ((k & 8) >> 1); return ((kk >> 3) * 4 + (c >> 5)) * 512 + ((kk & 7) * 32 + (c & 31)) * 2; }
; __device__ __forceinline__ int v_rd_base(int lane) { return ((lane & 3) << 3) | (((lane >> 2) & 3) << 6) | (((lane >> 4) & 1) << 5) | (((lane >> 5) & 1) << 8); }
; template <int OFF> __device__ __forceinline__ s16x4 tr_read(int vb) {
;   s16x4 r; asm volatile("ds_read_b64_tr_b16 %0, %1 offset:%2" : "=&v"(r) : "v"(vb), "i"(OFF) : "memory"); return r;
; }
; template <int D0> __device__ __forceinline__ void pv_one(f32x16& od, int vb, bf16x8 pa0, bf16x8 pa1, bf16x8 pa2, bf16x8 pa3) {
;   const s16x4 l0 = tr_read<v_rd_off(D0, 0, 0)>(vb), h0 = tr_read<v_rd_off(D0, 0, 1)>(vb), l1 = tr_read<v_rd_off(D0, 1, 0)>(vb), h1 = tr_read<v_rd_off(D0, 1, 1)>(vb);
;   const s16x4 l2 = tr_read<v_rd_off(D0, 2, 0)>(vb), h2 = tr_read<v_rd_off(D0, 2, 1)>(vb), l3 = tr_read<v_rd_off(D0, 3, 0)>(vb), h3 = tr_read<v_rd_off(D0, 3, 1)>(vb);
;   asm volatile("s_waitcnt lgkmcnt(0)" ::: "memory"); SBAR();
;     ...
;   od = __builtin_amdgcn_mfma_f32_32x32x16_bf16(pa0, PK(l0, h0), od, 0, 0, 0);
;   od = __builtin_amdgcn_mfma_f32_32x32x16_bf16(pa1, PK(l1, h1), od, 0, 0, 0);
;   od = __builtin_amdgcn_mfma_f32_32x32x16_bf16(pa2, PK(l2, h2), od, 0, 0, 0);
;   od = __builtin_amdgcn_mfma_f32_32x32x16_bf16(pa3, PK(l3, h3), od, 0, 0, 0);
;     ...
; }
; __device__ __forceinline__ void pv_d0(f32x16* o, int vb, bf16x8 pa0, bf16x8 pa1, bf16x8 pa2, bf16x8 pa3) {
;   pv_one<0>(o[0], vb, pa0, pa1, pa2, pa3); pv_one<1>(o[1], vb, pa0, pa1, pa2, pa3); pv_one<2>(o[2], vb, pa0, pa1, pa2, pa3); pv_one<3>(o[3], vb, pa0, pa1, pa2, pa3);
;     ...
;   for (int p = 0; p + 2 < NP; p += 2) {
;     PAIR_FULL(0, 1, p + 1);
;     PAIR_FULL(1, 0, p + 2);
	v_mfma_f32_16x16x32_bf16 v[4:7], v[204:207], v[184:187], v[4:7]
	v_exp_f32_e32 v130, v130
	s_waitcnt vmcnt(3)
	ds_write_b128 v181, v[246:249] offset:49152
	v_mfma_f32_16x16x32_bf16 v[36:39], v[204:207], v[192:195], v[36:39]
	ds_read_b64_tr_b16 v[238:239], v216 offset:0
	ds_read_b64_tr_b16 v[240:241], v216 offset:4096
	v_exp_f32_e32 v131, v131
	s_waitcnt lgkmcnt(9)
	v_mfma_f32_16x16x32_bf16 v[8:11], v[208:211], v[184:187], v[8:11]
	v_exp_f32_e32 v132, v132
	v_mfma_f32_16x16x32_bf16 v[40:43], v[208:211], v[192:195], v[40:43]
	ds_read_b64_tr_b16 v[242:243], v217 offset:0
	ds_read_b64_tr_b16 v[244:245], v217 offset:4096
	v_exp_f32_e32 v133, v133
	s_waitcnt lgkmcnt(9)
	v_mfma_f32_16x16x32_bf16 v[12:15], v[212:215], v[184:187], v[12:15]
	v_exp_f32_e32 v134, v134
	s_waitcnt vmcnt(2)
	ds_write_b128 v181, v[250:253] offset:57344
	v_mfma_f32_16x16x32_bf16 v[44:47], v[212:215], v[192:195], v[44:47]
	ds_read_b64_tr_b16 v[200:201], v176 offset:8192
	ds_read_b64_tr_b16 v[202:203], v176 offset:12288
	v_exp_f32_e32 v135, v135
	s_waitcnt lgkmcnt(10)
	v_mfma_f32_16x16x32_bf16 v[16:19], v[230:233], v[184:187], v[16:19]
	v_exp_f32_e32 v136, v136
	v_mfma_f32_16x16x32_bf16 v[48:51], v[230:233], v[192:195], v[48:51]
	ds_read_b64_tr_b16 v[204:205], v177 offset:8192
	ds_read_b64_tr_b16 v[206:207], v177 offset:12288
	v_exp_f32_e32 v137, v137
	s_waitcnt lgkmcnt(10)
	v_mfma_f32_16x16x32_bf16 v[20:23], v[234:237], v[184:187], v[20:23]
	v_exp_f32_e32 v138, v138
	s_waitcnt vmcnt(1)
	ds_write_b128 v219, v[164:167] offset:32768
	v_mfma_f32_16x16x32_bf16 v[52:55], v[234:237], v[192:195], v[52:55]
	ds_read_b64_tr_b16 v[208:209], v178 offset:8192
	ds_read_b64_tr_b16 v[210:211], v178 offset:12288
	v_exp_f32_e32 v139, v139
	s_waitcnt lgkmcnt(10)
	v_mfma_f32_16x16x32_bf16 v[24:27], v[238:241], v[184:187], v[24:27]
	v_exp_f32_e32 v140, v140
	v_mfma_f32_16x16x32_bf16 v[56:59], v[238:241], v[192:195], v[56:59]
	ds_read_b64_tr_b16 v[212:213], v179 offset:8192
	ds_read_b64_tr_b16 v[214:215], v179 offset:12288
	v_exp_f32_e32 v141, v141
	s_waitcnt lgkmcnt(10)
	v_mfma_f32_16x16x32_bf16 v[28:31], v[242:245], v[184:187], v[28:31]
	v_exp_f32_e32 v142, v142
	s_waitcnt vmcnt(0)
	ds_write_b128 v219, v[160:163] offset:40960
	v_mfma_f32_16x16x32_bf16 v[60:63], v[242:245], v[192:195], v[60:63]
	ds_read_b64_tr_b16 v[230:231], v180 offset:8192
	ds_read_b64_tr_b16 v[232:233], v180 offset:12288
	v_exp_f32_e32 v143, v143
	s_waitcnt lgkmcnt(10)
	v_mfma_f32_16x16x32_bf16 v[0:3], v[200:203], v[188:191], v[0:3]
	v_exp_f32_e32 v144, v144
	v_mfma_f32_16x16x32_bf16 v[32:35], v[200:203], v[196:199], v[32:35]
	ds_read_b64_tr_b16 v[234:235], v182 offset:8192
	ds_read_b64_tr_b16 v[236:237], v182 offset:12288
	ds_read_b128 v[200:203], v172 offset:32768
	v_exp_f32_e32 v145, v145
	s_waitcnt lgkmcnt(11)
	v_mfma_f32_16x16x32_bf16 v[4:7], v[204:207], v[188:191], v[4:7]
	v_exp_f32_e32 v146, v146
	v_mfma_f32_16x16x32_bf16 v[36:39], v[204:207], v[196:199], v[36:39]
	ds_read_b64_tr_b16 v[238:239], v216 offset:8192
	ds_read_b64_tr_b16 v[240:241], v216 offset:12288
	ds_read_b128 v[204:207], v172 offset:36864
	v_exp_f32_e32 v147, v147
	s_waitcnt lgkmcnt(11)
	v_mfma_f32_16x16x32_bf16 v[8:11], v[208:211], v[188:191], v[8:11]
	v_exp_f32_e32 v148, v148
	v_mfma_f32_16x16x32_bf16 v[40:43], v[208:211], v[196:199], v[40:43]
	ds_read_b64_tr_b16 v[242:243], v217 offset:8192
	ds_read_b64_tr_b16 v[244:245], v217 offset:12288
	ds_read_b128 v[208:211], v172 offset:40960
	v_exp_f32_e32 v149, v149
	s_waitcnt lgkmcnt(12)
	v_mfma_f32_16x16x32_bf16 v[12:15], v[212:215], v[188:191], v[12:15]
	v_exp_f32_e32 v150, v150
	v_mfma_f32_16x16x32_bf16 v[44:47], v[212:215], v[196:199], v[44:47]
	ds_read_b128 v[212:215], v172 offset:45056
	v_exp_f32_e32 v151, v151
	s_waitcnt lgkmcnt(10)
	v_mfma_f32_16x16x32_bf16 v[16:19], v[230:233], v[188:191], v[16:19]
	v_exp_f32_e32 v152, v152
	v_mfma_f32_16x16x32_bf16 v[48:51], v[230:233], v[196:199], v[48:51]
	ds_read_b128 v[230:233], v173 offset:32768
	v_exp_f32_e32 v153, v153
	s_waitcnt lgkmcnt(9)
	v_mfma_f32_16x16x32_bf16 v[20:23], v[234:237], v[188:191], v[20:23]
	v_exp_f32_e32 v154, v154
	v_mfma_f32_16x16x32_bf16 v[52:55], v[234:237], v[196:199], v[52:55]
	ds_read_b128 v[234:237], v173 offset:36864
	v_exp_f32_e32 v155, v155
	s_waitcnt lgkmcnt(7)
	v_mfma_f32_16x16x32_bf16 v[24:27], v[238:241], v[188:191], v[24:27]
	v_exp_f32_e32 v156, v156
	v_mfma_f32_16x16x32_bf16 v[56:59], v[238:241], v[196:199], v[56:59]
	ds_read_b128 v[238:241], v173 offset:40960
	v_exp_f32_e32 v157, v157
	s_waitcnt lgkmcnt(5)
	v_mfma_f32_16x16x32_bf16 v[28:31], v[242:245], v[188:191], v[28:31]
	v_exp_f32_e32 v158, v158
	v_mfma_f32_16x16x32_bf16 v[60:63], v[242:245], v[196:199], v[60:63]
	ds_read_b128 v[242:245], v173 offset:45056
	v_exp_f32_e32 v159, v159
	s_barrier
; __device__ __forceinline__ void qkt(f32x16& p0, f32x16& p1, const bf16* Ks, const bf16x8* qr, int r32, int hi) {
;   p0 = f32x16{}; p1 = f32x16{};
; #pragma unroll
;   for (int d0 = 0; d0 < 8; ++d0) { int cb = (d0 * 16 + hi * 8) * 2;
;     bf16x8 b0 = *reinterpret_cast<const bf16x8*>((const char*)Ks + KSWZ(r32, cb));
;     bf16x8 b1 = *reinterpret_cast<const bf16x8*>((const char*)Ks + KSWZ(32 + r32, cb));
;     p0 = __builtin_amdgcn_mfma_f32_32x32x16_bf16(b0, qr[d0], p0, 0, 0, 0);
;     p1 = __builtin_amdgcn_mfma_f32_32x32x16_bf16(b1, qr[d0], p1, 0, 0, 0); }
; }
; __device__ __forceinline__ int v_st(int k, int c) { const int kk = (k & ~0xC) | ((k & 4) << 1) | ((k & 8) >> 1); return ((kk >> 3) * 4 + (c >> 5)) * 512 + ((kk & 7) * 32 + (c & 31)) * 2; }
; __device__ __forceinline__ int v_rd_base(int lane) { return ((lane & 3) << 3) | (((lane >> 2) & 3) << 6) | (((lane >> 4) & 1) << 5) | (((lane >> 5) & 1) << 8); }
; template <int OFF> __device__ __forceinline__ s16x4 tr_read(int vb) {
;   s16x4 r; asm volatile("ds_read_b64_tr_b16 %0, %1 offset:%2" : "=&v"(r) : "v"(vb), "i"(OFF) : "memory"); return r;
; }
; template <int D0> __device__ __forceinline__ void pv_one(f32x16& od, int vb, bf16x8 pa0, bf16x8 pa1, bf16x8 pa2, bf16x8 pa3) {
;   const s16x4 l0 = tr_read<v_rd_off(D0, 0, 0)>(vb), h0 = tr_read<v_rd_off(D0, 0, 1)>(vb), l1 = tr_read<v_rd_off(D0, 1, 0)>(vb), h1 = tr_read<v_rd_off(D0, 1, 1)>(vb);
;   const s16x4 l2 = tr_read<v_rd_off(D0, 2, 0)>(vb), h2 = tr_read<v_rd_off(D0, 2, 1)>(vb), l3 = tr_read<v_rd_off(D0, 3, 0)>(vb), h3 = tr_read<v_rd_off(D0, 3, 1)>(vb);
;   asm volatile("s_waitcnt lgkmcnt(0)" ::: "memory"); SBAR();
;     ...
;   od = __builtin_amdgcn_mfma_f32_32x32x16_bf16(pa0, PK(l0, h0), od, 0, 0, 0);
;   od = __builtin_amdgcn_mfma_f32_32x32x16_bf16(pa1, PK(l1, h1), od, 0, 0, 0);
;   od = __builtin_amdgcn_mfma_f32_32x32x16_bf16(pa2, PK(l2, h2), od, 0, 0, 0);
;   od = __builtin_amdgcn_mfma_f32_32x32x16_bf16(pa3, PK(l3, h3), od, 0, 0, 0);
;     ...
; }
; __device__ __forceinline__ void pv_d0(f32x16* o, int vb, bf16x8 pa0, bf16x8 pa1, bf16x8 pa2, bf16x8 pa3) {
;   pv_one<0>(o[0], vb, pa0, pa1, pa2, pa3); pv_one<1>(o[1], vb, pa0, pa1, pa2, pa3); pv_one<2>(o[2], vb, pa0, pa1, pa2, pa3); pv_one<3>(o[3], vb, pa0, pa1, pa2, pa3);
;     ...
;   for (int p = 0; p + 2 < NP; p += 2) {
;     PAIR_FULL(0, 1, p + 1);
;     PAIR_FULL(1, 0, p + 2);
	v_mfma_f32_16x16x32_bf16 v[64:67], v[200:203], v[96:99], 0
	v_add_f32_e32 v169, v169, v128
	global_load_dwordx4 v[246:249], v183, s[98:99]
	v_mfma_f32_16x16x32_bf16 v[68:71], v[200:203], v[112:115], 0
	ds_read_b128 v[200:203], v174 offset:32768
	v_add_f32_e32 v169, v169, v129
	v_cvt_pk_bf16_f32 v184, v128, v129
	v_mfma_f32_16x16x32_bf16 v[72:75], v[204:207], v[96:99], 0
	v_add_f32_e32 v169, v169, v130
	v_mfma_f32_16x16x32_bf16 v[76:79], v[204:207], v[112:115], 0
	ds_read_b128 v[204:207], v174 offset:36864
	v_add_f32_e32 v169, v169, v131
	v_cvt_pk_bf16_f32 v185, v130, v131
	s_waitcnt lgkmcnt(7)
	v_mfma_f32_16x16x32_bf16 v[80:83], v[208:211], v[96:99], 0
	v_add_f32_e32 v222, v222, v132
	global_load_dwordx4 v[250:253], v183, s[100:101]
	s_add_u32 s98, s98, 0x150000
	s_addc_u32 s99, s99, 0
	s_add_u32 s100, s100, 0x150000
	s_addc_u32 s101, s101, 0
	v_mfma_f32_16x16x32_bf16 v[84:87], v[208:211], v[112:115], 0
	ds_read_b128 v[208:211], v174 offset:40960
	v_add_f32_e32 v222, v222, v133
	v_cvt_pk_bf16_f32 v186, v136, v137
	s_waitcnt lgkmcnt(7)
	v_mfma_f32_16x16x32_bf16 v[88:91], v[212:215], v[96:99], 0
	v_add_f32_e32 v222, v222, v134
	v_mfma_f32_16x16x32_bf16 v[92:95], v[212:215], v[112:115], 0
	ds_read_b128 v[212:215], v174 offset:45056
	v_add_f32_e32 v222, v222, v135
	v_cvt_pk_bf16_f32 v187, v138, v139
	s_waitcnt lgkmcnt(7)
	v_mfma_f32_16x16x32_bf16 v[64:67], v[230:233], v[100:103], v[64:67]
	v_add_f32_e32 v169, v169, v136
	global_load_dwordx4 v[164:167], v183, s[0:1] offset:512
	v_mfma_f32_16x16x32_bf16 v[68:71], v[230:233], v[116:119], v[68:71]
	ds_read_b128 v[230:233], v175 offset:32768
	v_add_f32_e32 v169, v169, v137
	v_cvt_pk_bf16_f32 v188, v144, v145
	s_waitcnt lgkmcnt(7)
	v_mfma_f32_16x16x32_bf16 v[72:75], v[234:237], v[100:103], v[72:75]
	v_add_f32_e32 v169, v169, v138
	v_mfma_f32_16x16x32_bf16 v[76:79], v[234:237], v[116:119], v[76:79]
	ds_read_b128 v[234:237], v175 offset:36864
	v_add_f32_e32 v169, v169, v139
	v_cvt_pk_bf16_f32 v189, v146, v147
	s_waitcnt lgkmcnt(7)
	v_mfma_f32_16x16x32_bf16 v[80:83], v[238:241], v[100:103], v[80:83]
	v_add_f32_e32 v222, v222, v140
	global_load_dwordx4 v[160:163], v183, s[4:5] offset:512
	s_add_u32 s0, s0, 0x150000
	s_addc_u32 s1, s1, 0
	s_add_u32 s4, s4, 0x150000
	s_addc_u32 s5, s5, 0
	v_mfma_f32_16x16x32_bf16 v[84:87], v[238:241], v[116:119], v[84:87]
	ds_read_b128 v[238:241], v175 offset:40960
	v_add_f32_e32 v222, v222, v141
	v_cvt_pk_bf16_f32 v190, v152, v153
	s_waitcnt lgkmcnt(7)
	v_mfma_f32_16x16x32_bf16 v[88:91], v[242:245], v[100:103], v[88:91]
	v_add_f32_e32 v222, v222, v142
	v_mfma_f32_16x16x32_bf16 v[92:95], v[242:245], v[116:119], v[92:95]
	ds_read_b128 v[242:245], v175 offset:45056
	v_add_f32_e32 v222, v222, v143
	v_cvt_pk_bf16_f32 v191, v154, v155
	s_waitcnt lgkmcnt(7)
	v_mfma_f32_16x16x32_bf16 v[64:67], v[200:203], v[104:107], v[64:67]
	v_add_f32_e32 v169, v169, v144
	v_mfma_f32_16x16x32_bf16 v[68:71], v[200:203], v[120:123], v[68:71]
	v_add_f32_e32 v169, v169, v145
	v_cvt_pk_bf16_f32 v192, v132, v133
	s_waitcnt lgkmcnt(6)
	v_mfma_f32_16x16x32_bf16 v[72:75], v[204:207], v[104:107], v[72:75]
	v_add_f32_e32 v169, v169, v146
	v_mfma_f32_16x16x32_bf16 v[76:79], v[204:207], v[120:123], v[76:79]
	v_add_f32_e32 v169, v169, v147
	v_cvt_pk_bf16_f32 v193, v134, v135
	s_waitcnt lgkmcnt(5)
	v_mfma_f32_16x16x32_bf16 v[80:83], v[208:211], v[104:107], v[80:83]
	v_add_f32_e32 v222, v222, v148
	v_mfma_f32_16x16x32_bf16 v[84:87], v[208:211], v[120:123], v[84:87]
	v_add_f32_e32 v222, v222, v149
	v_cvt_pk_bf16_f32 v194, v140, v141
	s_waitcnt lgkmcnt(4)
	v_mfma_f32_16x16x32_bf16 v[88:91], v[212:215], v[104:107], v[88:91]
	ds_read_b64_tr_b16 v[200:201], v176 offset:16384
	ds_read_b64_tr_b16 v[202:203], v176 offset:20480
	v_add_f32_e32 v222, v222, v150
	v_mfma_f32_16x16x32_bf16 v[92:95], v[212:215], v[120:123], v[92:95]
	v_add_f32_e32 v222, v222, v151
	v_cvt_pk_bf16_f32 v195, v142, v143
	s_waitcnt lgkmcnt(5)
	v_mfma_f32_16x16x32_bf16 v[64:67], v[230:233], v[108:111], v[64:67]
	ds_read_b64_tr_b16 v[204:205], v177 offset:16384
	ds_read_b64_tr_b16 v[206:207], v177 offset:20480
	v_add_f32_e32 v169, v169, v152
	v_mfma_f32_16x16x32_bf16 v[68:71], v[230:233], v[124:127], v[68:71]
	v_add_f32_e32 v169, v169, v153
	v_cvt_pk_bf16_f32 v196, v148, v149
	s_waitcnt lgkmcnt(6)
	v_mfma_f32_16x16x32_bf16 v[72:75], v[234:237], v[108:111], v[72:75]
	ds_read_b64_tr_b16 v[208:209], v178 offset:16384
	ds_read_b64_tr_b16 v[210:211], v178 offset:20480
	v_add_f32_e32 v169, v169, v154
	v_mfma_f32_16x16x32_bf16 v[76:79], v[234:237], v[124:127], v[76:79]
	v_add_f32_e32 v169, v169, v155
	v_cvt_pk_bf16_f32 v197, v150, v151
	s_waitcnt lgkmcnt(7)
	v_mfma_f32_16x16x32_bf16 v[80:83], v[238:241], v[108:111], v[80:83]
	ds_read_b64_tr_b16 v[212:213], v179 offset:16384
	ds_read_b64_tr_b16 v[214:215], v179 offset:20480
	v_add_f32_e32 v222, v222, v156
	v_mfma_f32_16x16x32_bf16 v[84:87], v[238:241], v[124:127], v[84:87]
	v_add_f32_e32 v222, v222, v157
	v_cvt_pk_bf16_f32 v198, v156, v157
	s_waitcnt lgkmcnt(8)
	v_mfma_f32_16x16x32_bf16 v[88:91], v[242:245], v[108:111], v[88:91]
	ds_read_b64_tr_b16 v[230:231], v180 offset:16384
	ds_read_b64_tr_b16 v[232:233], v180 offset:20480
	v_add_f32_e32 v222, v222, v158
	v_mfma_f32_16x16x32_bf16 v[92:95], v[242:245], v[124:127], v[92:95]
	v_add_f32_e32 v222, v222, v159
	v_cvt_pk_bf16_f32 v199, v158, v159
	s_waitcnt lgkmcnt(8)
	v_mfma_f32_16x16x32_bf16 v[0:3], v[200:203], v[184:187], v[0:3]
	v_exp_f32_e32 v64, v64
	v_mfma_f32_16x16x32_bf16 v[32:35], v[200:203], v[192:195], v[32:35]
	ds_read_b64_tr_b16 v[234:235], v182 offset:16384
	ds_read_b64_tr_b16 v[236:237], v182 offset:20480
	v_exp_f32_e32 v65, v65
	s_waitcnt lgkmcnt(8)
; __device__ __forceinline__ void qkt(f32x16& p0, f32x16& p1, const bf16* Ks, const bf16x8* qr, int r32, int hi) {
;   p0 = f32x16{}; p1 = f32x16{};
; #pragma unroll
;   for (int d0 = 0; d0 < 8; ++d0) { int cb = (d0 * 16 + hi * 8) * 2;
;     bf16x8 b0 = *reinterpret_cast<const bf16x8*>((const char*)Ks + KSWZ(r32, cb));
;     bf16x8 b1 = *reinterpret_cast<const bf16x8*>((const char*)Ks + KSWZ(32 + r32, cb));
;     p0 = __builtin_amdgcn_mfma_f32_32x32x16_bf16(b0, qr[d0], p0, 0, 0, 0);
;     p1 = __builtin_amdgcn_mfma_f32_32x32x16_bf16(b1, qr[d0], p1, 0, 0, 0); }
; }
; __device__ __forceinline__ int v_st(int k, int c) { const int kk = (k & ~0xC) | ((k & 4) << 1) | ((k & 8) >> 1); return ((kk >> 3) * 4 + (c >> 5)) * 512 + ((kk & 7) * 32 + (c & 31)) * 2; }
; __device__ __forceinline__ int v_rd_base(int lane) { return ((lane & 3) << 3) | (((lane >> 2) & 3) << 6) | (((lane >> 4) & 1) << 5) | (((lane >> 5) & 1) << 8); }
; template <int OFF> __device__ __forceinline__ s16x4 tr_read(int vb) {
;   s16x4 r; asm volatile("ds_read_b64_tr_b16 %0, %1 offset:%2" : "=&v"(r) : "v"(vb), "i"(OFF) : "memory"); return r;
; }
; template <int D0> __device__ __forceinline__ void pv_one(f32x16& od, int vb, bf16x8 pa0, bf16x8 pa1, bf16x8 pa2, bf16x8 pa3) {
;   const s16x4 l0 = tr_read<v_rd_off(D0, 0, 0)>(vb), h0 = tr_read<v_rd_off(D0, 0, 1)>(vb), l1 = tr_read<v_rd_off(D0, 1, 0)>(vb), h1 = tr_read<v_rd_off(D0, 1, 1)>(vb);
;   const s16x4 l2 = tr_read<v_rd_off(D0, 2, 0)>(vb), h2 = tr_read<v_rd_off(D0, 2, 1)>(vb), l3 = tr_read<v_rd_off(D0, 3, 0)>(vb), h3 = tr_read<v_rd_off(D0, 3, 1)>(vb);
;   asm volatile("s_waitcnt lgkmcnt(0)" ::: "memory"); SBAR();
;     ...
;   od = __builtin_amdgcn_mfma_f32_32x32x16_bf16(pa0, PK(l0, h0), od, 0, 0, 0);
;   od = __builtin_amdgcn_mfma_f32_32x32x16_bf16(pa1, PK(l1, h1), od, 0, 0, 0);
;   od = __builtin_amdgcn_mfma_f32_32x32x16_bf16(pa2, PK(l2, h2), od, 0, 0, 0);
;   od = __builtin_amdgcn_mfma_f32_32x32x16_bf16(pa3, PK(l3, h3), od, 0, 0, 0);
;     ...
; }
; __device__ __forceinline__ void pv_d0(f32x16* o, int vb, bf16x8 pa0, bf16x8 pa1, bf16x8 pa2, bf16x8 pa3) {
;   pv_one<0>(o[0], vb, pa0, pa1, pa2, pa3); pv_one<1>(o[1], vb, pa0, pa1, pa2, pa3); pv_one<2>(o[2], vb, pa0, pa1, pa2, pa3); pv_one<3>(o[3], vb, pa0, pa1, pa2, pa3);
;     ...
;   for (int p = 0; p + 2 < NP; p += 2) {
;     PAIR_FULL(0, 1, p + 1);
;     PAIR_FULL(1, 0, p + 2);
	v_mfma_f32_16x16x32_bf16 v[4:7], v[204:207], v[184:187], v[4:7]
	v_exp_f32_e32 v66, v66
	s_waitcnt vmcnt(3)
	ds_write_b128 v181, v[246:249] offset:0
	v_mfma_f32_16x16x32_bf16 v[36:39], v[204:207], v[192:195], v[36:39]
	ds_read_b64_tr_b16 v[238:239], v216 offset:16384
	ds_read_b64_tr_b16 v[240:241], v216 offset:20480
	v_exp_f32_e32 v67, v67
	s_waitcnt lgkmcnt(9)
	v_mfma_f32_16x16x32_bf16 v[8:11], v[208:211], v[184:187], v[8:11]
	v_exp_f32_e32 v68, v68
	v_mfma_f32_16x16x32_bf16 v[40:43], v[208:211], v[192:195], v[40:43]
	ds_read_b64_tr_b16 v[242:243], v217 offset:16384
	ds_read_b64_tr_b16 v[244:245], v217 offset:20480
	v_exp_f32_e32 v69, v69
	s_waitcnt lgkmcnt(9)
	v_mfma_f32_16x16x32_bf16 v[12:15], v[212:215], v[184:187], v[12:15]
	v_exp_f32_e32 v70, v70
	s_waitcnt vmcnt(2)
	ds_write_b128 v181, v[250:253] offset:8192
	v_mfma_f32_16x16x32_bf16 v[44:47], v[212:215], v[192:195], v[44:47]
	ds_read_b64_tr_b16 v[200:201], v176 offset:24576
	ds_read_b64_tr_b16 v[202:203], v176 offset:28672
	v_exp_f32_e32 v71, v71
	s_waitcnt lgkmcnt(10)
	v_mfma_f32_16x16x32_bf16 v[16:19], v[230:233], v[184:187], v[16:19]
	v_exp_f32_e32 v72, v72
	v_mfma_f32_16x16x32_bf16 v[48:51], v[230:233], v[192:195], v[48:51]
	ds_read_b64_tr_b16 v[204:205], v177 offset:24576
	ds_read_b64_tr_b16 v[206:207], v177 offset:28672
	v_exp_f32_e32 v73, v73
	s_waitcnt lgkmcnt(10)
	v_mfma_f32_16x16x32_bf16 v[20:23], v[234:237], v[184:187], v[20:23]
	v_exp_f32_e32 v74, v74
	s_waitcnt vmcnt(1)
	ds_write_b128 v219, v[164:167] offset:49152
	v_mfma_f32_16x16x32_bf16 v[52:55], v[234:237], v[192:195], v[52:55]
	ds_read_b64_tr_b16 v[208:209], v178 offset:24576
	ds_read_b64_tr_b16 v[210:211], v178 offset:28672
	v_exp_f32_e32 v75, v75
	s_waitcnt lgkmcnt(10)
	v_mfma_f32_16x16x32_bf16 v[24:27], v[238:241], v[184:187], v[24:27]
	v_exp_f32_e32 v76, v76
	v_mfma_f32_16x16x32_bf16 v[56:59], v[238:241], v[192:195], v[56:59]
	ds_read_b64_tr_b16 v[212:213], v179 offset:24576
	ds_read_b64_tr_b16 v[214:215], v179 offset:28672
	v_exp_f32_e32 v77, v77
	s_waitcnt lgkmcnt(10)
	v_mfma_f32_16x16x32_bf16 v[28:31], v[242:245], v[184:187], v[28:31]
	v_exp_f32_e32 v78, v78
	s_waitcnt vmcnt(0)
	ds_write_b128 v219, v[160:163] offset:57344
	v_mfma_f32_16x16x32_bf16 v[60:63], v[242:245], v[192:195], v[60:63]
	ds_read_b64_tr_b16 v[230:231], v180 offset:24576
	ds_read_b64_tr_b16 v[232:233], v180 offset:28672
	v_exp_f32_e32 v79, v79
	s_waitcnt lgkmcnt(10)
	v_mfma_f32_16x16x32_bf16 v[0:3], v[200:203], v[188:191], v[0:3]
	v_exp_f32_e32 v80, v80
	v_mfma_f32_16x16x32_bf16 v[32:35], v[200:203], v[196:199], v[32:35]
	ds_read_b64_tr_b16 v[234:235], v182 offset:24576
	ds_read_b64_tr_b16 v[236:237], v182 offset:28672
	ds_read_b128 v[200:203], v172 offset:49152
	v_exp_f32_e32 v81, v81
	s_waitcnt lgkmcnt(11)
	v_mfma_f32_16x16x32_bf16 v[4:7], v[204:207], v[188:191], v[4:7]
	v_exp_f32_e32 v82, v82
	v_mfma_f32_16x16x32_bf16 v[36:39], v[204:207], v[196:199], v[36:39]
	ds_read_b64_tr_b16 v[238:239], v216 offset:24576
	ds_read_b64_tr_b16 v[240:241], v216 offset:28672
	ds_read_b128 v[204:207], v172 offset:53248
	v_exp_f32_e32 v83, v83
	s_waitcnt lgkmcnt(11)
	v_mfma_f32_16x16x32_bf16 v[8:11], v[208:211], v[188:191], v[8:11]
	v_exp_f32_e32 v84, v84
	v_mfma_f32_16x16x32_bf16 v[40:43], v[208:211], v[196:199], v[40:43]
	ds_read_b64_tr_b16 v[242:243], v217 offset:24576
	ds_read_b64_tr_b16 v[244:245], v217 offset:28672
	ds_read_b128 v[208:211], v172 offset:57344
	v_exp_f32_e32 v85, v85
	s_waitcnt lgkmcnt(12)
	v_mfma_f32_16x16x32_bf16 v[12:15], v[212:215], v[188:191], v[12:15]
	v_exp_f32_e32 v86, v86
	v_mfma_f32_16x16x32_bf16 v[44:47], v[212:215], v[196:199], v[44:47]
	ds_read_b128 v[212:215], v172 offset:61440
	v_exp_f32_e32 v87, v87
	s_waitcnt lgkmcnt(10)
	v_mfma_f32_16x16x32_bf16 v[16:19], v[230:233], v[188:191], v[16:19]
	v_exp_f32_e32 v88, v88
	v_mfma_f32_16x16x32_bf16 v[48:51], v[230:233], v[196:199], v[48:51]
	ds_read_b128 v[230:233], v173 offset:49152
	v_exp_f32_e32 v89, v89
	s_waitcnt lgkmcnt(9)
	v_mfma_f32_16x16x32_bf16 v[20:23], v[234:237], v[188:191], v[20:23]
	v_exp_f32_e32 v90, v90
	v_mfma_f32_16x16x32_bf16 v[52:55], v[234:237], v[196:199], v[52:55]
	ds_read_b128 v[234:237], v173 offset:53248
	v_exp_f32_e32 v91, v91
	s_waitcnt lgkmcnt(7)
	v_mfma_f32_16x16x32_bf16 v[24:27], v[238:241], v[188:191], v[24:27]
	v_exp_f32_e32 v92, v92
	v_mfma_f32_16x16x32_bf16 v[56:59], v[238:241], v[196:199], v[56:59]
	ds_read_b128 v[238:241], v173 offset:57344
	v_exp_f32_e32 v93, v93
	s_waitcnt lgkmcnt(5)
	v_mfma_f32_16x16x32_bf16 v[28:31], v[242:245], v[188:191], v[28:31]
	v_exp_f32_e32 v94, v94
	v_mfma_f32_16x16x32_bf16 v[60:63], v[242:245], v[196:199], v[60:63]
	ds_read_b128 v[242:245], v173 offset:61440
	v_exp_f32_e32 v95, v95
	s_barrier
; __device__ __forceinline__ void qkt(f32x16& p0, f32x16& p1, const bf16* Ks, const bf16x8* qr, int r32, int hi) {
;   p0 = f32x16{}; p1 = f32x16{};
; #pragma unroll
;   for (int d0 = 0; d0 < 8; ++d0) { int cb = (d0 * 16 + hi * 8) * 2;
;     bf16x8 b0 = *reinterpret_cast<const bf16x8*>((const char*)Ks + KSWZ(r32, cb));
;     bf16x8 b1 = *reinterpret_cast<const bf16x8*>((const char*)Ks + KSWZ(32 + r32, cb));
;     p0 = __builtin_amdgcn_mfma_f32_32x32x16_bf16(b0, qr[d0], p0, 0, 0, 0);
;     p1 = __builtin_amdgcn_mfma_f32_32x32x16_bf16(b1, qr[d0], p1, 0, 0, 0); }
; }
; __device__ __forceinline__ int v_st(int k, int c) { const int kk = (k & ~0xC) | ((k & 4) << 1) | ((k & 8) >> 1); return ((kk >> 3) * 4 + (c >> 5)) * 512 + ((kk & 7) * 32 + (c & 31)) * 2; }
; __device__ __forceinline__ int v_rd_base(int lane) { return ((lane & 3) << 3) | (((lane >> 2) & 3) << 6) | (((lane >> 4) & 1) << 5) | (((lane >> 5) & 1) << 8); }
; template <int OFF> __device__ __forceinline__ s16x4 tr_read(int vb) {
;   s16x4 r; asm volatile("ds_read_b64_tr_b16 %0, %1 offset:%2" : "=&v"(r) : "v"(vb), "i"(OFF) : "memory"); return r;
; }
; template <int D0> __device__ __forceinline__ void pv_one(f32x16& od, int vb, bf16x8 pa0, bf16x8 pa1, bf16x8 pa2, bf16x8 pa3) {
;   const s16x4 l0 = tr_read<v_rd_off(D0, 0, 0)>(vb), h0 = tr_read<v_rd_off(D0, 0, 1)>(vb), l1 = tr_read<v_rd_off(D0, 1, 0)>(vb), h1 = tr_read<v_rd_off(D0, 1, 1)>(vb);
;   const s16x4 l2 = tr_read<v_rd_off(D0, 2, 0)>(vb), h2 = tr_read<v_rd_off(D0, 2, 1)>(vb), l3 = tr_read<v_rd_off(D0, 3, 0)>(vb), h3 = tr_read<v_rd_off(D0, 3, 1)>(vb);
;   asm volatile("s_waitcnt lgkmcnt(0)" ::: "memory"); SBAR();
;     ...
;   od = __builtin_amdgcn_mfma_f32_32x32x16_bf16(pa0, PK(l0, h0), od, 0, 0, 0);
;   od = __builtin_amdgcn_mfma_f32_32x32x16_bf16(pa1, PK(l1, h1), od, 0, 0, 0);
;   od = __builtin_amdgcn_mfma_f32_32x32x16_bf16(pa2, PK(l2, h2), od, 0, 0, 0);
;   od = __builtin_amdgcn_mfma_f32_32x32x16_bf16(pa3, PK(l3, h3), od, 0, 0, 0);
;     ...
; }
; __device__ __forceinline__ void pv_d0(f32x16* o, int vb, bf16x8 pa0, bf16x8 pa1, bf16x8 pa2, bf16x8 pa3) {
;   pv_one<0>(o[0], vb, pa0, pa1, pa2, pa3); pv_one<1>(o[1], vb, pa0, pa1, pa2, pa3); pv_one<2>(o[2], vb, pa0, pa1, pa2, pa3); pv_one<3>(o[3], vb, pa0, pa1, pa2, pa3);
;     ...
;   for (int p = 0; p + 2 < NP; p += 2) {
;     PAIR_FULL(0, 1, p + 1);
;     PAIR_FULL(1, 0, p + 2);
	v_mfma_f32_16x16x32_bf16 v[128:131], v[200:203], v[96:99], 0
	v_add_f32_e32 v169, v169, v64
	global_load_dwordx4 v[246:249], v183, s[98:99]
	v_mfma_f32_16x16x32_bf16 v[132:135], v[200:203], v[112:115], 0
	ds_read_b128 v[200:203], v174 offset:49152
	v_add_f32_e32 v169, v169, v65
	v_cvt_pk_bf16_f32 v184, v64, v65
	v_mfma_f32_16x16x32_bf16 v[136:139], v[204:207], v[96:99], 0
	v_add_f32_e32 v169, v169, v66
	v_mfma_f32_16x16x32_bf16 v[140:143], v[204:207], v[112:115], 0
	ds_read_b128 v[204:207], v174 offset:53248
	v_add_f32_e32 v169, v169, v67
	v_cvt_pk_bf16_f32 v185, v66, v67
	s_waitcnt lgkmcnt(7)
	v_mfma_f32_16x16x32_bf16 v[144:147], v[208:211], v[96:99], 0
	v_add_f32_e32 v222, v222, v68
	global_load_dwordx4 v[250:253], v183, s[100:101]
	s_add_u32 s98, s98, 0x150000
	s_addc_u32 s99, s99, 0
	s_add_u32 s100, s100, 0x150000
	s_addc_u32 s101, s101, 0
	v_mfma_f32_16x16x32_bf16 v[148:151], v[208:211], v[112:115], 0
	ds_read_b128 v[208:211], v174 offset:57344
	v_add_f32_e32 v222, v222, v69
	v_cvt_pk_bf16_f32 v186, v72, v73
	s_waitcnt lgkmcnt(7)
	v_mfma_f32_16x16x32_bf16 v[152:155], v[212:215], v[96:99], 0
	v_add_f32_e32 v222, v222, v70
	v_mfma_f32_16x16x32_bf16 v[156:159], v[212:215], v[112:115], 0
	ds_read_b128 v[212:215], v174 offset:61440
	v_add_f32_e32 v222, v222, v71
	v_cvt_pk_bf16_f32 v187, v74, v75
	s_waitcnt lgkmcnt(7)
	v_mfma_f32_16x16x32_bf16 v[128:131], v[230:233], v[100:103], v[128:131]
	v_add_f32_e32 v169, v169, v72
	global_load_dwordx4 v[164:167], v183, s[0:1] offset:512
	v_mfma_f32_16x16x32_bf16 v[132:135], v[230:233], v[116:119], v[132:135]
	ds_read_b128 v[230:233], v175 offset:49152
	v_add_f32_e32 v169, v169, v73
	v_cvt_pk_bf16_f32 v188, v80, v81
	s_waitcnt lgkmcnt(7)
	v_mfma_f32_16x16x32_bf16 v[136:139], v[234:237], v[100:103], v[136:139]
	v_add_f32_e32 v169, v169, v74
	v_mfma_f32_16x16x32_bf16 v[140:143], v[234:237], v[116:119], v[140:143]
	ds_read_b128 v[234:237], v175 offset:53248
	v_add_f32_e32 v169, v169, v75
	v_cvt_pk_bf16_f32 v189, v82, v83
	s_waitcnt lgkmcnt(7)
	v_mfma_f32_16x16x32_bf16 v[144:147], v[238:241], v[100:103], v[144:147]
	v_add_f32_e32 v222, v222, v76
	global_load_dwordx4 v[160:163], v183, s[4:5] offset:512
	s_add_u32 s0, s0, 0x150000
	s_addc_u32 s1, s1, 0
	s_add_u32 s4, s4, 0x150000
	s_addc_u32 s5, s5, 0
	v_mfma_f32_16x16x32_bf16 v[148:151], v[238:241], v[116:119], v[148:151]
	ds_read_b128 v[238:241], v175 offset:57344
	v_add_f32_e32 v222, v222, v77
	v_cvt_pk_bf16_f32 v190, v88, v89
	s_waitcnt lgkmcnt(7)
	v_mfma_f32_16x16x32_bf16 v[152:155], v[242:245], v[100:103], v[152:155]
	v_add_f32_e32 v222, v222, v78
	v_mfma_f32_16x16x32_bf16 v[156:159], v[242:245], v[116:119], v[156:159]
	ds_read_b128 v[242:245], v175 offset:61440
	v_add_f32_e32 v222, v222, v79
	v_cvt_pk_bf16_f32 v191, v90, v91
	s_waitcnt lgkmcnt(7)
	v_mfma_f32_16x16x32_bf16 v[128:131], v[200:203], v[104:107], v[128:131]
	v_add_f32_e32 v169, v169, v80
	v_mfma_f32_16x16x32_bf16 v[132:135], v[200:203], v[120:123], v[132:135]
	v_add_f32_e32 v169, v169, v81
	v_cvt_pk_bf16_f32 v192, v68, v69
	s_waitcnt lgkmcnt(6)
	v_mfma_f32_16x16x32_bf16 v[136:139], v[204:207], v[104:107], v[136:139]
	v_add_f32_e32 v169, v169, v82
	v_mfma_f32_16x16x32_bf16 v[140:143], v[204:207], v[120:123], v[140:143]
	v_add_f32_e32 v169, v169, v83
	v_cvt_pk_bf16_f32 v193, v70, v71
	s_waitcnt lgkmcnt(5)
	v_mfma_f32_16x16x32_bf16 v[144:147], v[208:211], v[104:107], v[144:147]
	v_add_f32_e32 v222, v222, v84
	v_mfma_f32_16x16x32_bf16 v[148:151], v[208:211], v[120:123], v[148:151]
	v_add_f32_e32 v222, v222, v85
	v_cvt_pk_bf16_f32 v194, v76, v77
	s_waitcnt lgkmcnt(4)
	v_mfma_f32_16x16x32_bf16 v[152:155], v[212:215], v[104:107], v[152:155]
	ds_read_b64_tr_b16 v[200:201], v176 offset:32768
	ds_read_b64_tr_b16 v[202:203], v176 offset:36864
	v_add_f32_e32 v222, v222, v86
	v_mfma_f32_16x16x32_bf16 v[156:159], v[212:215], v[120:123], v[156:159]
	v_add_f32_e32 v222, v222, v87
	v_cvt_pk_bf16_f32 v195, v78, v79
	s_waitcnt lgkmcnt(5)
	v_mfma_f32_16x16x32_bf16 v[128:131], v[230:233], v[108:111], v[128:131]
	ds_read_b64_tr_b16 v[204:205], v177 offset:32768
	ds_read_b64_tr_b16 v[206:207], v177 offset:36864
	v_add_f32_e32 v169, v169, v88
	v_mfma_f32_16x16x32_bf16 v[132:135], v[230:233], v[124:127], v[132:135]
	v_add_f32_e32 v169, v169, v89
	v_cvt_pk_bf16_f32 v196, v84, v85
	s_waitcnt lgkmcnt(6)
	v_mfma_f32_16x16x32_bf16 v[136:139], v[234:237], v[108:111], v[136:139]
	ds_read_b64_tr_b16 v[208:209], v178 offset:32768
	ds_read_b64_tr_b16 v[210:211], v178 offset:36864
	v_add_f32_e32 v169, v169, v90
	v_mfma_f32_16x16x32_bf16 v[140:143], v[234:237], v[124:127], v[140:143]
	v_add_f32_e32 v169, v169, v91
	v_cvt_pk_bf16_f32 v197, v86, v87
	s_waitcnt lgkmcnt(7)
	v_mfma_f32_16x16x32_bf16 v[144:147], v[238:241], v[108:111], v[144:147]
	ds_read_b64_tr_b16 v[212:213], v179 offset:32768
	ds_read_b64_tr_b16 v[214:215], v179 offset:36864
	v_add_f32_e32 v222, v222, v92
	v_mfma_f32_16x16x32_bf16 v[148:151], v[238:241], v[124:127], v[148:151]
	v_add_f32_e32 v222, v222, v93
	v_cvt_pk_bf16_f32 v198, v92, v93
	s_waitcnt lgkmcnt(8)
	v_mfma_f32_16x16x32_bf16 v[152:155], v[242:245], v[108:111], v[152:155]
	ds_read_b64_tr_b16 v[230:231], v180 offset:32768
	ds_read_b64_tr_b16 v[232:233], v180 offset:36864
	v_add_f32_e32 v222, v222, v94
	v_mfma_f32_16x16x32_bf16 v[156:159], v[242:245], v[124:127], v[156:159]
	v_add_f32_e32 v222, v222, v95
	v_cvt_pk_bf16_f32 v199, v94, v95
	s_waitcnt lgkmcnt(8)
	v_mfma_f32_16x16x32_bf16 v[0:3], v[200:203], v[184:187], v[0:3]
	v_exp_f32_e32 v128, v128
	v_mfma_f32_16x16x32_bf16 v[32:35], v[200:203], v[192:195], v[32:35]
	ds_read_b64_tr_b16 v[234:235], v182 offset:32768
	ds_read_b64_tr_b16 v[236:237], v182 offset:36864
	v_exp_f32_e32 v129, v129
	s_waitcnt lgkmcnt(8)
; __device__ __forceinline__ void qkt(f32x16& p0, f32x16& p1, const bf16* Ks, const bf16x8* qr, int r32, int hi) {
;   p0 = f32x16{}; p1 = f32x16{};
; #pragma unroll
;   for (int d0 = 0; d0 < 8; ++d0) { int cb = (d0 * 16 + hi * 8) * 2;
;     bf16x8 b0 = *reinterpret_cast<const bf16x8*>((const char*)Ks + KSWZ(r32, cb));
;     bf16x8 b1 = *reinterpret_cast<const bf16x8*>((const char*)Ks + KSWZ(32 + r32, cb));
;     p0 = __builtin_amdgcn_mfma_f32_32x32x16_bf16(b0, qr[d0], p0, 0, 0, 0);
;     p1 = __builtin_amdgcn_mfma_f32_32x32x16_bf16(b1, qr[d0], p1, 0, 0, 0); }
; }
; __device__ __forceinline__ int v_st(int k, int c) { const int kk = (k & ~0xC) | ((k & 4) << 1) | ((k & 8) >> 1); return ((kk >> 3) * 4 + (c >> 5)) * 512 + ((kk & 7) * 32 + (c & 31)) * 2; }
; __device__ __forceinline__ int v_rd_base(int lane) { return ((lane & 3) << 3) | (((lane >> 2) & 3) << 6) | (((lane >> 4) & 1) << 5) | (((lane >> 5) & 1) << 8); }
; template <int OFF> __device__ __forceinline__ s16x4 tr_read(int vb) {
;   s16x4 r; asm volatile("ds_read_b64_tr_b16 %0, %1 offset:%2" : "=&v"(r) : "v"(vb), "i"(OFF) : "memory"); return r;
; }
; template <int D0> __device__ __forceinline__ void pv_one(f32x16& od, int vb, bf16x8 pa0, bf16x8 pa1, bf16x8 pa2, bf16x8 pa3) {
;   const s16x4 l0 = tr_read<v_rd_off(D0, 0, 0)>(vb), h0 = tr_read<v_rd_off(D0, 0, 1)>(vb), l1 = tr_read<v_rd_off(D0, 1, 0)>(vb), h1 = tr_read<v_rd_off(D0, 1, 1)>(vb);
;   const s16x4 l2 = tr_read<v_rd_off(D0, 2, 0)>(vb), h2 = tr_read<v_rd_off(D0, 2, 1)>(vb), l3 = tr_read<v_rd_off(D0, 3, 0)>(vb), h3 = tr_read<v_rd_off(D0, 3, 1)>(vb);
;   asm volatile("s_waitcnt lgkmcnt(0)" ::: "memory"); SBAR();
;     ...
;   od = __builtin_amdgcn_mfma_f32_32x32x16_bf16(pa0, PK(l0, h0), od, 0, 0, 0);
;   od = __builtin_amdgcn_mfma_f32_32x32x16_bf16(pa1, PK(l1, h1), od, 0, 0, 0);
;   od = __builtin_amdgcn_mfma_f32_32x32x16_bf16(pa2, PK(l2, h2), od, 0, 0, 0);
;   od = __builtin_amdgcn_mfma_f32_32x32x16_bf16(pa3, PK(l3, h3), od, 0, 0, 0);
;     ...
; }
; __device__ __forceinline__ void pv_d0(f32x16* o, int vb, bf16x8 pa0, bf16x8 pa1, bf16x8 pa2, bf16x8 pa3) {
;   pv_one<0>(o[0], vb, pa0, pa1, pa2, pa3); pv_one<1>(o[1], vb, pa0, pa1, pa2, pa3); pv_one<2>(o[2], vb, pa0, pa1, pa2, pa3); pv_one<3>(o[3], vb, pa0, pa1, pa2, pa3);
;     ...
;   for (int p = 0; p + 2 < NP; p += 2) {
;     PAIR_FULL(0, 1, p + 1);
;     PAIR_FULL(1, 0, p + 2);
	v_mfma_f32_16x16x32_bf16 v[4:7], v[204:207], v[184:187], v[4:7]
	v_exp_f32_e32 v130, v130
	s_waitcnt vmcnt(3)
	ds_write_b128 v181, v[246:249] offset:16384
	v_mfma_f32_16x16x32_bf16 v[36:39], v[204:207], v[192:195], v[36:39]
	ds_read_b64_tr_b16 v[238:239], v216 offset:32768
	ds_read_b64_tr_b16 v[240:241], v216 offset:36864
	v_exp_f32_e32 v131, v131
	s_waitcnt lgkmcnt(9)
	v_mfma_f32_16x16x32_bf16 v[8:11], v[208:211], v[184:187], v[8:11]
	v_exp_f32_e32 v132, v132
	v_mfma_f32_16x16x32_bf16 v[40:43], v[208:211], v[192:195], v[40:43]
	ds_read_b64_tr_b16 v[242:243], v217 offset:32768
	ds_read_b64_tr_b16 v[244:245], v217 offset:36864
	v_exp_f32_e32 v133, v133
	s_waitcnt lgkmcnt(9)
	v_mfma_f32_16x16x32_bf16 v[12:15], v[212:215], v[184:187], v[12:15]
	v_exp_f32_e32 v134, v134
	s_waitcnt vmcnt(2)
	ds_write_b128 v181, v[250:253] offset:24576
	v_mfma_f32_16x16x32_bf16 v[44:47], v[212:215], v[192:195], v[44:47]
	ds_read_b64_tr_b16 v[200:201], v176 offset:40960
	ds_read_b64_tr_b16 v[202:203], v176 offset:45056
	v_exp_f32_e32 v135, v135
	s_waitcnt lgkmcnt(10)
	v_mfma_f32_16x16x32_bf16 v[16:19], v[230:233], v[184:187], v[16:19]
	v_exp_f32_e32 v136, v136
	v_mfma_f32_16x16x32_bf16 v[48:51], v[230:233], v[192:195], v[48:51]
	ds_read_b64_tr_b16 v[204:205], v177 offset:40960
	ds_read_b64_tr_b16 v[206:207], v177 offset:45056
	v_exp_f32_e32 v137, v137
	s_waitcnt lgkmcnt(10)
	v_mfma_f32_16x16x32_bf16 v[20:23], v[234:237], v[184:187], v[20:23]
	v_exp_f32_e32 v138, v138
	s_waitcnt vmcnt(1)
	ds_write_b128 v219, v[164:167] offset:0
	v_mfma_f32_16x16x32_bf16 v[52:55], v[234:237], v[192:195], v[52:55]
	ds_read_b64_tr_b16 v[208:209], v178 offset:40960
	ds_read_b64_tr_b16 v[210:211], v178 offset:45056
	v_exp_f32_e32 v139, v139
	s_waitcnt lgkmcnt(10)
	v_mfma_f32_16x16x32_bf16 v[24:27], v[238:241], v[184:187], v[24:27]
	v_exp_f32_e32 v140, v140
	v_mfma_f32_16x16x32_bf16 v[56:59], v[238:241], v[192:195], v[56:59]
	ds_read_b64_tr_b16 v[212:213], v179 offset:40960
	ds_read_b64_tr_b16 v[214:215], v179 offset:45056
	v_exp_f32_e32 v141, v141
	s_waitcnt lgkmcnt(10)
	v_mfma_f32_16x16x32_bf16 v[28:31], v[242:245], v[184:187], v[28:31]
	v_exp_f32_e32 v142, v142
	s_waitcnt vmcnt(0)
	ds_write_b128 v219, v[160:163] offset:8192
	v_mfma_f32_16x16x32_bf16 v[60:63], v[242:245], v[192:195], v[60:63]
	ds_read_b64_tr_b16 v[230:231], v180 offset:40960
	ds_read_b64_tr_b16 v[232:233], v180 offset:45056
	v_exp_f32_e32 v143, v143
	s_waitcnt lgkmcnt(10)
	v_mfma_f32_16x16x32_bf16 v[0:3], v[200:203], v[188:191], v[0:3]
	v_exp_f32_e32 v144, v144
	v_mfma_f32_16x16x32_bf16 v[32:35], v[200:203], v[196:199], v[32:35]
	ds_read_b64_tr_b16 v[234:235], v182 offset:40960
	ds_read_b64_tr_b16 v[236:237], v182 offset:45056
	ds_read_b128 v[200:203], v172 offset:0
	v_exp_f32_e32 v145, v145
	s_waitcnt lgkmcnt(11)
	v_mfma_f32_16x16x32_bf16 v[4:7], v[204:207], v[188:191], v[4:7]
	v_exp_f32_e32 v146, v146
	v_mfma_f32_16x16x32_bf16 v[36:39], v[204:207], v[196:199], v[36:39]
	ds_read_b64_tr_b16 v[238:239], v216 offset:40960
	ds_read_b64_tr_b16 v[240:241], v216 offset:45056
	ds_read_b128 v[204:207], v172 offset:4096
	v_exp_f32_e32 v147, v147
	s_waitcnt lgkmcnt(11)
	v_mfma_f32_16x16x32_bf16 v[8:11], v[208:211], v[188:191], v[8:11]
	v_exp_f32_e32 v148, v148
	v_mfma_f32_16x16x32_bf16 v[40:43], v[208:211], v[196:199], v[40:43]
	ds_read_b64_tr_b16 v[242:243], v217 offset:40960
	ds_read_b64_tr_b16 v[244:245], v217 offset:45056
	ds_read_b128 v[208:211], v172 offset:8192
	v_exp_f32_e32 v149, v149
	s_waitcnt lgkmcnt(12)
	v_mfma_f32_16x16x32_bf16 v[12:15], v[212:215], v[188:191], v[12:15]
	v_exp_f32_e32 v150, v150
	v_mfma_f32_16x16x32_bf16 v[44:47], v[212:215], v[196:199], v[44:47]
	ds_read_b128 v[212:215], v172 offset:12288
	v_exp_f32_e32 v151, v151
	s_waitcnt lgkmcnt(10)
	v_mfma_f32_16x16x32_bf16 v[16:19], v[230:233], v[188:191], v[16:19]
	v_exp_f32_e32 v152, v152
	v_mfma_f32_16x16x32_bf16 v[48:51], v[230:233], v[196:199], v[48:51]
	ds_read_b128 v[230:233], v173 offset:0
	v_exp_f32_e32 v153, v153
	s_waitcnt lgkmcnt(9)
	v_mfma_f32_16x16x32_bf16 v[20:23], v[234:237], v[188:191], v[20:23]
	v_exp_f32_e32 v154, v154
	v_mfma_f32_16x16x32_bf16 v[52:55], v[234:237], v[196:199], v[52:55]
	ds_read_b128 v[234:237], v173 offset:4096
	v_exp_f32_e32 v155, v155
	s_waitcnt lgkmcnt(7)
	v_mfma_f32_16x16x32_bf16 v[24:27], v[238:241], v[188:191], v[24:27]
	v_exp_f32_e32 v156, v156
	v_mfma_f32_16x16x32_bf16 v[56:59], v[238:241], v[196:199], v[56:59]
	ds_read_b128 v[238:241], v173 offset:8192
	v_exp_f32_e32 v157, v157
	s_waitcnt lgkmcnt(5)
	v_mfma_f32_16x16x32_bf16 v[28:31], v[242:245], v[188:191], v[28:31]
	v_exp_f32_e32 v158, v158
	v_mfma_f32_16x16x32_bf16 v[60:63], v[242:245], v[196:199], v[60:63]
	ds_read_b128 v[242:245], v173 offset:12288
	v_exp_f32_e32 v159, v159
	s_barrier
; __device__ __forceinline__ void qkt(f32x16& p0, f32x16& p1, const bf16* Ks, const bf16x8* qr, int r32, int hi) {
;   p0 = f32x16{}; p1 = f32x16{};
; #pragma unroll
;   for (int d0 = 0; d0 < 8; ++d0) { int cb = (d0 * 16 + hi * 8) * 2;
;     bf16x8 b0 = *reinterpret_cast<const bf16x8*>((const char*)Ks + KSWZ(r32, cb));
;     bf16x8 b1 = *reinterpret_cast<const bf16x8*>((const char*)Ks + KSWZ(32 + r32, cb));
;     p0 = __builtin_amdgcn_mfma_f32_32x32x16_bf16(b0, qr[d0], p0, 0, 0, 0);
;     p1 = __builtin_amdgcn_mfma_f32_32x32x16_bf16(b1, qr[d0], p1, 0, 0, 0); }
; }
; __device__ __forceinline__ int v_st(int k, int c) { const int kk = (k & ~0xC) | ((k & 4) << 1) | ((k & 8) >> 1); return ((kk >> 3) * 4 + (c >> 5)) * 512 + ((kk & 7) * 32 + (c & 31)) * 2; }
; __device__ __forceinline__ int v_rd_base(int lane) { return ((lane & 3) << 3) | (((lane >> 2) & 3) << 6) | (((lane >> 4) & 1) << 5) | (((lane >> 5) & 1) << 8); }
; template <int OFF> __device__ __forceinline__ s16x4 tr_read(int vb) {
;   s16x4 r; asm volatile("ds_read_b64_tr_b16 %0, %1 offset:%2" : "=&v"(r) : "v"(vb), "i"(OFF) : "memory"); return r;
; }
; template <int D0> __device__ __forceinline__ void pv_one(f32x16& od, int vb, bf16x8 pa0, bf16x8 pa1, bf16x8 pa2, bf16x8 pa3) {
;   const s16x4 l0 = tr_read<v_rd_off(D0, 0, 0)>(vb), h0 = tr_read<v_rd_off(D0, 0, 1)>(vb), l1 = tr_read<v_rd_off(D0, 1, 0)>(vb), h1 = tr_read<v_rd_off(D0, 1, 1)>(vb);
;   const s16x4 l2 = tr_read<v_rd_off(D0, 2, 0)>(vb), h2 = tr_read<v_rd_off(D0, 2, 1)>(vb), l3 = tr_read<v_rd_off(D0, 3, 0)>(vb), h3 = tr_read<v_rd_off(D0, 3, 1)>(vb);
;   asm volatile("s_waitcnt lgkmcnt(0)" ::: "memory"); SBAR();
;     ...
;   od = __builtin_amdgcn_mfma_f32_32x32x16_bf16(pa0, PK(l0, h0), od, 0, 0, 0);
;   od = __builtin_amdgcn_mfma_f32_32x32x16_bf16(pa1, PK(l1, h1), od, 0, 0, 0);
;   od = __builtin_amdgcn_mfma_f32_32x32x16_bf16(pa2, PK(l2, h2), od, 0, 0, 0);
;   od = __builtin_amdgcn_mfma_f32_32x32x16_bf16(pa3, PK(l3, h3), od, 0, 0, 0);
;     ...
; }
; __device__ __forceinline__ void pv_d0(f32x16* o, int vb, bf16x8 pa0, bf16x8 pa1, bf16x8 pa2, bf16x8 pa3) {
;   pv_one<0>(o[0], vb, pa0, pa1, pa2, pa3); pv_one<1>(o[1], vb, pa0, pa1, pa2, pa3); pv_one<2>(o[2], vb, pa0, pa1, pa2, pa3); pv_one<3>(o[3], vb, pa0, pa1, pa2, pa3);
;     ...
;   for (int p = 0; p + 2 < NP; p += 2) {
;     PAIR_FULL(0, 1, p + 1);
;     PAIR_FULL(1, 0, p + 2);
	v_mfma_f32_16x16x32_bf16 v[64:67], v[200:203], v[96:99], 0
	v_add_f32_e32 v169, v169, v128
	global_load_dwordx4 v[246:249], v183, s[98:99]
	v_mfma_f32_16x16x32_bf16 v[68:71], v[200:203], v[112:115], 0
	ds_read_b128 v[200:203], v174 offset:0
	v_add_f32_e32 v169, v169, v129
	v_cvt_pk_bf16_f32 v184, v128, v129
	v_mfma_f32_16x16x32_bf16 v[72:75], v[204:207], v[96:99], 0
	v_add_f32_e32 v169, v169, v130
	v_mfma_f32_16x16x32_bf16 v[76:79], v[204:207], v[112:115], 0
	ds_read_b128 v[204:207], v174 offset:4096
	v_add_f32_e32 v169, v169, v131
	v_cvt_pk_bf16_f32 v185, v130, v131
	s_waitcnt lgkmcnt(7)
	v_mfma_f32_16x16x32_bf16 v[80:83], v[208:211], v[96:99], 0
	v_add_f32_e32 v222, v222, v132
	global_load_dwordx4 v[250:253], v183, s[100:101]
	s_add_u32 s98, s98, 0x150000
	s_addc_u32 s99, s99, 0
	s_add_u32 s100, s100, 0x150000
	s_addc_u32 s101, s101, 0
	v_mfma_f32_16x16x32_bf16 v[84:87], v[208:211], v[112:115], 0
	ds_read_b128 v[208:211], v174 offset:8192
	v_add_f32_e32 v222, v222, v133
	v_cvt_pk_bf16_f32 v186, v136, v137
	s_waitcnt lgkmcnt(7)
	v_mfma_f32_16x16x32_bf16 v[88:91], v[212:215], v[96:99], 0
	v_add_f32_e32 v222, v222, v134
	v_mfma_f32_16x16x32_bf16 v[92:95], v[212:215], v[112:115], 0
	ds_read_b128 v[212:215], v174 offset:12288
	v_add_f32_e32 v222, v222, v135
	v_cvt_pk_bf16_f32 v187, v138, v139
	s_waitcnt lgkmcnt(7)
	v_mfma_f32_16x16x32_bf16 v[64:67], v[230:233], v[100:103], v[64:67]
	v_add_f32_e32 v169, v169, v136
	global_load_dwordx4 v[164:167], v183, s[0:1] offset:512
	v_mfma_f32_16x16x32_bf16 v[68:71], v[230:233], v[116:119], v[68:71]
	ds_read_b128 v[230:233], v175 offset:0
	v_add_f32_e32 v169, v169, v137
	v_cvt_pk_bf16_f32 v188, v144, v145
	s_waitcnt lgkmcnt(7)
	v_mfma_f32_16x16x32_bf16 v[72:75], v[234:237], v[100:103], v[72:75]
	v_add_f32_e32 v169, v169, v138
	v_mfma_f32_16x16x32_bf16 v[76:79], v[234:237], v[116:119], v[76:79]
	ds_read_b128 v[234:237], v175 offset:4096
	v_add_f32_e32 v169, v169, v139
	v_cvt_pk_bf16_f32 v189, v146, v147
	s_waitcnt lgkmcnt(7)
	v_mfma_f32_16x16x32_bf16 v[80:83], v[238:241], v[100:103], v[80:83]
	v_add_f32_e32 v222, v222, v140
	global_load_dwordx4 v[160:163], v183, s[4:5] offset:512
	s_add_u32 s0, s0, 0x150000
	s_addc_u32 s1, s1, 0
	s_add_u32 s4, s4, 0x150000
	s_addc_u32 s5, s5, 0
	v_mfma_f32_16x16x32_bf16 v[84:87], v[238:241], v[116:119], v[84:87]
	ds_read_b128 v[238:241], v175 offset:8192
	v_add_f32_e32 v222, v222, v141
	v_cvt_pk_bf16_f32 v190, v152, v153
	s_waitcnt lgkmcnt(7)
	v_mfma_f32_16x16x32_bf16 v[88:91], v[242:245], v[100:103], v[88:91]
	v_add_f32_e32 v222, v222, v142
	v_mfma_f32_16x16x32_bf16 v[92:95], v[242:245], v[116:119], v[92:95]
	ds_read_b128 v[242:245], v175 offset:12288
	v_add_f32_e32 v222, v222, v143
	v_cvt_pk_bf16_f32 v191, v154, v155
	s_waitcnt lgkmcnt(7)
	v_mfma_f32_16x16x32_bf16 v[64:67], v[200:203], v[104:107], v[64:67]
	v_add_f32_e32 v169, v169, v144
	v_mfma_f32_16x16x32_bf16 v[68:71], v[200:203], v[120:123], v[68:71]
	v_add_f32_e32 v169, v169, v145
	v_cvt_pk_bf16_f32 v192, v132, v133
	s_waitcnt lgkmcnt(6)
	v_mfma_f32_16x16x32_bf16 v[72:75], v[204:207], v[104:107], v[72:75]
	v_add_f32_e32 v169, v169, v146
	v_mfma_f32_16x16x32_bf16 v[76:79], v[204:207], v[120:123], v[76:79]
	v_add_f32_e32 v169, v169, v147
	v_cvt_pk_bf16_f32 v193, v134, v135
	s_waitcnt lgkmcnt(5)
	v_mfma_f32_16x16x32_bf16 v[80:83], v[208:211], v[104:107], v[80:83]
	v_add_f32_e32 v222, v222, v148
	v_mfma_f32_16x16x32_bf16 v[84:87], v[208:211], v[120:123], v[84:87]
	v_add_f32_e32 v222, v222, v149
	v_cvt_pk_bf16_f32 v194, v140, v141
	s_waitcnt lgkmcnt(4)
	v_mfma_f32_16x16x32_bf16 v[88:91], v[212:215], v[104:107], v[88:91]
	ds_read_b64_tr_b16 v[200:201], v176 offset:49152
	ds_read_b64_tr_b16 v[202:203], v176 offset:53248
	v_add_f32_e32 v222, v222, v150
	v_mfma_f32_16x16x32_bf16 v[92:95], v[212:215], v[120:123], v[92:95]
	v_add_f32_e32 v222, v222, v151
	v_cvt_pk_bf16_f32 v195, v142, v143
	s_waitcnt lgkmcnt(5)
	v_mfma_f32_16x16x32_bf16 v[64:67], v[230:233], v[108:111], v[64:67]
	ds_read_b64_tr_b16 v[204:205], v177 offset:49152
	ds_read_b64_tr_b16 v[206:207], v177 offset:53248
	v_add_f32_e32 v169, v169, v152
	v_mfma_f32_16x16x32_bf16 v[68:71], v[230:233], v[124:127], v[68:71]
	v_add_f32_e32 v169, v169, v153
	v_cvt_pk_bf16_f32 v196, v148, v149
	s_waitcnt lgkmcnt(6)
	v_mfma_f32_16x16x32_bf16 v[72:75], v[234:237], v[108:111], v[72:75]
	ds_read_b64_tr_b16 v[208:209], v178 offset:49152
	ds_read_b64_tr_b16 v[210:211], v178 offset:53248
	v_add_f32_e32 v169, v169, v154
	v_mfma_f32_16x16x32_bf16 v[76:79], v[234:237], v[124:127], v[76:79]
	v_add_f32_e32 v169, v169, v155
	v_cvt_pk_bf16_f32 v197, v150, v151
	s_waitcnt lgkmcnt(7)
	v_mfma_f32_16x16x32_bf16 v[80:83], v[238:241], v[108:111], v[80:83]
	ds_read_b64_tr_b16 v[212:213], v179 offset:49152
	ds_read_b64_tr_b16 v[214:215], v179 offset:53248
	v_add_f32_e32 v222, v222, v156
	v_mfma_f32_16x16x32_bf16 v[84:87], v[238:241], v[124:127], v[84:87]
	v_add_f32_e32 v222, v222, v157
	v_cvt_pk_bf16_f32 v198, v156, v157
	s_waitcnt lgkmcnt(8)
	v_mfma_f32_16x16x32_bf16 v[88:91], v[242:245], v[108:111], v[88:91]
	ds_read_b64_tr_b16 v[230:231], v180 offset:49152
	ds_read_b64_tr_b16 v[232:233], v180 offset:53248
	v_add_f32_e32 v222, v222, v158
	v_mfma_f32_16x16x32_bf16 v[92:95], v[242:245], v[124:127], v[92:95]
	v_add_f32_e32 v222, v222, v159
	v_cvt_pk_bf16_f32 v199, v158, v159
	s_waitcnt lgkmcnt(8)
	v_mfma_f32_16x16x32_bf16 v[0:3], v[200:203], v[184:187], v[0:3]
	v_exp_f32_e32 v64, v64
	v_mfma_f32_16x16x32_bf16 v[32:35], v[200:203], v[192:195], v[32:35]
	ds_read_b64_tr_b16 v[234:235], v182 offset:49152
	ds_read_b64_tr_b16 v[236:237], v182 offset:53248
	v_exp_f32_e32 v65, v65
	s_waitcnt lgkmcnt(8)
; __device__ __forceinline__ void qkt(f32x16& p0, f32x16& p1, const bf16* Ks, const bf16x8* qr, int r32, int hi) {
;   p0 = f32x16{}; p1 = f32x16{};
; #pragma unroll
;   for (int d0 = 0; d0 < 8; ++d0) { int cb = (d0 * 16 + hi * 8) * 2;
;     bf16x8 b0 = *reinterpret_cast<const bf16x8*>((const char*)Ks + KSWZ(r32, cb));
;     bf16x8 b1 = *reinterpret_cast<const bf16x8*>((const char*)Ks + KSWZ(32 + r32, cb));
;     p0 = __builtin_amdgcn_mfma_f32_32x32x16_bf16(b0, qr[d0], p0, 0, 0, 0);
;     p1 = __builtin_amdgcn_mfma_f32_32x32x16_bf16(b1, qr[d0], p1, 0, 0, 0); }
; }
; __device__ __forceinline__ int v_st(int k, int c) { const int kk = (k & ~0xC) | ((k & 4) << 1) | ((k & 8) >> 1); return ((kk >> 3) * 4 + (c >> 5)) * 512 + ((kk & 7) * 32 + (c & 31)) * 2; }
; __device__ __forceinline__ int v_rd_base(int lane) { return ((lane & 3) << 3) | (((lane >> 2) & 3) << 6) | (((lane >> 4) & 1) << 5) | (((lane >> 5) & 1) << 8); }
; template <int OFF> __device__ __forceinline__ s16x4 tr_read(int vb) {
;   s16x4 r; asm volatile("ds_read_b64_tr_b16 %0, %1 offset:%2" : "=&v"(r) : "v"(vb), "i"(OFF) : "memory"); return r;
; }
; template <int D0> __device__ __forceinline__ void pv_one(f32x16& od, int vb, bf16x8 pa0, bf16x8 pa1, bf16x8 pa2, bf16x8 pa3) {
;   const s16x4 l0 = tr_read<v_rd_off(D0, 0, 0)>(vb), h0 = tr_read<v_rd_off(D0, 0, 1)>(vb), l1 = tr_read<v_rd_off(D0, 1, 0)>(vb), h1 = tr_read<v_rd_off(D0, 1, 1)>(vb);
;   const s16x4 l2 = tr_read<v_rd_off(D0, 2, 0)>(vb), h2 = tr_read<v_rd_off(D0, 2, 1)>(vb), l3 = tr_read<v_rd_off(D0, 3, 0)>(vb), h3 = tr_read<v_rd_off(D0, 3, 1)>(vb);
;   asm volatile("s_waitcnt lgkmcnt(0)" ::: "memory"); SBAR();
;     ...
;   od = __builtin_amdgcn_mfma_f32_32x32x16_bf16(pa0, PK(l0, h0), od, 0, 0, 0);
;   od = __builtin_amdgcn_mfma_f32_32x32x16_bf16(pa1, PK(l1, h1), od, 0, 0, 0);
;   od = __builtin_amdgcn_mfma_f32_32x32x16_bf16(pa2, PK(l2, h2), od, 0, 0, 0);
;   od = __builtin_amdgcn_mfma_f32_32x32x16_bf16(pa3, PK(l3, h3), od, 0, 0, 0);
;     ...
; }
; __device__ __forceinline__ void pv_d0(f32x16* o, int vb, bf16x8 pa0, bf16x8 pa1, bf16x8 pa2, bf16x8 pa3) {
;   pv_one<0>(o[0], vb, pa0, pa1, pa2, pa3); pv_one<1>(o[1], vb, pa0, pa1, pa2, pa3); pv_one<2>(o[2], vb, pa0, pa1, pa2, pa3); pv_one<3>(o[3], vb, pa0, pa1, pa2, pa3);
;     ...
;   for (int p = 0; p + 2 < NP; p += 2) {
;     PAIR_FULL(0, 1, p + 1);
;     PAIR_FULL(1, 0, p + 2);
	v_mfma_f32_16x16x32_bf16 v[4:7], v[204:207], v[184:187], v[4:7]
	v_exp_f32_e32 v66, v66
	s_waitcnt vmcnt(3)
	ds_write_b128 v181, v[246:249] offset:32768
	v_mfma_f32_16x16x32_bf16 v[36:39], v[204:207], v[192:195], v[36:39]
	ds_read_b64_tr_b16 v[238:239], v216 offset:49152
	ds_read_b64_tr_b16 v[240:241], v216 offset:53248
	v_exp_f32_e32 v67, v67
	s_waitcnt lgkmcnt(9)
	v_mfma_f32_16x16x32_bf16 v[8:11], v[208:211], v[184:187], v[8:11]
	v_exp_f32_e32 v68, v68
	v_mfma_f32_16x16x32_bf16 v[40:43], v[208:211], v[192:195], v[40:43]
	ds_read_b64_tr_b16 v[242:243], v217 offset:49152
	ds_read_b64_tr_b16 v[244:245], v217 offset:53248
	v_exp_f32_e32 v69, v69
	s_waitcnt lgkmcnt(9)
	v_mfma_f32_16x16x32_bf16 v[12:15], v[212:215], v[184:187], v[12:15]
	v_exp_f32_e32 v70, v70
	s_waitcnt vmcnt(2)
	ds_write_b128 v181, v[250:253] offset:40960
	v_mfma_f32_16x16x32_bf16 v[44:47], v[212:215], v[192:195], v[44:47]
	ds_read_b64_tr_b16 v[200:201], v176 offset:57344
	ds_read_b64_tr_b16 v[202:203], v176 offset:61440
	v_exp_f32_e32 v71, v71
	s_waitcnt lgkmcnt(10)
	v_mfma_f32_16x16x32_bf16 v[16:19], v[230:233], v[184:187], v[16:19]
	v_exp_f32_e32 v72, v72
	v_mfma_f32_16x16x32_bf16 v[48:51], v[230:233], v[192:195], v[48:51]
	ds_read_b64_tr_b16 v[204:205], v177 offset:57344
	ds_read_b64_tr_b16 v[206:207], v177 offset:61440
	v_exp_f32_e32 v73, v73
	s_waitcnt lgkmcnt(10)
	v_mfma_f32_16x16x32_bf16 v[20:23], v[234:237], v[184:187], v[20:23]
	v_exp_f32_e32 v74, v74
	s_waitcnt vmcnt(1)
	ds_write_b128 v219, v[164:167] offset:16384
	v_mfma_f32_16x16x32_bf16 v[52:55], v[234:237], v[192:195], v[52:55]
	ds_read_b64_tr_b16 v[208:209], v178 offset:57344
	ds_read_b64_tr_b16 v[210:211], v178 offset:61440
	v_exp_f32_e32 v75, v75
	s_waitcnt lgkmcnt(10)
	v_mfma_f32_16x16x32_bf16 v[24:27], v[238:241], v[184:187], v[24:27]
	v_exp_f32_e32 v76, v76
	v_mfma_f32_16x16x32_bf16 v[56:59], v[238:241], v[192:195], v[56:59]
	ds_read_b64_tr_b16 v[212:213], v179 offset:57344
	ds_read_b64_tr_b16 v[214:215], v179 offset:61440
	v_exp_f32_e32 v77, v77
	s_waitcnt lgkmcnt(10)
	v_mfma_f32_16x16x32_bf16 v[28:31], v[242:245], v[184:187], v[28:31]
	v_exp_f32_e32 v78, v78
	s_waitcnt vmcnt(0)
	ds_write_b128 v219, v[160:163] offset:24576
	v_mfma_f32_16x16x32_bf16 v[60:63], v[242:245], v[192:195], v[60:63]
	ds_read_b64_tr_b16 v[230:231], v180 offset:57344
	ds_read_b64_tr_b16 v[232:233], v180 offset:61440
	v_exp_f32_e32 v79, v79
	s_waitcnt lgkmcnt(10)
	v_mfma_f32_16x16x32_bf16 v[0:3], v[200:203], v[188:191], v[0:3]
	v_exp_f32_e32 v80, v80
	v_mfma_f32_16x16x32_bf16 v[32:35], v[200:203], v[196:199], v[32:35]
	ds_read_b64_tr_b16 v[234:235], v182 offset:57344
	ds_read_b64_tr_b16 v[236:237], v182 offset:61440
	ds_read_b128 v[200:203], v172 offset:16384
	v_exp_f32_e32 v81, v81
	s_waitcnt lgkmcnt(11)
	v_mfma_f32_16x16x32_bf16 v[4:7], v[204:207], v[188:191], v[4:7]
	v_exp_f32_e32 v82, v82
	v_mfma_f32_16x16x32_bf16 v[36:39], v[204:207], v[196:199], v[36:39]
	ds_read_b64_tr_b16 v[238:239], v216 offset:57344
	ds_read_b64_tr_b16 v[240:241], v216 offset:61440
	ds_read_b128 v[204:207], v172 offset:20480
	v_exp_f32_e32 v83, v83
	s_waitcnt lgkmcnt(11)
	v_mfma_f32_16x16x32_bf16 v[8:11], v[208:211], v[188:191], v[8:11]
	v_exp_f32_e32 v84, v84
	v_mfma_f32_16x16x32_bf16 v[40:43], v[208:211], v[196:199], v[40:43]
	ds_read_b64_tr_b16 v[242:243], v217 offset:57344
	ds_read_b64_tr_b16 v[244:245], v217 offset:61440
	ds_read_b128 v[208:211], v172 offset:24576
	v_exp_f32_e32 v85, v85
	s_waitcnt lgkmcnt(12)
	v_mfma_f32_16x16x32_bf16 v[12:15], v[212:215], v[188:191], v[12:15]
	v_exp_f32_e32 v86, v86
	v_mfma_f32_16x16x32_bf16 v[44:47], v[212:215], v[196:199], v[44:47]
	ds_read_b128 v[212:215], v172 offset:28672
	v_exp_f32_e32 v87, v87
	s_waitcnt lgkmcnt(10)
	v_mfma_f32_16x16x32_bf16 v[16:19], v[230:233], v[188:191], v[16:19]
	v_exp_f32_e32 v88, v88
	v_mfma_f32_16x16x32_bf16 v[48:51], v[230:233], v[196:199], v[48:51]
	ds_read_b128 v[230:233], v173 offset:16384
	v_exp_f32_e32 v89, v89
	s_waitcnt lgkmcnt(9)
	v_mfma_f32_16x16x32_bf16 v[20:23], v[234:237], v[188:191], v[20:23]
	v_exp_f32_e32 v90, v90
	v_mfma_f32_16x16x32_bf16 v[52:55], v[234:237], v[196:199], v[52:55]
	ds_read_b128 v[234:237], v173 offset:20480
	v_exp_f32_e32 v91, v91
	s_waitcnt lgkmcnt(7)
	v_mfma_f32_16x16x32_bf16 v[24:27], v[238:241], v[188:191], v[24:27]
	v_exp_f32_e32 v92, v92
	v_mfma_f32_16x16x32_bf16 v[56:59], v[238:241], v[196:199], v[56:59]
	ds_read_b128 v[238:241], v173 offset:24576
	v_exp_f32_e32 v93, v93
	s_waitcnt lgkmcnt(5)
	v_mfma_f32_16x16x32_bf16 v[28:31], v[242:245], v[188:191], v[28:31]
	v_exp_f32_e32 v94, v94
	v_mfma_f32_16x16x32_bf16 v[60:63], v[242:245], v[196:199], v[60:63]
	ds_read_b128 v[242:245], v173 offset:28672
	v_exp_f32_e32 v95, v95
	s_barrier
	s_add_i32 s44, s44, 1
	s_cmp_lt_u32 s44, 63
	s_cbranch_scc1 .Ldense_loop
; __device__ __forceinline__ void qkt(f32x16& p0, f32x16& p1, const bf16* Ks, const bf16x8* qr, int r32, int hi) {
;   p0 = f32x16{}; p1 = f32x16{};
; #pragma unroll
;   for (int d0 = 0; d0 < 8; ++d0) { int cb = (d0 * 16 + hi * 8) * 2;
;     bf16x8 b0 = *reinterpret_cast<const bf16x8*>((const char*)Ks + KSWZ(r32, cb));
;     bf16x8 b1 = *reinterpret_cast<const bf16x8*>((const char*)Ks + KSWZ(32 + r32, cb));
;     p0 = __builtin_amdgcn_mfma_f32_32x32x16_bf16(b0, qr[d0], p0, 0, 0, 0);
;     p1 = __builtin_amdgcn_mfma_f32_32x32x16_bf16(b1, qr[d0], p1, 0, 0, 0); }
; }
; __device__ __forceinline__ int v_st(int k, int c) { const int kk = (k & ~0xC) | ((k & 4) << 1) | ((k & 8) >> 1); return ((kk >> 3) * 4 + (c >> 5)) * 512 + ((kk & 7) * 32 + (c & 31)) * 2; }
; __device__ __forceinline__ int v_rd_base(int lane) { return ((lane & 3) << 3) | (((lane >> 2) & 3) << 6) | (((lane >> 4) & 1) << 5) | (((lane >> 5) & 1) << 8); }
; template <int OFF> __device__ __forceinline__ s16x4 tr_read(int vb) {
;   s16x4 r; asm volatile("ds_read_b64_tr_b16 %0, %1 offset:%2" : "=&v"(r) : "v"(vb), "i"(OFF) : "memory"); return r;
; }
; template <int D0> __device__ __forceinline__ void pv_one(f32x16& od, int vb, bf16x8 pa0, bf16x8 pa1, bf16x8 pa2, bf16x8 pa3) {
;   const s16x4 l0 = tr_read<v_rd_off(D0, 0, 0)>(vb), h0 = tr_read<v_rd_off(D0, 0, 1)>(vb), l1 = tr_read<v_rd_off(D0, 1, 0)>(vb), h1 = tr_read<v_rd_off(D0, 1, 1)>(vb);
;   const s16x4 l2 = tr_read<v_rd_off(D0, 2, 0)>(vb), h2 = tr_read<v_rd_off(D0, 2, 1)>(vb), l3 = tr_read<v_rd_off(D0, 3, 0)>(vb), h3 = tr_read<v_rd_off(D0, 3, 1)>(vb);
;   asm volatile("s_waitcnt lgkmcnt(0)" ::: "memory"); SBAR();
;     ...
;   od = __builtin_amdgcn_mfma_f32_32x32x16_bf16(pa0, PK(l0, h0), od, 0, 0, 0);
;   od = __builtin_amdgcn_mfma_f32_32x32x16_bf16(pa1, PK(l1, h1), od, 0, 0, 0);
;   od = __builtin_amdgcn_mfma_f32_32x32x16_bf16(pa2, PK(l2, h2), od, 0, 0, 0);
;   od = __builtin_amdgcn_mfma_f32_32x32x16_bf16(pa3, PK(l3, h3), od, 0, 0, 0);
;     ...
; }
; __device__ __forceinline__ void pv_d0(f32x16* o, int vb, bf16x8 pa0, bf16x8 pa1, bf16x8 pa2, bf16x8 pa3) {
;   pv_one<0>(o[0], vb, pa0, pa1, pa2, pa3); pv_one<1>(o[1], vb, pa0, pa1, pa2, pa3); pv_one<2>(o[2], vb, pa0, pa1, pa2, pa3); pv_one<3>(o[3], vb, pa0, pa1, pa2, pa3);
;     ...
;   PAIR_FULL(0, 1, NP - 1);
;   { SBAR(); qkt(pB0, pB1, KSUB(1, 1), qr, r32, hi);
;     finishSM(pA0, pA1, alA, l_reg, pa0, pa1, pa2, pa3); SBAR();
	v_mfma_f32_16x16x32_bf16 v[128:131], v[200:203], v[96:99], 0
	v_add_f32_e32 v169, v169, v64
	global_load_dwordx4 v[246:249], v183, s[98:99]
	v_mfma_f32_16x16x32_bf16 v[132:135], v[200:203], v[112:115], 0
	ds_read_b128 v[200:203], v174 offset:16384
	v_add_f32_e32 v169, v169, v65
	v_cvt_pk_bf16_f32 v184, v64, v65
	v_mfma_f32_16x16x32_bf16 v[136:139], v[204:207], v[96:99], 0
	v_add_f32_e32 v169, v169, v66
	v_mfma_f32_16x16x32_bf16 v[140:143], v[204:207], v[112:115], 0
	ds_read_b128 v[204:207], v174 offset:20480
	v_add_f32_e32 v169, v169, v67
	v_cvt_pk_bf16_f32 v185, v66, v67
	s_waitcnt lgkmcnt(7)
	v_mfma_f32_16x16x32_bf16 v[144:147], v[208:211], v[96:99], 0
	v_add_f32_e32 v222, v222, v68
	global_load_dwordx4 v[250:253], v183, s[100:101]
	s_add_u32 s98, s98, 0x150000
	s_addc_u32 s99, s99, 0
	s_add_u32 s100, s100, 0x150000
	s_addc_u32 s101, s101, 0
	v_mfma_f32_16x16x32_bf16 v[148:151], v[208:211], v[112:115], 0
	ds_read_b128 v[208:211], v174 offset:24576
	v_add_f32_e32 v222, v222, v69
	v_cvt_pk_bf16_f32 v186, v72, v73
	s_waitcnt lgkmcnt(7)
	v_mfma_f32_16x16x32_bf16 v[152:155], v[212:215], v[96:99], 0
	v_add_f32_e32 v222, v222, v70
	v_mfma_f32_16x16x32_bf16 v[156:159], v[212:215], v[112:115], 0
	ds_read_b128 v[212:215], v174 offset:28672
	v_add_f32_e32 v222, v222, v71
	v_cvt_pk_bf16_f32 v187, v74, v75
	s_waitcnt lgkmcnt(7)
	v_mfma_f32_16x16x32_bf16 v[128:131], v[230:233], v[100:103], v[128:131]
	v_add_f32_e32 v169, v169, v72
	global_load_dwordx4 v[164:167], v183, s[0:1] offset:512
	v_mfma_f32_16x16x32_bf16 v[132:135], v[230:233], v[116:119], v[132:135]
	ds_read_b128 v[230:233], v175 offset:16384
	v_add_f32_e32 v169, v169, v73
	v_cvt_pk_bf16_f32 v188, v80, v81
	s_waitcnt lgkmcnt(7)
	v_mfma_f32_16x16x32_bf16 v[136:139], v[234:237], v[100:103], v[136:139]
	v_add_f32_e32 v169, v169, v74
	v_mfma_f32_16x16x32_bf16 v[140:143], v[234:237], v[116:119], v[140:143]
	ds_read_b128 v[234:237], v175 offset:20480
	v_add_f32_e32 v169, v169, v75
	v_cvt_pk_bf16_f32 v189, v82, v83
	s_waitcnt lgkmcnt(7)
	v_mfma_f32_16x16x32_bf16 v[144:147], v[238:241], v[100:103], v[144:147]
	v_add_f32_e32 v222, v222, v76
	global_load_dwordx4 v[160:163], v183, s[4:5] offset:512
	s_add_u32 s0, s0, 0x150000
	s_addc_u32 s1, s1, 0
	s_add_u32 s4, s4, 0x150000
	s_addc_u32 s5, s5, 0
	v_mfma_f32_16x16x32_bf16 v[148:151], v[238:241], v[116:119], v[148:151]
	ds_read_b128 v[238:241], v175 offset:24576
	v_add_f32_e32 v222, v222, v77
	v_cvt_pk_bf16_f32 v190, v88, v89
	s_waitcnt lgkmcnt(7)
	v_mfma_f32_16x16x32_bf16 v[152:155], v[242:245], v[100:103], v[152:155]
	v_add_f32_e32 v222, v222, v78
	v_mfma_f32_16x16x32_bf16 v[156:159], v[242:245], v[116:119], v[156:159]
	ds_read_b128 v[242:245], v175 offset:28672
	v_add_f32_e32 v222, v222, v79
	v_cvt_pk_bf16_f32 v191, v90, v91
	s_waitcnt lgkmcnt(7)
	v_mfma_f32_16x16x32_bf16 v[128:131], v[200:203], v[104:107], v[128:131]
	v_add_f32_e32 v169, v169, v80
	v_mfma_f32_16x16x32_bf16 v[132:135], v[200:203], v[120:123], v[132:135]
	v_add_f32_e32 v169, v169, v81
	v_cvt_pk_bf16_f32 v192, v68, v69
	s_waitcnt lgkmcnt(6)
	v_mfma_f32_16x16x32_bf16 v[136:139], v[204:207], v[104:107], v[136:139]
	v_add_f32_e32 v169, v169, v82
	v_mfma_f32_16x16x32_bf16 v[140:143], v[204:207], v[120:123], v[140:143]
	v_add_f32_e32 v169, v169, v83
	v_cvt_pk_bf16_f32 v193, v70, v71
	s_waitcnt lgkmcnt(5)
	v_mfma_f32_16x16x32_bf16 v[144:147], v[208:211], v[104:107], v[144:147]
	v_add_f32_e32 v222, v222, v84
	v_mfma_f32_16x16x32_bf16 v[148:151], v[208:211], v[120:123], v[148:151]
	v_add_f32_e32 v222, v222, v85
	v_cvt_pk_bf16_f32 v194, v76, v77
	s_waitcnt lgkmcnt(4)
	v_mfma_f32_16x16x32_bf16 v[152:155], v[212:215], v[104:107], v[152:155]
	ds_read_b64_tr_b16 v[200:201], v176 offset:0
	ds_read_b64_tr_b16 v[202:203], v176 offset:4096
	v_add_f32_e32 v222, v222, v86
	v_mfma_f32_16x16x32_bf16 v[156:159], v[212:215], v[120:123], v[156:159]
	v_add_f32_e32 v222, v222, v87
	v_cvt_pk_bf16_f32 v195, v78, v79
	s_waitcnt lgkmcnt(5)
	v_mfma_f32_16x16x32_bf16 v[128:131], v[230:233], v[108:111], v[128:131]
	ds_read_b64_tr_b16 v[204:205], v177 offset:0
	ds_read_b64_tr_b16 v[206:207], v177 offset:4096
	v_add_f32_e32 v169, v169, v88
	v_mfma_f32_16x16x32_bf16 v[132:135], v[230:233], v[124:127], v[132:135]
	v_add_f32_e32 v169, v169, v89
	v_cvt_pk_bf16_f32 v196, v84, v85
	s_waitcnt lgkmcnt(6)
	v_mfma_f32_16x16x32_bf16 v[136:139], v[234:237], v[108:111], v[136:139]
	ds_read_b64_tr_b16 v[208:209], v178 offset:0
	ds_read_b64_tr_b16 v[210:211], v178 offset:4096
	v_add_f32_e32 v169, v169, v90
	v_mfma_f32_16x16x32_bf16 v[140:143], v[234:237], v[124:127], v[140:143]
	v_add_f32_e32 v169, v169, v91
	v_cvt_pk_bf16_f32 v197, v86, v87
	s_waitcnt lgkmcnt(7)
	v_mfma_f32_16x16x32_bf16 v[144:147], v[238:241], v[108:111], v[144:147]
	ds_read_b64_tr_b16 v[212:213], v179 offset:0
	ds_read_b64_tr_b16 v[214:215], v179 offset:4096
	v_add_f32_e32 v222, v222, v92
	v_mfma_f32_16x16x32_bf16 v[148:151], v[238:241], v[124:127], v[148:151]
	v_add_f32_e32 v222, v222, v93
	v_cvt_pk_bf16_f32 v198, v92, v93
	s_waitcnt lgkmcnt(8)
	v_mfma_f32_16x16x32_bf16 v[152:155], v[242:245], v[108:111], v[152:155]
	ds_read_b64_tr_b16 v[230:231], v180 offset:0
	ds_read_b64_tr_b16 v[232:233], v180 offset:4096
	v_add_f32_e32 v222, v222, v94
	v_mfma_f32_16x16x32_bf16 v[156:159], v[242:245], v[124:127], v[156:159]
	v_add_f32_e32 v222, v222, v95
	v_cvt_pk_bf16_f32 v199, v94, v95
	s_waitcnt lgkmcnt(8)
	v_mfma_f32_16x16x32_bf16 v[0:3], v[200:203], v[184:187], v[0:3]
	v_exp_f32_e32 v128, v128
	v_mfma_f32_16x16x32_bf16 v[32:35], v[200:203], v[192:195], v[32:35]
	ds_read_b64_tr_b16 v[234:235], v182 offset:0
	ds_read_b64_tr_b16 v[236:237], v182 offset:4096
	v_exp_f32_e32 v129, v129
	s_waitcnt lgkmcnt(8)
; __device__ __forceinline__ void qkt(f32x16& p0, f32x16& p1, const bf16* Ks, const bf16x8* qr, int r32, int hi) {
;   p0 = f32x16{}; p1 = f32x16{};
; #pragma unroll
;   for (int d0 = 0; d0 < 8; ++d0) { int cb = (d0 * 16 + hi * 8) * 2;
;     bf16x8 b0 = *reinterpret_cast<const bf16x8*>((const char*)Ks + KSWZ(r32, cb));
;     bf16x8 b1 = *reinterpret_cast<const bf16x8*>((const char*)Ks + KSWZ(32 + r32, cb));
;     p0 = __builtin_amdgcn_mfma_f32_32x32x16_bf16(b0, qr[d0], p0, 0, 0, 0);
;     p1 = __builtin_amdgcn_mfma_f32_32x32x16_bf16(b1, qr[d0], p1, 0, 0, 0); }
; }
; __device__ __forceinline__ int v_st(int k, int c) { const int kk = (k & ~0xC) | ((k & 4) << 1) | ((k & 8) >> 1); return ((kk >> 3) * 4 + (c >> 5)) * 512 + ((kk & 7) * 32 + (c & 31)) * 2; }
; __device__ __forceinline__ int v_rd_base(int lane) { return ((lane & 3) << 3) | (((lane >> 2) & 3) << 6) | (((lane >> 4) & 1) << 5) | (((lane >> 5) & 1) << 8); }
; template <int OFF> __device__ __forceinline__ s16x4 tr_read(int vb) {
;   s16x4 r; asm volatile("ds_read_b64_tr_b16 %0, %1 offset:%2" : "=&v"(r) : "v"(vb), "i"(OFF) : "memory"); return r;
; }
; template <int D0> __device__ __forceinline__ void pv_one(f32x16& od, int vb, bf16x8 pa0, bf16x8 pa1, bf16x8 pa2, bf16x8 pa3) {
;   const s16x4 l0 = tr_read<v_rd_off(D0, 0, 0)>(vb), h0 = tr_read<v_rd_off(D0, 0, 1)>(vb), l1 = tr_read<v_rd_off(D0, 1, 0)>(vb), h1 = tr_read<v_rd_off(D0, 1, 1)>(vb);
;   const s16x4 l2 = tr_read<v_rd_off(D0, 2, 0)>(vb), h2 = tr_read<v_rd_off(D0, 2, 1)>(vb), l3 = tr_read<v_rd_off(D0, 3, 0)>(vb), h3 = tr_read<v_rd_off(D0, 3, 1)>(vb);
;   asm volatile("s_waitcnt lgkmcnt(0)" ::: "memory"); SBAR();
;     ...
;   od = __builtin_amdgcn_mfma_f32_32x32x16_bf16(pa0, PK(l0, h0), od, 0, 0, 0);
;   od = __builtin_amdgcn_mfma_f32_32x32x16_bf16(pa1, PK(l1, h1), od, 0, 0, 0);
;   od = __builtin_amdgcn_mfma_f32_32x32x16_bf16(pa2, PK(l2, h2), od, 0, 0, 0);
;   od = __builtin_amdgcn_mfma_f32_32x32x16_bf16(pa3, PK(l3, h3), od, 0, 0, 0);
;     ...
; }
; __device__ __forceinline__ void pv_d0(f32x16* o, int vb, bf16x8 pa0, bf16x8 pa1, bf16x8 pa2, bf16x8 pa3) {
;   pv_one<0>(o[0], vb, pa0, pa1, pa2, pa3); pv_one<1>(o[1], vb, pa0, pa1, pa2, pa3); pv_one<2>(o[2], vb, pa0, pa1, pa2, pa3); pv_one<3>(o[3], vb, pa0, pa1, pa2, pa3);
;     ...
;   PAIR_FULL(0, 1, NP - 1);
;   { SBAR(); qkt(pB0, pB1, KSUB(1, 1), qr, r32, hi);
;     finishSM(pA0, pA1, alA, l_reg, pa0, pa1, pa2, pa3); SBAR();
	v_mfma_f32_16x16x32_bf16 v[4:7], v[204:207], v[184:187], v[4:7]
	v_exp_f32_e32 v130, v130
	s_waitcnt vmcnt(3)
	ds_write_b128 v181, v[246:249] offset:49152
	v_mfma_f32_16x16x32_bf16 v[36:39], v[204:207], v[192:195], v[36:39]
	ds_read_b64_tr_b16 v[238:239], v216 offset:0
	ds_read_b64_tr_b16 v[240:241], v216 offset:4096
	v_exp_f32_e32 v131, v131
	s_waitcnt lgkmcnt(9)
	v_mfma_f32_16x16x32_bf16 v[8:11], v[208:211], v[184:187], v[8:11]
	v_exp_f32_e32 v132, v132
	v_mfma_f32_16x16x32_bf16 v[40:43], v[208:211], v[192:195], v[40:43]
	ds_read_b64_tr_b16 v[242:243], v217 offset:0
	ds_read_b64_tr_b16 v[244:245], v217 offset:4096
	v_exp_f32_e32 v133, v133
	s_waitcnt lgkmcnt(9)
	v_mfma_f32_16x16x32_bf16 v[12:15], v[212:215], v[184:187], v[12:15]
	v_exp_f32_e32 v134, v134
	s_waitcnt vmcnt(2)
	ds_write_b128 v181, v[250:253] offset:57344
	v_mfma_f32_16x16x32_bf16 v[44:47], v[212:215], v[192:195], v[44:47]
	ds_read_b64_tr_b16 v[200:201], v176 offset:8192
	ds_read_b64_tr_b16 v[202:203], v176 offset:12288
	v_exp_f32_e32 v135, v135
	s_waitcnt lgkmcnt(10)
	v_mfma_f32_16x16x32_bf16 v[16:19], v[230:233], v[184:187], v[16:19]
	v_exp_f32_e32 v136, v136
	v_mfma_f32_16x16x32_bf16 v[48:51], v[230:233], v[192:195], v[48:51]
	ds_read_b64_tr_b16 v[204:205], v177 offset:8192
	ds_read_b64_tr_b16 v[206:207], v177 offset:12288
	v_exp_f32_e32 v137, v137
	s_waitcnt lgkmcnt(10)
	v_mfma_f32_16x16x32_bf16 v[20:23], v[234:237], v[184:187], v[20:23]
	v_exp_f32_e32 v138, v138
	s_waitcnt vmcnt(1)
	ds_write_b128 v219, v[164:167] offset:32768
	v_mfma_f32_16x16x32_bf16 v[52:55], v[234:237], v[192:195], v[52:55]
	ds_read_b64_tr_b16 v[208:209], v178 offset:8192
	ds_read_b64_tr_b16 v[210:211], v178 offset:12288
	v_exp_f32_e32 v139, v139
	s_waitcnt lgkmcnt(10)
	v_mfma_f32_16x16x32_bf16 v[24:27], v[238:241], v[184:187], v[24:27]
	v_exp_f32_e32 v140, v140
	v_mfma_f32_16x16x32_bf16 v[56:59], v[238:241], v[192:195], v[56:59]
	ds_read_b64_tr_b16 v[212:213], v179 offset:8192
	ds_read_b64_tr_b16 v[214:215], v179 offset:12288
	v_exp_f32_e32 v141, v141
	s_waitcnt lgkmcnt(10)
	v_mfma_f32_16x16x32_bf16 v[28:31], v[242:245], v[184:187], v[28:31]
	v_exp_f32_e32 v142, v142
	s_waitcnt vmcnt(0)
	ds_write_b128 v219, v[160:163] offset:40960
	v_mfma_f32_16x16x32_bf16 v[60:63], v[242:245], v[192:195], v[60:63]
	ds_read_b64_tr_b16 v[230:231], v180 offset:8192
	ds_read_b64_tr_b16 v[232:233], v180 offset:12288
	v_exp_f32_e32 v143, v143
	s_waitcnt lgkmcnt(10)
	v_mfma_f32_16x16x32_bf16 v[0:3], v[200:203], v[188:191], v[0:3]
	v_exp_f32_e32 v144, v144
	v_mfma_f32_16x16x32_bf16 v[32:35], v[200:203], v[196:199], v[32:35]
	ds_read_b64_tr_b16 v[234:235], v182 offset:8192
	ds_read_b64_tr_b16 v[236:237], v182 offset:12288
	ds_read_b128 v[200:203], v172 offset:32768
	v_exp_f32_e32 v145, v145
	s_waitcnt lgkmcnt(11)
	v_mfma_f32_16x16x32_bf16 v[4:7], v[204:207], v[188:191], v[4:7]
	v_exp_f32_e32 v146, v146
	v_mfma_f32_16x16x32_bf16 v[36:39], v[204:207], v[196:199], v[36:39]
	ds_read_b64_tr_b16 v[238:239], v216 offset:8192
	ds_read_b64_tr_b16 v[240:241], v216 offset:12288
	ds_read_b128 v[204:207], v172 offset:36864
	v_exp_f32_e32 v147, v147
	s_waitcnt lgkmcnt(11)
	v_mfma_f32_16x16x32_bf16 v[8:11], v[208:211], v[188:191], v[8:11]
	v_exp_f32_e32 v148, v148
	v_mfma_f32_16x16x32_bf16 v[40:43], v[208:211], v[196:199], v[40:43]
	ds_read_b64_tr_b16 v[242:243], v217 offset:8192
	ds_read_b64_tr_b16 v[244:245], v217 offset:12288
	ds_read_b128 v[208:211], v172 offset:40960
	v_exp_f32_e32 v149, v149
	s_waitcnt lgkmcnt(12)
	v_mfma_f32_16x16x32_bf16 v[12:15], v[212:215], v[188:191], v[12:15]
	v_exp_f32_e32 v150, v150
	v_mfma_f32_16x16x32_bf16 v[44:47], v[212:215], v[196:199], v[44:47]
	ds_read_b128 v[212:215], v172 offset:45056
	v_exp_f32_e32 v151, v151
	s_waitcnt lgkmcnt(10)
	v_mfma_f32_16x16x32_bf16 v[16:19], v[230:233], v[188:191], v[16:19]
	v_exp_f32_e32 v152, v152
	v_mfma_f32_16x16x32_bf16 v[48:51], v[230:233], v[196:199], v[48:51]
	ds_read_b128 v[230:233], v173 offset:32768
	v_exp_f32_e32 v153, v153
	s_waitcnt lgkmcnt(9)
	v_mfma_f32_16x16x32_bf16 v[20:23], v[234:237], v[188:191], v[20:23]
	v_exp_f32_e32 v154, v154
	v_mfma_f32_16x16x32_bf16 v[52:55], v[234:237], v[196:199], v[52:55]
	ds_read_b128 v[234:237], v173 offset:36864
	v_exp_f32_e32 v155, v155
	s_waitcnt lgkmcnt(7)
	v_mfma_f32_16x16x32_bf16 v[24:27], v[238:241], v[188:191], v[24:27]
	v_exp_f32_e32 v156, v156
	v_mfma_f32_16x16x32_bf16 v[56:59], v[238:241], v[196:199], v[56:59]
	ds_read_b128 v[238:241], v173 offset:40960
	v_exp_f32_e32 v157, v157
	s_waitcnt lgkmcnt(5)
	v_mfma_f32_16x16x32_bf16 v[28:31], v[242:245], v[188:191], v[28:31]
	v_exp_f32_e32 v158, v158
	v_mfma_f32_16x16x32_bf16 v[60:63], v[242:245], v[196:199], v[60:63]
	ds_read_b128 v[242:245], v173 offset:45056
	v_exp_f32_e32 v159, v159
	s_barrier
; __device__ __forceinline__ void qkt(f32x16& p0, f32x16& p1, const bf16* Ks, const bf16x8* qr, int r32, int hi) {
;   p0 = f32x16{}; p1 = f32x16{};
; #pragma unroll
;   for (int d0 = 0; d0 < 8; ++d0) { int cb = (d0 * 16 + hi * 8) * 2;
;     bf16x8 b0 = *reinterpret_cast<const bf16x8*>((const char*)Ks + KSWZ(r32, cb));
;     bf16x8 b1 = *reinterpret_cast<const bf16x8*>((const char*)Ks + KSWZ(32 + r32, cb));
;     p0 = __builtin_amdgcn_mfma_f32_32x32x16_bf16(b0, qr[d0], p0, 0, 0, 0);
;     p1 = __builtin_amdgcn_mfma_f32_32x32x16_bf16(b1, qr[d0], p1, 0, 0, 0); }
; }
; __device__ __forceinline__ int v_st(int k, int c) { const int kk = (k & ~0xC) | ((k & 4) << 1) | ((k & 8) >> 1); return ((kk >> 3) * 4 + (c >> 5)) * 512 + ((kk & 7) * 32 + (c & 31)) * 2; }
; __device__ __forceinline__ int v_rd_base(int lane) { return ((lane & 3) << 3) | (((lane >> 2) & 3) << 6) | (((lane >> 4) & 1) << 5) | (((lane >> 5) & 1) << 8); }
; template <int OFF> __device__ __forceinline__ s16x4 tr_read(int vb) {
;   s16x4 r; asm volatile("ds_read_b64_tr_b16 %0, %1 offset:%2" : "=&v"(r) : "v"(vb), "i"(OFF) : "memory"); return r;
; }
; template <int D0> __device__ __forceinline__ void pv_one(f32x16& od, int vb, bf16x8 pa0, bf16x8 pa1, bf16x8 pa2, bf16x8 pa3) {
;   const s16x4 l0 = tr_read<v_rd_off(D0, 0, 0)>(vb), h0 = tr_read<v_rd_off(D0, 0, 1)>(vb), l1 = tr_read<v_rd_off(D0, 1, 0)>(vb), h1 = tr_read<v_rd_off(D0, 1, 1)>(vb);
;   const s16x4 l2 = tr_read<v_rd_off(D0, 2, 0)>(vb), h2 = tr_read<v_rd_off(D0, 2, 1)>(vb), l3 = tr_read<v_rd_off(D0, 3, 0)>(vb), h3 = tr_read<v_rd_off(D0, 3, 1)>(vb);
;   asm volatile("s_waitcnt lgkmcnt(0)" ::: "memory"); SBAR();
;     ...
;   od = __builtin_amdgcn_mfma_f32_32x32x16_bf16(pa0, PK(l0, h0), od, 0, 0, 0);
;   od = __builtin_amdgcn_mfma_f32_32x32x16_bf16(pa1, PK(l1, h1), od, 0, 0, 0);
;   od = __builtin_amdgcn_mfma_f32_32x32x16_bf16(pa2, PK(l2, h2), od, 0, 0, 0);
;   od = __builtin_amdgcn_mfma_f32_32x32x16_bf16(pa3, PK(l3, h3), od, 0, 0, 0);
;     ...
; }
; __device__ __forceinline__ void pv_d0(f32x16* o, int vb, bf16x8 pa0, bf16x8 pa1, bf16x8 pa2, bf16x8 pa3) {
;   pv_one<0>(o[0], vb, pa0, pa1, pa2, pa3); pv_one<1>(o[1], vb, pa0, pa1, pa2, pa3); pv_one<2>(o[2], vb, pa0, pa1, pa2, pa3); pv_one<3>(o[3], vb, pa0, pa1, pa2, pa3);
;     ...
;   PAIR_FULL(0, 1, NP - 1);
;   { SBAR(); qkt(pB0, pB1, KSUB(1, 1), qr, r32, hi);
;     finishSM(pA0, pA1, alA, l_reg, pa0, pa1, pa2, pa3); SBAR();
	v_mfma_f32_16x16x32_bf16 v[64:67], v[200:203], v[96:99], 0
	v_add_f32_e32 v169, v169, v128
	global_load_dwordx4 v[164:167], v183, s[0:1] offset:512
	v_mfma_f32_16x16x32_bf16 v[68:71], v[200:203], v[112:115], 0
	ds_read_b128 v[200:203], v174 offset:32768
	v_add_f32_e32 v169, v169, v129
	v_cvt_pk_bf16_f32 v184, v128, v129
	v_mfma_f32_16x16x32_bf16 v[72:75], v[204:207], v[96:99], 0
	v_add_f32_e32 v169, v169, v130
	v_mfma_f32_16x16x32_bf16 v[76:79], v[204:207], v[112:115], 0
	ds_read_b128 v[204:207], v174 offset:36864
	v_add_f32_e32 v169, v169, v131
	v_cvt_pk_bf16_f32 v185, v130, v131
	s_waitcnt lgkmcnt(7)
	v_mfma_f32_16x16x32_bf16 v[80:83], v[208:211], v[96:99], 0
	v_add_f32_e32 v222, v222, v132
	global_load_dwordx4 v[160:163], v183, s[4:5] offset:512
	s_add_u32 s0, s0, 0x150000
	s_addc_u32 s1, s1, 0
	s_add_u32 s4, s4, 0x150000
	s_addc_u32 s5, s5, 0
	v_mfma_f32_16x16x32_bf16 v[84:87], v[208:211], v[112:115], 0
	ds_read_b128 v[208:211], v174 offset:40960
	v_add_f32_e32 v222, v222, v133
	v_cvt_pk_bf16_f32 v186, v136, v137
	s_waitcnt lgkmcnt(7)
	v_mfma_f32_16x16x32_bf16 v[88:91], v[212:215], v[96:99], 0
	v_add_f32_e32 v222, v222, v134
	v_mfma_f32_16x16x32_bf16 v[92:95], v[212:215], v[112:115], 0
	ds_read_b128 v[212:215], v174 offset:45056
	v_add_f32_e32 v222, v222, v135
	v_cvt_pk_bf16_f32 v187, v138, v139
	s_waitcnt lgkmcnt(7)
	v_mfma_f32_16x16x32_bf16 v[64:67], v[230:233], v[100:103], v[64:67]
	v_add_f32_e32 v169, v169, v136
	v_mfma_f32_16x16x32_bf16 v[68:71], v[230:233], v[116:119], v[68:71]
	ds_read_b128 v[230:233], v175 offset:32768
	v_add_f32_e32 v169, v169, v137
	v_cvt_pk_bf16_f32 v188, v144, v145
	s_waitcnt lgkmcnt(7)
	v_mfma_f32_16x16x32_bf16 v[72:75], v[234:237], v[100:103], v[72:75]
	v_add_f32_e32 v169, v169, v138
	v_mfma_f32_16x16x32_bf16 v[76:79], v[234:237], v[116:119], v[76:79]
	ds_read_b128 v[234:237], v175 offset:36864
	v_add_f32_e32 v169, v169, v139
	v_cvt_pk_bf16_f32 v189, v146, v147
	s_waitcnt lgkmcnt(7)
	v_mfma_f32_16x16x32_bf16 v[80:83], v[238:241], v[100:103], v[80:83]
	v_add_f32_e32 v222, v222, v140
	v_mfma_f32_16x16x32_bf16 v[84:87], v[238:241], v[116:119], v[84:87]
	ds_read_b128 v[238:241], v175 offset:40960
	v_add_f32_e32 v222, v222, v141
	v_cvt_pk_bf16_f32 v190, v152, v153
	s_waitcnt lgkmcnt(7)
	v_mfma_f32_16x16x32_bf16 v[88:91], v[242:245], v[100:103], v[88:91]
	v_add_f32_e32 v222, v222, v142
	v_mfma_f32_16x16x32_bf16 v[92:95], v[242:245], v[116:119], v[92:95]
	ds_read_b128 v[242:245], v175 offset:45056
	v_add_f32_e32 v222, v222, v143
	v_cvt_pk_bf16_f32 v191, v154, v155
	s_waitcnt lgkmcnt(7)
	v_mfma_f32_16x16x32_bf16 v[64:67], v[200:203], v[104:107], v[64:67]
	v_add_f32_e32 v169, v169, v144
	v_mfma_f32_16x16x32_bf16 v[68:71], v[200:203], v[120:123], v[68:71]
	v_add_f32_e32 v169, v169, v145
	v_cvt_pk_bf16_f32 v192, v132, v133
	s_waitcnt lgkmcnt(6)
	v_mfma_f32_16x16x32_bf16 v[72:75], v[204:207], v[104:107], v[72:75]
	v_add_f32_e32 v169, v169, v146
	v_mfma_f32_16x16x32_bf16 v[76:79], v[204:207], v[120:123], v[76:79]
	v_add_f32_e32 v169, v169, v147
	v_cvt_pk_bf16_f32 v193, v134, v135
	s_waitcnt lgkmcnt(5)
	v_mfma_f32_16x16x32_bf16 v[80:83], v[208:211], v[104:107], v[80:83]
	v_add_f32_e32 v222, v222, v148
	v_mfma_f32_16x16x32_bf16 v[84:87], v[208:211], v[120:123], v[84:87]
	v_add_f32_e32 v222, v222, v149
	v_cvt_pk_bf16_f32 v194, v140, v141
	s_waitcnt lgkmcnt(4)
	v_mfma_f32_16x16x32_bf16 v[88:91], v[212:215], v[104:107], v[88:91]
	ds_read_b64_tr_b16 v[200:201], v176 offset:16384
	ds_read_b64_tr_b16 v[202:203], v176 offset:20480
	v_add_f32_e32 v222, v222, v150
	v_mfma_f32_16x16x32_bf16 v[92:95], v[212:215], v[120:123], v[92:95]
	v_add_f32_e32 v222, v222, v151
	v_cvt_pk_bf16_f32 v195, v142, v143
	s_waitcnt lgkmcnt(5)
	v_mfma_f32_16x16x32_bf16 v[64:67], v[230:233], v[108:111], v[64:67]
	ds_read_b64_tr_b16 v[204:205], v177 offset:16384
	ds_read_b64_tr_b16 v[206:207], v177 offset:20480
	v_add_f32_e32 v169, v169, v152
	v_mfma_f32_16x16x32_bf16 v[68:71], v[230:233], v[124:127], v[68:71]
	v_add_f32_e32 v169, v169, v153
	v_cvt_pk_bf16_f32 v196, v148, v149
	s_waitcnt lgkmcnt(6)
	v_mfma_f32_16x16x32_bf16 v[72:75], v[234:237], v[108:111], v[72:75]
	ds_read_b64_tr_b16 v[208:209], v178 offset:16384
	ds_read_b64_tr_b16 v[210:211], v178 offset:20480
	v_add_f32_e32 v169, v169, v154
	v_mfma_f32_16x16x32_bf16 v[76:79], v[234:237], v[124:127], v[76:79]
	v_add_f32_e32 v169, v169, v155
	v_cvt_pk_bf16_f32 v197, v150, v151
	s_waitcnt lgkmcnt(7)
	v_mfma_f32_16x16x32_bf16 v[80:83], v[238:241], v[108:111], v[80:83]
	ds_read_b64_tr_b16 v[212:213], v179 offset:16384
	ds_read_b64_tr_b16 v[214:215], v179 offset:20480
	v_add_f32_e32 v222, v222, v156
	v_mfma_f32_16x16x32_bf16 v[84:87], v[238:241], v[124:127], v[84:87]
	v_add_f32_e32 v222, v222, v157
	v_cvt_pk_bf16_f32 v198, v156, v157
	s_waitcnt lgkmcnt(8)
	v_mfma_f32_16x16x32_bf16 v[88:91], v[242:245], v[108:111], v[88:91]
	ds_read_b64_tr_b16 v[230:231], v180 offset:16384
	ds_read_b64_tr_b16 v[232:233], v180 offset:20480
	v_add_f32_e32 v222, v222, v158
	v_mfma_f32_16x16x32_bf16 v[92:95], v[242:245], v[124:127], v[92:95]
	v_add_f32_e32 v222, v222, v159
	v_cvt_pk_bf16_f32 v199, v158, v159
	s_waitcnt lgkmcnt(8)
	v_mfma_f32_16x16x32_bf16 v[0:3], v[200:203], v[184:187], v[0:3]
	v_exp_f32_e32 v64, v64
	v_mfma_f32_16x16x32_bf16 v[32:35], v[200:203], v[192:195], v[32:35]
	ds_read_b64_tr_b16 v[234:235], v182 offset:16384
	ds_read_b64_tr_b16 v[236:237], v182 offset:20480
	v_exp_f32_e32 v65, v65
	s_waitcnt lgkmcnt(8)
	v_mfma_f32_16x16x32_bf16 v[4:7], v[204:207], v[184:187], v[4:7]
	v_exp_f32_e32 v66, v66
	s_waitcnt vmcnt(1)
; __device__ __forceinline__ void qkt(f32x16& p0, f32x16& p1, const bf16* Ks, const bf16x8* qr, int r32, int hi) {
;   p0 = f32x16{}; p1 = f32x16{};
; #pragma unroll
;   for (int d0 = 0; d0 < 8; ++d0) { int cb = (d0 * 16 + hi * 8) * 2;
;     bf16x8 b0 = *reinterpret_cast<const bf16x8*>((const char*)Ks + KSWZ(r32, cb));
;     bf16x8 b1 = *reinterpret_cast<const bf16x8*>((const char*)Ks + KSWZ(32 + r32, cb));
;     p0 = __builtin_amdgcn_mfma_f32_32x32x16_bf16(b0, qr[d0], p0, 0, 0, 0);
;     p1 = __builtin_amdgcn_mfma_f32_32x32x16_bf16(b1, qr[d0], p1, 0, 0, 0); }
; }
; __device__ __forceinline__ int v_st(int k, int c) { const int kk = (k & ~0xC) | ((k & 4) << 1) | ((k & 8) >> 1); return ((kk >> 3) * 4 + (c >> 5)) * 512 + ((kk & 7) * 32 + (c & 31)) * 2; }
; __device__ __forceinline__ int v_rd_base(int lane) { return ((lane & 3) << 3) | (((lane >> 2) & 3) << 6) | (((lane >> 4) & 1) << 5) | (((lane >> 5) & 1) << 8); }
; template <int OFF> __device__ __forceinline__ s16x4 tr_read(int vb) {
;   s16x4 r; asm volatile("ds_read_b64_tr_b16 %0, %1 offset:%2" : "=&v"(r) : "v"(vb), "i"(OFF) : "memory"); return r;
; }
; template <int D0> __device__ __forceinline__ void pv_one(f32x16& od, int vb, bf16x8 pa0, bf16x8 pa1, bf16x8 pa2, bf16x8 pa3) {
;   const s16x4 l0 = tr_read<v_rd_off(D0, 0, 0)>(vb), h0 = tr_read<v_rd_off(D0, 0, 1)>(vb), l1 = tr_read<v_rd_off(D0, 1, 0)>(vb), h1 = tr_read<v_rd_off(D0, 1, 1)>(vb);
;   const s16x4 l2 = tr_read<v_rd_off(D0, 2, 0)>(vb), h2 = tr_read<v_rd_off(D0, 2, 1)>(vb), l3 = tr_read<v_rd_off(D0, 3, 0)>(vb), h3 = tr_read<v_rd_off(D0, 3, 1)>(vb);
;   asm volatile("s_waitcnt lgkmcnt(0)" ::: "memory"); SBAR();
;     ...
;   od = __builtin_amdgcn_mfma_f32_32x32x16_bf16(pa0, PK(l0, h0), od, 0, 0, 0);
;   od = __builtin_amdgcn_mfma_f32_32x32x16_bf16(pa1, PK(l1, h1), od, 0, 0, 0);
;   od = __builtin_amdgcn_mfma_f32_32x32x16_bf16(pa2, PK(l2, h2), od, 0, 0, 0);
;   od = __builtin_amdgcn_mfma_f32_32x32x16_bf16(pa3, PK(l3, h3), od, 0, 0, 0);
;     ...
; }
; __device__ __forceinline__ void pv_d0(f32x16* o, int vb, bf16x8 pa0, bf16x8 pa1, bf16x8 pa2, bf16x8 pa3) {
;   pv_one<0>(o[0], vb, pa0, pa1, pa2, pa3); pv_one<1>(o[1], vb, pa0, pa1, pa2, pa3); pv_one<2>(o[2], vb, pa0, pa1, pa2, pa3); pv_one<3>(o[3], vb, pa0, pa1, pa2, pa3);
;     ...
;   PAIR_FULL(0, 1, NP - 1);
;   { SBAR(); qkt(pB0, pB1, KSUB(1, 1), qr, r32, hi);
;     finishSM(pA0, pA1, alA, l_reg, pa0, pa1, pa2, pa3); SBAR();
	ds_write_b128 v219, v[164:167] offset:49152
	v_mfma_f32_16x16x32_bf16 v[36:39], v[204:207], v[192:195], v[36:39]
	ds_read_b64_tr_b16 v[238:239], v216 offset:16384
	ds_read_b64_tr_b16 v[240:241], v216 offset:20480
	v_exp_f32_e32 v67, v67
	s_waitcnt lgkmcnt(9)
	v_mfma_f32_16x16x32_bf16 v[8:11], v[208:211], v[184:187], v[8:11]
	v_exp_f32_e32 v68, v68
	v_mfma_f32_16x16x32_bf16 v[40:43], v[208:211], v[192:195], v[40:43]
	ds_read_b64_tr_b16 v[242:243], v217 offset:16384
	ds_read_b64_tr_b16 v[244:245], v217 offset:20480
	v_exp_f32_e32 v69, v69
	s_waitcnt lgkmcnt(9)
	v_mfma_f32_16x16x32_bf16 v[12:15], v[212:215], v[184:187], v[12:15]
	v_exp_f32_e32 v70, v70
	s_waitcnt vmcnt(0)
	ds_write_b128 v219, v[160:163] offset:57344
	v_mfma_f32_16x16x32_bf16 v[44:47], v[212:215], v[192:195], v[44:47]
	ds_read_b64_tr_b16 v[200:201], v176 offset:24576
	ds_read_b64_tr_b16 v[202:203], v176 offset:28672
	v_exp_f32_e32 v71, v71
	s_waitcnt lgkmcnt(10)
	v_mfma_f32_16x16x32_bf16 v[16:19], v[230:233], v[184:187], v[16:19]
	v_exp_f32_e32 v72, v72
	v_mfma_f32_16x16x32_bf16 v[48:51], v[230:233], v[192:195], v[48:51]
	ds_read_b64_tr_b16 v[204:205], v177 offset:24576
	ds_read_b64_tr_b16 v[206:207], v177 offset:28672
	v_exp_f32_e32 v73, v73
	s_waitcnt lgkmcnt(10)
	v_mfma_f32_16x16x32_bf16 v[20:23], v[234:237], v[184:187], v[20:23]
	v_exp_f32_e32 v74, v74
	v_mfma_f32_16x16x32_bf16 v[52:55], v[234:237], v[192:195], v[52:55]
	ds_read_b64_tr_b16 v[208:209], v178 offset:24576
	ds_read_b64_tr_b16 v[210:211], v178 offset:28672
	v_exp_f32_e32 v75, v75
	s_waitcnt lgkmcnt(9)
	v_mfma_f32_16x16x32_bf16 v[24:27], v[238:241], v[184:187], v[24:27]
	v_exp_f32_e32 v76, v76
	v_mfma_f32_16x16x32_bf16 v[56:59], v[238:241], v[192:195], v[56:59]
	ds_read_b64_tr_b16 v[212:213], v179 offset:24576
	ds_read_b64_tr_b16 v[214:215], v179 offset:28672
	v_exp_f32_e32 v77, v77
	s_waitcnt lgkmcnt(9)
	v_mfma_f32_16x16x32_bf16 v[28:31], v[242:245], v[184:187], v[28:31]
	v_exp_f32_e32 v78, v78
	v_mfma_f32_16x16x32_bf16 v[60:63], v[242:245], v[192:195], v[60:63]
	ds_read_b64_tr_b16 v[230:231], v180 offset:24576
	ds_read_b64_tr_b16 v[232:233], v180 offset:28672
	v_exp_f32_e32 v79, v79
	s_waitcnt lgkmcnt(8)
	v_mfma_f32_16x16x32_bf16 v[0:3], v[200:203], v[188:191], v[0:3]
	v_exp_f32_e32 v80, v80
	v_mfma_f32_16x16x32_bf16 v[32:35], v[200:203], v[196:199], v[32:35]
	ds_read_b64_tr_b16 v[234:235], v182 offset:24576
	ds_read_b64_tr_b16 v[236:237], v182 offset:28672
	ds_read_b128 v[200:203], v172 offset:49152
	v_exp_f32_e32 v81, v81
	s_waitcnt lgkmcnt(9)
	v_mfma_f32_16x16x32_bf16 v[4:7], v[204:207], v[188:191], v[4:7]
	v_exp_f32_e32 v82, v82
	v_mfma_f32_16x16x32_bf16 v[36:39], v[204:207], v[196:199], v[36:39]
	ds_read_b64_tr_b16 v[238:239], v216 offset:24576
	ds_read_b64_tr_b16 v[240:241], v216 offset:28672
	ds_read_b128 v[204:207], v172 offset:53248
	v_exp_f32_e32 v83, v83
	s_waitcnt lgkmcnt(10)
	v_mfma_f32_16x16x32_bf16 v[8:11], v[208:211], v[188:191], v[8:11]
	v_exp_f32_e32 v84, v84
	v_mfma_f32_16x16x32_bf16 v[40:43], v[208:211], v[196:199], v[40:43]
	ds_read_b64_tr_b16 v[242:243], v217 offset:24576
	ds_read_b64_tr_b16 v[244:245], v217 offset:28672
	ds_read_b128 v[208:211], v172 offset:57344
	v_exp_f32_e32 v85, v85
	s_waitcnt lgkmcnt(11)
	v_mfma_f32_16x16x32_bf16 v[12:15], v[212:215], v[188:191], v[12:15]
	v_exp_f32_e32 v86, v86
	v_mfma_f32_16x16x32_bf16 v[44:47], v[212:215], v[196:199], v[44:47]
	ds_read_b128 v[212:215], v172 offset:61440
	v_exp_f32_e32 v87, v87
	s_waitcnt lgkmcnt(10)
	v_mfma_f32_16x16x32_bf16 v[16:19], v[230:233], v[188:191], v[16:19]
	v_exp_f32_e32 v88, v88
	v_mfma_f32_16x16x32_bf16 v[48:51], v[230:233], v[196:199], v[48:51]
	ds_read_b128 v[230:233], v173 offset:49152
	v_exp_f32_e32 v89, v89
	s_waitcnt lgkmcnt(9)
	v_mfma_f32_16x16x32_bf16 v[20:23], v[234:237], v[188:191], v[20:23]
	v_exp_f32_e32 v90, v90
	v_mfma_f32_16x16x32_bf16 v[52:55], v[234:237], v[196:199], v[52:55]
	ds_read_b128 v[234:237], v173 offset:53248
	v_exp_f32_e32 v91, v91
	s_waitcnt lgkmcnt(7)
	v_mfma_f32_16x16x32_bf16 v[24:27], v[238:241], v[188:191], v[24:27]
	v_exp_f32_e32 v92, v92
	v_mfma_f32_16x16x32_bf16 v[56:59], v[238:241], v[196:199], v[56:59]
	ds_read_b128 v[238:241], v173 offset:57344
	v_exp_f32_e32 v93, v93
	s_waitcnt lgkmcnt(5)
	v_mfma_f32_16x16x32_bf16 v[28:31], v[242:245], v[188:191], v[28:31]
	v_exp_f32_e32 v94, v94
	v_mfma_f32_16x16x32_bf16 v[60:63], v[242:245], v[196:199], v[60:63]
	ds_read_b128 v[242:245], v173 offset:61440
	v_exp_f32_e32 v95, v95
	s_barrier
; __device__ __forceinline__ void qkt(f32x16& p0, f32x16& p1, const bf16* Ks, const bf16x8* qr, int r32, int hi) {
;   p0 = f32x16{}; p1 = f32x16{};
; #pragma unroll
;   for (int d0 = 0; d0 < 8; ++d0) { int cb = (d0 * 16 + hi * 8) * 2;
;     bf16x8 b0 = *reinterpret_cast<const bf16x8*>((const char*)Ks + KSWZ(r32, cb));
;     bf16x8 b1 = *reinterpret_cast<const bf16x8*>((const char*)Ks + KSWZ(32 + r32, cb));
;     p0 = __builtin_amdgcn_mfma_f32_32x32x16_bf16(b0, qr[d0], p0, 0, 0, 0);
;     p1 = __builtin_amdgcn_mfma_f32_32x32x16_bf16(b1, qr[d0], p1, 0, 0, 0); }
; }
; __device__ __forceinline__ int v_st(int k, int c) { const int kk = (k & ~0xC) | ((k & 4) << 1) | ((k & 8) >> 1); return ((kk >> 3) * 4 + (c >> 5)) * 512 + ((kk & 7) * 32 + (c & 31)) * 2; }
; __device__ __forceinline__ int v_rd_base(int lane) { return ((lane & 3) << 3) | (((lane >> 2) & 3) << 6) | (((lane >> 4) & 1) << 5) | (((lane >> 5) & 1) << 8); }
; template <int OFF> __device__ __forceinline__ s16x4 tr_read(int vb) {
;   s16x4 r; asm volatile("ds_read_b64_tr_b16 %0, %1 offset:%2" : "=&v"(r) : "v"(vb), "i"(OFF) : "memory"); return r;
; }
; template <int D0> __device__ __forceinline__ void pv_one(f32x16& od, int vb, bf16x8 pa0, bf16x8 pa1, bf16x8 pa2, bf16x8 pa3) {
;   const s16x4 l0 = tr_read<v_rd_off(D0, 0, 0)>(vb), h0 = tr_read<v_rd_off(D0, 0, 1)>(vb), l1 = tr_read<v_rd_off(D0, 1, 0)>(vb), h1 = tr_read<v_rd_off(D0, 1, 1)>(vb);
;   const s16x4 l2 = tr_read<v_rd_off(D0, 2, 0)>(vb), h2 = tr_read<v_rd_off(D0, 2, 1)>(vb), l3 = tr_read<v_rd_off(D0, 3, 0)>(vb), h3 = tr_read<v_rd_off(D0, 3, 1)>(vb);
;   asm volatile("s_waitcnt lgkmcnt(0)" ::: "memory"); SBAR();
;     ...
;   od = __builtin_amdgcn_mfma_f32_32x32x16_bf16(pa0, PK(l0, h0), od, 0, 0, 0);
;   od = __builtin_amdgcn_mfma_f32_32x32x16_bf16(pa1, PK(l1, h1), od, 0, 0, 0);
;   od = __builtin_amdgcn_mfma_f32_32x32x16_bf16(pa2, PK(l2, h2), od, 0, 0, 0);
;   od = __builtin_amdgcn_mfma_f32_32x32x16_bf16(pa3, PK(l3, h3), od, 0, 0, 0);
;     ...
; }
; __device__ __forceinline__ void pv_d0(f32x16* o, int vb, bf16x8 pa0, bf16x8 pa1, bf16x8 pa2, bf16x8 pa3) {
;   pv_one<0>(o[0], vb, pa0, pa1, pa2, pa3); pv_one<1>(o[1], vb, pa0, pa1, pa2, pa3); pv_one<2>(o[2], vb, pa0, pa1, pa2, pa3); pv_one<3>(o[3], vb, pa0, pa1, pa2, pa3);
;     ...
;   PAIR_FULL(0, 1, NP - 1);
;   { SBAR(); qkt(pB0, pB1, KSUB(1, 1), qr, r32, hi);
;     finishSM(pA0, pA1, alA, l_reg, pa0, pa1, pa2, pa3); SBAR();
	v_mfma_f32_16x16x32_bf16 v[128:131], v[200:203], v[96:99], 0
	v_add_f32_e32 v169, v169, v64
	v_mfma_f32_16x16x32_bf16 v[132:135], v[200:203], v[112:115], 0
	ds_read_b128 v[200:203], v174 offset:49152
	v_add_f32_e32 v169, v169, v65
	v_cvt_pk_bf16_f32 v184, v64, v65
	v_mfma_f32_16x16x32_bf16 v[136:139], v[204:207], v[96:99], 0
	v_add_f32_e32 v169, v169, v66
	v_mfma_f32_16x16x32_bf16 v[140:143], v[204:207], v[112:115], 0
	ds_read_b128 v[204:207], v174 offset:53248
	v_add_f32_e32 v169, v169, v67
	v_cvt_pk_bf16_f32 v185, v66, v67
	s_waitcnt lgkmcnt(7)
	v_mfma_f32_16x16x32_bf16 v[144:147], v[208:211], v[96:99], 0
	v_add_f32_e32 v222, v222, v68
	v_mfma_f32_16x16x32_bf16 v[148:151], v[208:211], v[112:115], 0
	ds_read_b128 v[208:211], v174 offset:57344
	v_add_f32_e32 v222, v222, v69
	v_cvt_pk_bf16_f32 v186, v72, v73
	s_waitcnt lgkmcnt(7)
	v_mfma_f32_16x16x32_bf16 v[152:155], v[212:215], v[96:99], 0
	v_add_f32_e32 v222, v222, v70
	v_mfma_f32_16x16x32_bf16 v[156:159], v[212:215], v[112:115], 0
	ds_read_b128 v[212:215], v174 offset:61440
	v_add_f32_e32 v222, v222, v71
	v_cvt_pk_bf16_f32 v187, v74, v75
	s_waitcnt lgkmcnt(7)
	v_mfma_f32_16x16x32_bf16 v[128:131], v[230:233], v[100:103], v[128:131]
	v_add_f32_e32 v169, v169, v72
	v_mfma_f32_16x16x32_bf16 v[132:135], v[230:233], v[116:119], v[132:135]
	ds_read_b128 v[230:233], v175 offset:49152
	v_add_f32_e32 v169, v169, v73
	v_cvt_pk_bf16_f32 v188, v80, v81
	s_waitcnt lgkmcnt(7)
	v_mfma_f32_16x16x32_bf16 v[136:139], v[234:237], v[100:103], v[136:139]
	v_add_f32_e32 v169, v169, v74
	v_mfma_f32_16x16x32_bf16 v[140:143], v[234:237], v[116:119], v[140:143]
	ds_read_b128 v[234:237], v175 offset:53248
	v_add_f32_e32 v169, v169, v75
	v_cvt_pk_bf16_f32 v189, v82, v83
	s_waitcnt lgkmcnt(7)
	v_mfma_f32_16x16x32_bf16 v[144:147], v[238:241], v[100:103], v[144:147]
	v_add_f32_e32 v222, v222, v76
	v_mfma_f32_16x16x32_bf16 v[148:151], v[238:241], v[116:119], v[148:151]
	ds_read_b128 v[238:241], v175 offset:57344
	v_add_f32_e32 v222, v222, v77
	v_cvt_pk_bf16_f32 v190, v88, v89
	s_waitcnt lgkmcnt(7)
	v_mfma_f32_16x16x32_bf16 v[152:155], v[242:245], v[100:103], v[152:155]
	v_add_f32_e32 v222, v222, v78
	v_mfma_f32_16x16x32_bf16 v[156:159], v[242:245], v[116:119], v[156:159]
	ds_read_b128 v[242:245], v175 offset:61440
	v_add_f32_e32 v222, v222, v79
	v_cvt_pk_bf16_f32 v191, v90, v91
	s_waitcnt lgkmcnt(7)
	v_mfma_f32_16x16x32_bf16 v[128:131], v[200:203], v[104:107], v[128:131]
	v_add_f32_e32 v169, v169, v80
	v_mfma_f32_16x16x32_bf16 v[132:135], v[200:203], v[120:123], v[132:135]
	v_add_f32_e32 v169, v169, v81
	v_cvt_pk_bf16_f32 v192, v68, v69
	s_waitcnt lgkmcnt(6)
	v_mfma_f32_16x16x32_bf16 v[136:139], v[204:207], v[104:107], v[136:139]
	v_add_f32_e32 v169, v169, v82
	v_mfma_f32_16x16x32_bf16 v[140:143], v[204:207], v[120:123], v[140:143]
	v_add_f32_e32 v169, v169, v83
	v_cvt_pk_bf16_f32 v193, v70, v71
	s_waitcnt lgkmcnt(5)
	v_mfma_f32_16x16x32_bf16 v[144:147], v[208:211], v[104:107], v[144:147]
	v_add_f32_e32 v222, v222, v84
	v_mfma_f32_16x16x32_bf16 v[148:151], v[208:211], v[120:123], v[148:151]
	v_add_f32_e32 v222, v222, v85
	v_cvt_pk_bf16_f32 v194, v76, v77
	s_waitcnt lgkmcnt(4)
	v_mfma_f32_16x16x32_bf16 v[152:155], v[212:215], v[104:107], v[152:155]
	ds_read_b64_tr_b16 v[200:201], v176 offset:32768
	ds_read_b64_tr_b16 v[202:203], v176 offset:36864
	v_add_f32_e32 v222, v222, v86
	v_mfma_f32_16x16x32_bf16 v[156:159], v[212:215], v[120:123], v[156:159]
	v_add_f32_e32 v222, v222, v87
	v_cvt_pk_bf16_f32 v195, v78, v79
	s_waitcnt lgkmcnt(5)
	v_mfma_f32_16x16x32_bf16 v[128:131], v[230:233], v[108:111], v[128:131]
	ds_read_b64_tr_b16 v[204:205], v177 offset:32768
	ds_read_b64_tr_b16 v[206:207], v177 offset:36864
	v_add_f32_e32 v169, v169, v88
	v_mfma_f32_16x16x32_bf16 v[132:135], v[230:233], v[124:127], v[132:135]
	v_add_f32_e32 v169, v169, v89
	v_cvt_pk_bf16_f32 v196, v84, v85
	s_waitcnt lgkmcnt(6)
	v_mfma_f32_16x16x32_bf16 v[136:139], v[234:237], v[108:111], v[136:139]
	ds_read_b64_tr_b16 v[208:209], v178 offset:32768
	ds_read_b64_tr_b16 v[210:211], v178 offset:36864
	v_add_f32_e32 v169, v169, v90
	v_mfma_f32_16x16x32_bf16 v[140:143], v[234:237], v[124:127], v[140:143]
	v_add_f32_e32 v169, v169, v91
	v_cvt_pk_bf16_f32 v197, v86, v87
	s_waitcnt lgkmcnt(7)
	v_mfma_f32_16x16x32_bf16 v[144:147], v[238:241], v[108:111], v[144:147]
	ds_read_b64_tr_b16 v[212:213], v179 offset:32768
	ds_read_b64_tr_b16 v[214:215], v179 offset:36864
	v_add_f32_e32 v222, v222, v92
	v_mfma_f32_16x16x32_bf16 v[148:151], v[238:241], v[124:127], v[148:151]
	v_add_f32_e32 v222, v222, v93
	v_cvt_pk_bf16_f32 v198, v92, v93
	s_waitcnt lgkmcnt(8)
	v_mfma_f32_16x16x32_bf16 v[152:155], v[242:245], v[108:111], v[152:155]
	ds_read_b64_tr_b16 v[230:231], v180 offset:32768
	ds_read_b64_tr_b16 v[232:233], v180 offset:36864
	v_add_f32_e32 v222, v222, v94
	v_mfma_f32_16x16x32_bf16 v[156:159], v[242:245], v[124:127], v[156:159]
	v_add_f32_e32 v222, v222, v95
	v_cvt_pk_bf16_f32 v199, v94, v95
	s_waitcnt lgkmcnt(8)
	v_mfma_f32_16x16x32_bf16 v[0:3], v[200:203], v[184:187], v[0:3]
	v_exp_f32_e32 v128, v128
	v_mfma_f32_16x16x32_bf16 v[32:35], v[200:203], v[192:195], v[32:35]
	ds_read_b64_tr_b16 v[234:235], v182 offset:32768
	ds_read_b64_tr_b16 v[236:237], v182 offset:36864
	v_exp_f32_e32 v129, v129
	s_waitcnt lgkmcnt(8)
	v_mfma_f32_16x16x32_bf16 v[4:7], v[204:207], v[184:187], v[4:7]
	v_exp_f32_e32 v130, v130
	v_mfma_f32_16x16x32_bf16 v[36:39], v[204:207], v[192:195], v[36:39]
	ds_read_b64_tr_b16 v[238:239], v216 offset:32768
	ds_read_b64_tr_b16 v[240:241], v216 offset:36864
	v_exp_f32_e32 v131, v131
	s_waitcnt lgkmcnt(8)
; #define SBAR() __builtin_amdgcn_sched_barrier(0)
; __device__ __forceinline__ void finishSM(f32x16& p0, f32x16& p1, float alpha, float& l_reg, bf16x8& pa0, bf16x8& pa1, bf16x8& pa2, bf16x8& pa3) {
; #pragma unroll
;   for (int r = 0; r < 16; ++r) p1[r] = __builtin_amdgcn_exp2f(p1[r]);
;   float ps = 0;
; #pragma unroll
;   for (int r = 0; r < 16; ++r) ps += p0[r];
; #pragma unroll
;   for (int r = 0; r < 16; ++r) ps += p1[r];
;   { auto rr = __builtin_amdgcn_permlane32_swap(__float_as_uint(ps), __float_as_uint(ps), false, false);
;     ps = __uint_as_float(rr[0]) + __uint_as_float(rr[1]); }
;   l_reg = l_reg * alpha + ps;
;     ...
;   PK4(p0, 0, pa0); PK4(p0, 8, pa1); PK4(p1, 0, pa2); PK4(p1, 8, pa3);
;     ...
; }
; template <int D0> __device__ __forceinline__ void pv_one(f32x16& od, int vb, bf16x8 pa0, bf16x8 pa1, bf16x8 pa2, bf16x8 pa3) {
;   const s16x4 l0 = tr_read<v_rd_off(D0, 0, 0)>(vb), h0 = tr_read<v_rd_off(D0, 0, 1)>(vb), l1 = tr_read<v_rd_off(D0, 1, 0)>(vb), h1 = tr_read<v_rd_off(D0, 1, 1)>(vb);
;   const s16x4 l2 = tr_read<v_rd_off(D0, 2, 0)>(vb), h2 = tr_read<v_rd_off(D0, 2, 1)>(vb), l3 = tr_read<v_rd_off(D0, 3, 0)>(vb), h3 = tr_read<v_rd_off(D0, 3, 1)>(vb);
;   asm volatile("s_waitcnt lgkmcnt(0)" ::: "memory"); SBAR();
;     ...
;   od = __builtin_amdgcn_mfma_f32_32x32x16_bf16(pa0, PK(l0, h0), od, 0, 0, 0);
;   od = __builtin_amdgcn_mfma_f32_32x32x16_bf16(pa1, PK(l1, h1), od, 0, 0, 0);
;   od = __builtin_amdgcn_mfma_f32_32x32x16_bf16(pa2, PK(l2, h2), od, 0, 0, 0);
;   od = __builtin_amdgcn_mfma_f32_32x32x16_bf16(pa3, PK(l3, h3), od, 0, 0, 0);
;     ...
; }
; __device__ __forceinline__ void pv_d0(f32x16* o, int vb, bf16x8 pa0, bf16x8 pa1, bf16x8 pa2, bf16x8 pa3) {
;   pv_one<0>(o[0], vb, pa0, pa1, pa2, pa3); pv_one<1>(o[1], vb, pa0, pa1, pa2, pa3); pv_one<2>(o[2], vb, pa0, pa1, pa2, pa3); pv_one<3>(o[3], vb, pa0, pa1, pa2, pa3);
; }
	v_mfma_f32_16x16x32_bf16 v[8:11], v[208:211], v[184:187], v[8:11]
	v_exp_f32_e32 v132, v132
	v_mfma_f32_16x16x32_bf16 v[40:43], v[208:211], v[192:195], v[40:43]
	ds_read_b64_tr_b16 v[242:243], v217 offset:32768
	ds_read_b64_tr_b16 v[244:245], v217 offset:36864
	v_exp_f32_e32 v133, v133
	s_waitcnt lgkmcnt(8)
	v_mfma_f32_16x16x32_bf16 v[12:15], v[212:215], v[184:187], v[12:15]
	v_exp_f32_e32 v134, v134
	v_mfma_f32_16x16x32_bf16 v[44:47], v[212:215], v[192:195], v[44:47]
	ds_read_b64_tr_b16 v[200:201], v176 offset:40960
	ds_read_b64_tr_b16 v[202:203], v176 offset:45056
	v_exp_f32_e32 v135, v135
	s_waitcnt lgkmcnt(8)
	v_mfma_f32_16x16x32_bf16 v[16:19], v[230:233], v[184:187], v[16:19]
	v_exp_f32_e32 v136, v136
	v_mfma_f32_16x16x32_bf16 v[48:51], v[230:233], v[192:195], v[48:51]
	ds_read_b64_tr_b16 v[204:205], v177 offset:40960
	ds_read_b64_tr_b16 v[206:207], v177 offset:45056
	v_exp_f32_e32 v137, v137
	s_waitcnt lgkmcnt(8)
	v_mfma_f32_16x16x32_bf16 v[20:23], v[234:237], v[184:187], v[20:23]
	v_exp_f32_e32 v138, v138
	v_mfma_f32_16x16x32_bf16 v[52:55], v[234:237], v[192:195], v[52:55]
	ds_read_b64_tr_b16 v[208:209], v178 offset:40960
	ds_read_b64_tr_b16 v[210:211], v178 offset:45056
	v_exp_f32_e32 v139, v139
	s_waitcnt lgkmcnt(8)
	v_mfma_f32_16x16x32_bf16 v[24:27], v[238:241], v[184:187], v[24:27]
	v_exp_f32_e32 v140, v140
	v_mfma_f32_16x16x32_bf16 v[56:59], v[238:241], v[192:195], v[56:59]
	ds_read_b64_tr_b16 v[212:213], v179 offset:40960
	ds_read_b64_tr_b16 v[214:215], v179 offset:45056
	v_exp_f32_e32 v141, v141
	s_waitcnt lgkmcnt(8)
	v_mfma_f32_16x16x32_bf16 v[28:31], v[242:245], v[184:187], v[28:31]
	v_exp_f32_e32 v142, v142
	v_mfma_f32_16x16x32_bf16 v[60:63], v[242:245], v[192:195], v[60:63]
	ds_read_b64_tr_b16 v[230:231], v180 offset:40960
	ds_read_b64_tr_b16 v[232:233], v180 offset:45056
	v_exp_f32_e32 v143, v143
	s_waitcnt lgkmcnt(8)
	v_mfma_f32_16x16x32_bf16 v[0:3], v[200:203], v[188:191], v[0:3]
	v_exp_f32_e32 v144, v144
	v_mfma_f32_16x16x32_bf16 v[32:35], v[200:203], v[196:199], v[32:35]
	ds_read_b64_tr_b16 v[234:235], v182 offset:40960
	ds_read_b64_tr_b16 v[236:237], v182 offset:45056
	v_exp_f32_e32 v145, v145
	s_waitcnt lgkmcnt(8)
	v_mfma_f32_16x16x32_bf16 v[4:7], v[204:207], v[188:191], v[4:7]
	v_exp_f32_e32 v146, v146
	v_mfma_f32_16x16x32_bf16 v[36:39], v[204:207], v[196:199], v[36:39]
	ds_read_b64_tr_b16 v[238:239], v216 offset:40960
	ds_read_b64_tr_b16 v[240:241], v216 offset:45056
	v_exp_f32_e32 v147, v147
	s_waitcnt lgkmcnt(8)
	v_mfma_f32_16x16x32_bf16 v[8:11], v[208:211], v[188:191], v[8:11]
	v_exp_f32_e32 v148, v148
	v_mfma_f32_16x16x32_bf16 v[40:43], v[208:211], v[196:199], v[40:43]
	ds_read_b64_tr_b16 v[242:243], v217 offset:40960
	ds_read_b64_tr_b16 v[244:245], v217 offset:45056
	v_exp_f32_e32 v149, v149
	s_waitcnt lgkmcnt(8)
	v_mfma_f32_16x16x32_bf16 v[12:15], v[212:215], v[188:191], v[12:15]
	v_exp_f32_e32 v150, v150
	v_mfma_f32_16x16x32_bf16 v[44:47], v[212:215], v[196:199], v[44:47]
	v_exp_f32_e32 v151, v151
	s_waitcnt lgkmcnt(6)
	v_mfma_f32_16x16x32_bf16 v[16:19], v[230:233], v[188:191], v[16:19]
	v_exp_f32_e32 v152, v152
	v_mfma_f32_16x16x32_bf16 v[48:51], v[230:233], v[196:199], v[48:51]
	v_exp_f32_e32 v153, v153
	s_waitcnt lgkmcnt(4)
	v_mfma_f32_16x16x32_bf16 v[20:23], v[234:237], v[188:191], v[20:23]
	v_exp_f32_e32 v154, v154
	v_mfma_f32_16x16x32_bf16 v[52:55], v[234:237], v[196:199], v[52:55]
	v_exp_f32_e32 v155, v155
	s_waitcnt lgkmcnt(2)
	v_mfma_f32_16x16x32_bf16 v[24:27], v[238:241], v[188:191], v[24:27]
	v_exp_f32_e32 v156, v156
	v_mfma_f32_16x16x32_bf16 v[56:59], v[238:241], v[196:199], v[56:59]
	v_exp_f32_e32 v157, v157
	s_waitcnt lgkmcnt(0)
	v_mfma_f32_16x16x32_bf16 v[28:31], v[242:245], v[188:191], v[28:31]
	v_exp_f32_e32 v158, v158
	v_mfma_f32_16x16x32_bf16 v[60:63], v[242:245], v[196:199], v[60:63]
	v_exp_f32_e32 v159, v159
	s_waitcnt lgkmcnt(0)
	s_barrier
	v_add_f32_e32 v169, v169, v128
	v_add_f32_e32 v169, v169, v129
	v_cvt_pk_bf16_f32 v184, v128, v129
	v_add_f32_e32 v169, v169, v130
	v_add_f32_e32 v169, v169, v131
	v_cvt_pk_bf16_f32 v185, v130, v131
	v_add_f32_e32 v222, v222, v132
	v_add_f32_e32 v222, v222, v133
	v_cvt_pk_bf16_f32 v186, v136, v137
	v_add_f32_e32 v222, v222, v134
	v_add_f32_e32 v222, v222, v135
	v_cvt_pk_bf16_f32 v187, v138, v139
	v_add_f32_e32 v169, v169, v136
	v_add_f32_e32 v169, v169, v137
	v_cvt_pk_bf16_f32 v188, v144, v145
	v_add_f32_e32 v169, v169, v138
	v_add_f32_e32 v169, v169, v139
	v_cvt_pk_bf16_f32 v189, v146, v147
	v_add_f32_e32 v222, v222, v140
	v_add_f32_e32 v222, v222, v141
	v_cvt_pk_bf16_f32 v190, v152, v153
	v_add_f32_e32 v222, v222, v142
	v_add_f32_e32 v222, v222, v143
	v_cvt_pk_bf16_f32 v191, v154, v155
	v_add_f32_e32 v169, v169, v144
	v_add_f32_e32 v169, v169, v145
	v_cvt_pk_bf16_f32 v192, v132, v133
	v_add_f32_e32 v169, v169, v146
	v_add_f32_e32 v169, v169, v147
	v_cvt_pk_bf16_f32 v193, v134, v135
	v_add_f32_e32 v222, v222, v148
	v_add_f32_e32 v222, v222, v149
	v_cvt_pk_bf16_f32 v194, v140, v141
	ds_read_b64_tr_b16 v[200:201], v176 offset:49152
	ds_read_b64_tr_b16 v[202:203], v176 offset:53248
	v_add_f32_e32 v222, v222, v150
	v_add_f32_e32 v222, v222, v151
	v_cvt_pk_bf16_f32 v195, v142, v143
	ds_read_b64_tr_b16 v[204:205], v177 offset:49152
	ds_read_b64_tr_b16 v[206:207], v177 offset:53248
	v_add_f32_e32 v169, v169, v152
	v_add_f32_e32 v169, v169, v153
	v_cvt_pk_bf16_f32 v196, v148, v149
	ds_read_b64_tr_b16 v[208:209], v178 offset:49152
	ds_read_b64_tr_b16 v[210:211], v178 offset:53248
	v_add_f32_e32 v169, v169, v154
	v_add_f32_e32 v169, v169, v155
	v_cvt_pk_bf16_f32 v197, v150, v151
	ds_read_b64_tr_b16 v[212:213], v179 offset:49152
	ds_read_b64_tr_b16 v[214:215], v179 offset:53248
	v_add_f32_e32 v222, v222, v156
	v_add_f32_e32 v222, v222, v157
	v_cvt_pk_bf16_f32 v198, v156, v157
	ds_read_b64_tr_b16 v[230:231], v180 offset:49152
	ds_read_b64_tr_b16 v[232:233], v180 offset:53248
	v_add_f32_e32 v222, v222, v158
	v_add_f32_e32 v222, v222, v159
	v_cvt_pk_bf16_f32 v199, v158, v159
	s_waitcnt lgkmcnt(8)
; #define SBAR() __builtin_amdgcn_sched_barrier(0)
; template <int D0> __device__ __forceinline__ void pv_one(f32x16& od, int vb, bf16x8 pa0, bf16x8 pa1, bf16x8 pa2, bf16x8 pa3) {
;   const s16x4 l0 = tr_read<v_rd_off(D0, 0, 0)>(vb), h0 = tr_read<v_rd_off(D0, 0, 1)>(vb), l1 = tr_read<v_rd_off(D0, 1, 0)>(vb), h1 = tr_read<v_rd_off(D0, 1, 1)>(vb);
;   const s16x4 l2 = tr_read<v_rd_off(D0, 2, 0)>(vb), h2 = tr_read<v_rd_off(D0, 2, 1)>(vb), l3 = tr_read<v_rd_off(D0, 3, 0)>(vb), h3 = tr_read<v_rd_off(D0, 3, 1)>(vb);
;   asm volatile("s_waitcnt lgkmcnt(0)" ::: "memory"); SBAR();
;     ...
;   od = __builtin_amdgcn_mfma_f32_32x32x16_bf16(pa0, PK(l0, h0), od, 0, 0, 0);
;   od = __builtin_amdgcn_mfma_f32_32x32x16_bf16(pa1, PK(l1, h1), od, 0, 0, 0);
;   od = __builtin_amdgcn_mfma_f32_32x32x16_bf16(pa2, PK(l2, h2), od, 0, 0, 0);
;   od = __builtin_amdgcn_mfma_f32_32x32x16_bf16(pa3, PK(l3, h3), od, 0, 0, 0);
;     ...
; }
; __device__ __forceinline__ void pv_d0(f32x16* o, int vb, bf16x8 pa0, bf16x8 pa1, bf16x8 pa2, bf16x8 pa3) {
;   pv_one<0>(o[0], vb, pa0, pa1, pa2, pa3); pv_one<1>(o[1], vb, pa0, pa1, pa2, pa3); pv_one<2>(o[2], vb, pa0, pa1, pa2, pa3); pv_one<3>(o[3], vb, pa0, pa1, pa2, pa3);
; }
	v_mfma_f32_16x16x32_bf16 v[0:3], v[200:203], v[184:187], v[0:3]
	v_mfma_f32_16x16x32_bf16 v[32:35], v[200:203], v[192:195], v[32:35]
	ds_read_b64_tr_b16 v[234:235], v182 offset:49152
	ds_read_b64_tr_b16 v[236:237], v182 offset:53248
	s_waitcnt lgkmcnt(8)
	v_mfma_f32_16x16x32_bf16 v[4:7], v[204:207], v[184:187], v[4:7]
	v_mfma_f32_16x16x32_bf16 v[36:39], v[204:207], v[192:195], v[36:39]
	ds_read_b64_tr_b16 v[238:239], v216 offset:49152
	ds_read_b64_tr_b16 v[240:241], v216 offset:53248
	s_waitcnt lgkmcnt(8)
	v_mfma_f32_16x16x32_bf16 v[8:11], v[208:211], v[184:187], v[8:11]
	v_mfma_f32_16x16x32_bf16 v[40:43], v[208:211], v[192:195], v[40:43]
	ds_read_b64_tr_b16 v[242:243], v217 offset:49152
	ds_read_b64_tr_b16 v[244:245], v217 offset:53248
	s_waitcnt lgkmcnt(8)
	v_mfma_f32_16x16x32_bf16 v[12:15], v[212:215], v[184:187], v[12:15]
	v_mfma_f32_16x16x32_bf16 v[44:47], v[212:215], v[192:195], v[44:47]
	ds_read_b64_tr_b16 v[200:201], v176 offset:57344
	ds_read_b64_tr_b16 v[202:203], v176 offset:61440
	s_waitcnt lgkmcnt(8)
	v_mfma_f32_16x16x32_bf16 v[16:19], v[230:233], v[184:187], v[16:19]
	v_mfma_f32_16x16x32_bf16 v[48:51], v[230:233], v[192:195], v[48:51]
	ds_read_b64_tr_b16 v[204:205], v177 offset:57344
	ds_read_b64_tr_b16 v[206:207], v177 offset:61440
	s_waitcnt lgkmcnt(8)
	v_mfma_f32_16x16x32_bf16 v[20:23], v[234:237], v[184:187], v[20:23]
	v_mfma_f32_16x16x32_bf16 v[52:55], v[234:237], v[192:195], v[52:55]
	ds_read_b64_tr_b16 v[208:209], v178 offset:57344
	ds_read_b64_tr_b16 v[210:211], v178 offset:61440
	s_waitcnt lgkmcnt(8)
	v_mfma_f32_16x16x32_bf16 v[24:27], v[238:241], v[184:187], v[24:27]
	v_mfma_f32_16x16x32_bf16 v[56:59], v[238:241], v[192:195], v[56:59]
	ds_read_b64_tr_b16 v[212:213], v179 offset:57344
	ds_read_b64_tr_b16 v[214:215], v179 offset:61440
	s_waitcnt lgkmcnt(8)
	v_mfma_f32_16x16x32_bf16 v[28:31], v[242:245], v[184:187], v[28:31]
	v_mfma_f32_16x16x32_bf16 v[60:63], v[242:245], v[192:195], v[60:63]
	ds_read_b64_tr_b16 v[230:231], v180 offset:57344
	ds_read_b64_tr_b16 v[232:233], v180 offset:61440
	s_waitcnt lgkmcnt(8)
	v_mfma_f32_16x16x32_bf16 v[0:3], v[200:203], v[188:191], v[0:3]
	v_mfma_f32_16x16x32_bf16 v[32:35], v[200:203], v[196:199], v[32:35]
	ds_read_b64_tr_b16 v[234:235], v182 offset:57344
	ds_read_b64_tr_b16 v[236:237], v182 offset:61440
	s_waitcnt lgkmcnt(8)
	v_mfma_f32_16x16x32_bf16 v[4:7], v[204:207], v[188:191], v[4:7]
	v_mfma_f32_16x16x32_bf16 v[36:39], v[204:207], v[196:199], v[36:39]
	ds_read_b64_tr_b16 v[238:239], v216 offset:57344
	ds_read_b64_tr_b16 v[240:241], v216 offset:61440
	s_waitcnt lgkmcnt(8)
	v_mfma_f32_16x16x32_bf16 v[8:11], v[208:211], v[188:191], v[8:11]
	v_mfma_f32_16x16x32_bf16 v[40:43], v[208:211], v[196:199], v[40:43]
	ds_read_b64_tr_b16 v[242:243], v217 offset:57344
	ds_read_b64_tr_b16 v[244:245], v217 offset:61440
	s_waitcnt lgkmcnt(8)
	v_mfma_f32_16x16x32_bf16 v[12:15], v[212:215], v[188:191], v[12:15]
	v_mfma_f32_16x16x32_bf16 v[44:47], v[212:215], v[196:199], v[44:47]
	s_waitcnt lgkmcnt(6)
	v_mfma_f32_16x16x32_bf16 v[16:19], v[230:233], v[188:191], v[16:19]
	v_mfma_f32_16x16x32_bf16 v[48:51], v[230:233], v[196:199], v[48:51]
	s_waitcnt lgkmcnt(4)
	v_mfma_f32_16x16x32_bf16 v[20:23], v[234:237], v[188:191], v[20:23]
	v_mfma_f32_16x16x32_bf16 v[52:55], v[234:237], v[196:199], v[52:55]
	s_waitcnt lgkmcnt(2)
	v_mfma_f32_16x16x32_bf16 v[24:27], v[238:241], v[188:191], v[24:27]
	v_mfma_f32_16x16x32_bf16 v[56:59], v[238:241], v[196:199], v[56:59]
	s_waitcnt lgkmcnt(0)
	v_mfma_f32_16x16x32_bf16 v[28:31], v[242:245], v[188:191], v[28:31]
	v_mfma_f32_16x16x32_bf16 v[60:63], v[242:245], v[196:199], v[60:63]
	s_waitcnt lgkmcnt(0)
	s_barrier
; __device__ __forceinline__ int crow(int r, int hi) { return (r & 3) + 8 * (r >> 2) + 4 * hi; }
;     ...
;   if (hi == 0) li_l[r32] = l_reg; asm volatile("s_waitcnt lgkmcnt(0)" ::: "memory");
;   if constexpr (MODE == 1) { if (hi == 0) lse_out[(long)(wid * QBLK + r32) * lse_stride] = m_reg * SCALE + __logf(l_reg); }
;   float rli[16];
; #pragma unroll
;   for (int r = 0; r < 16; ++r) rli[r] = __builtin_amdgcn_rcpf(li_l[crow(r, hi)]);
;   bf16* Ow = Ob + (long)(wid * QBLK) * ldo;
; #pragma unroll
;   for (int r = 0; r < 16; ++r) { const int orow = crow(r, hi);
; #pragma unroll
;     for (int d0 = 0; d0 < 4; ++d0) Ow[(long)orow * ldo + d0 * 32 + r32] = __float2bfloat16(o[d0][r] * rli[r]); }
;   __syncthreads();
	s_setprio 0
	v_and_b32_e32 v64, 63, v218
	v_lshlrev_b32_e32 v64, 2, v64
	v_xor_b32_e32 v65, 64, v64
	v_xor_b32_e32 v66, 0x80, v64
	ds_bpermute_b32 v67, v65, v169
	s_waitcnt lgkmcnt(0)
	v_add_f32_e32 v169, v169, v67
	ds_bpermute_b32 v67, v66, v169
	s_waitcnt lgkmcnt(0)
	v_add_f32_e32 v169, v169, v67
	v_rcp_f32_e32 v169, v169
	ds_bpermute_b32 v67, v65, v222
	s_waitcnt lgkmcnt(0)
	v_add_f32_e32 v222, v222, v67
	ds_bpermute_b32 v67, v66, v222
	s_waitcnt lgkmcnt(0)
	v_add_f32_e32 v222, v222, v67
	v_rcp_f32_e32 v222, v222
	s_lshl_b64 s[0:1], s[20:21], 12
	s_add_u32 s0, s24, s0
	s_addc_u32 s1, s25, s1
	s_lshl_b32 s2, s14, 1
	s_add_u32 s2, s0, s2
	s_addc_u32 s3, s1, 0
	s_ashr_i32 s39, s38, 31
	s_lshl_b64 s[0:1], s[38:39], 12
	s_add_u32 s0, s2, s0
	s_addc_u32 s1, s3, s1
	v_and_b32_e32 v64, 63, v218
	v_and_b32_e32 v65, 15, v64
	v_lshrrev_b32_e32 v66, 4, v64
	v_lshlrev_b32_e32 v66, 3, v66
	v_lshl_or_b32 v68, v65, 12, v66
	v_add_u32_e32 v69, 0x10000, v68
	v_mul_f32_e32 v0, v0, v169
	v_mul_f32_e32 v1, v1, v169
	v_mul_f32_e32 v2, v2, v169
	v_mul_f32_e32 v3, v3, v169
	v_cvt_pk_bf16_f32 v130, v0, v1
	v_cvt_pk_bf16_f32 v131, v2, v3
	global_store_dwordx2 v68, v[130:131], s[0:1] offset:0
	v_mul_f32_e32 v4, v4, v169
	v_mul_f32_e32 v5, v5, v169
	v_mul_f32_e32 v6, v6, v169
	v_mul_f32_e32 v7, v7, v169
	v_cvt_pk_bf16_f32 v132, v4, v5
	v_cvt_pk_bf16_f32 v133, v6, v7
	global_store_dwordx2 v68, v[132:133], s[0:1] offset:32
	v_mul_f32_e32 v8, v8, v169
	v_mul_f32_e32 v9, v9, v169
	v_mul_f32_e32 v10, v10, v169
	v_mul_f32_e32 v11, v11, v169
	v_cvt_pk_bf16_f32 v134, v8, v9
	v_cvt_pk_bf16_f32 v135, v10, v11
	global_store_dwordx2 v68, v[134:135], s[0:1] offset:64
	v_mul_f32_e32 v12, v12, v169
	v_mul_f32_e32 v13, v13, v169
	v_mul_f32_e32 v14, v14, v169
	v_mul_f32_e32 v15, v15, v169
	v_cvt_pk_bf16_f32 v136, v12, v13
	v_cvt_pk_bf16_f32 v137, v14, v15
	global_store_dwordx2 v68, v[136:137], s[0:1] offset:96
	v_mul_f32_e32 v16, v16, v169
	v_mul_f32_e32 v17, v17, v169
	v_mul_f32_e32 v18, v18, v169
	v_mul_f32_e32 v19, v19, v169
	v_cvt_pk_bf16_f32 v138, v16, v17
	v_cvt_pk_bf16_f32 v139, v18, v19
	global_store_dwordx2 v68, v[138:139], s[0:1] offset:128
	v_mul_f32_e32 v20, v20, v169
	v_mul_f32_e32 v21, v21, v169
	v_mul_f32_e32 v22, v22, v169
	v_mul_f32_e32 v23, v23, v169
	v_cvt_pk_bf16_f32 v140, v20, v21
	v_cvt_pk_bf16_f32 v141, v22, v23
	global_store_dwordx2 v68, v[140:141], s[0:1] offset:160
	v_mul_f32_e32 v24, v24, v169
	v_mul_f32_e32 v25, v25, v169
	v_mul_f32_e32 v26, v26, v169
	v_mul_f32_e32 v27, v27, v169
	v_cvt_pk_bf16_f32 v142, v24, v25
	v_cvt_pk_bf16_f32 v143, v26, v27
	global_store_dwordx2 v68, v[142:143], s[0:1] offset:192
	v_mul_f32_e32 v28, v28, v169
	v_mul_f32_e32 v29, v29, v169
	v_mul_f32_e32 v30, v30, v169
	v_mul_f32_e32 v31, v31, v169
	v_cvt_pk_bf16_f32 v144, v28, v29
	v_cvt_pk_bf16_f32 v145, v30, v31
	global_store_dwordx2 v68, v[144:145], s[0:1] offset:224
	v_mul_f32_e32 v32, v32, v222
	v_mul_f32_e32 v33, v33, v222
	v_mul_f32_e32 v34, v34, v222
	v_mul_f32_e32 v35, v35, v222
	v_cvt_pk_bf16_f32 v130, v32, v33
	v_cvt_pk_bf16_f32 v131, v34, v35
	global_store_dwordx2 v69, v[130:131], s[0:1] offset:0
	v_mul_f32_e32 v36, v36, v222
	v_mul_f32_e32 v37, v37, v222
	v_mul_f32_e32 v38, v38, v222
	v_mul_f32_e32 v39, v39, v222
	v_cvt_pk_bf16_f32 v132, v36, v37
	v_cvt_pk_bf16_f32 v133, v38, v39
	global_store_dwordx2 v69, v[132:133], s[0:1] offset:32
	v_mul_f32_e32 v40, v40, v222
	v_mul_f32_e32 v41, v41, v222
	v_mul_f32_e32 v42, v42, v222
	v_mul_f32_e32 v43, v43, v222
	v_cvt_pk_bf16_f32 v134, v40, v41
	v_cvt_pk_bf16_f32 v135, v42, v43
	global_store_dwordx2 v69, v[134:135], s[0:1] offset:64
	v_mul_f32_e32 v44, v44, v222
	v_mul_f32_e32 v45, v45, v222
	v_mul_f32_e32 v46, v46, v222
	v_mul_f32_e32 v47, v47, v222
	v_cvt_pk_bf16_f32 v136, v44, v45
	v_cvt_pk_bf16_f32 v137, v46, v47
	global_store_dwordx2 v69, v[136:137], s[0:1] offset:96
	v_mul_f32_e32 v48, v48, v222
	v_mul_f32_e32 v49, v49, v222
	v_mul_f32_e32 v50, v50, v222
	v_mul_f32_e32 v51, v51, v222
	v_cvt_pk_bf16_f32 v138, v48, v49
	v_cvt_pk_bf16_f32 v139, v50, v51
	global_store_dwordx2 v69, v[138:139], s[0:1] offset:128
	v_mul_f32_e32 v52, v52, v222
	v_mul_f32_e32 v53, v53, v222
	v_mul_f32_e32 v54, v54, v222
	v_mul_f32_e32 v55, v55, v222
	v_cvt_pk_bf16_f32 v140, v52, v53
	v_cvt_pk_bf16_f32 v141, v54, v55
	global_store_dwordx2 v69, v[140:141], s[0:1] offset:160
	v_mul_f32_e32 v56, v56, v222
	v_mul_f32_e32 v57, v57, v222
	v_mul_f32_e32 v58, v58, v222
	v_mul_f32_e32 v59, v59, v222
	v_cvt_pk_bf16_f32 v142, v56, v57
	v_cvt_pk_bf16_f32 v143, v58, v59
	global_store_dwordx2 v69, v[142:143], s[0:1] offset:192
	v_mul_f32_e32 v60, v60, v222
	v_mul_f32_e32 v61, v61, v222
	v_mul_f32_e32 v62, v62, v222
	v_mul_f32_e32 v63, v63, v222
	v_cvt_pk_bf16_f32 v144, v60, v61
	v_cvt_pk_bf16_f32 v145, v62, v63
	global_store_dwordx2 v69, v[144:145], s[0:1] offset:224
	v_lshlrev_b32_e32 v164, 4, v229
	v_mov_b32_e32 v165, 0
	s_mov_b32 s50, -1
	s_barrier
	s_branch .LBB0_478
